# static priority raise for the younger wave half (waves 4-7): per-half copies of the six GEMM K-loops, raised copy uses s_setprio 2/1 instead of 1/0
# baseline (speedup 1.0000x reference)
; template <class Epi, class Sched, bool ALIGN_EPI = false, bool SP2 = false>
; __device__ __forceinline__ void gemm_phase(PG8_LAS unsigned char* lds, const Gemm g, const Sched& S, const Epi& E) {
;     const int tid = threadIdx.x, wid = __builtin_amdgcn_readfirstlane(tid >> 6), lane = tid & 63, wr = wid >> 2, wc = wid & 3, fr = lane & 15, fq = lane >> 4;
; __global__ void __launch_bounds__(NWAVES * 64, 2) fwd(Args args) {
;     ...
;     const int tid = threadIdx.x, lane = tid & 63, wave = __builtin_amdgcn_readfirstlane(tid >> 6);
;     const int G = gridDim.x; const int bx = blockIdx.x; const int vcu = (G % 8 == 0) ? (bx % 8) * (G / 8) + bx / 8 : bx;
_Z3fwd4Args:
	v_readfirstlane_b32 s101, v0
	s_nop 3
	s_lshr_b32 s101, s101, 8
	s_load_dword s34, s[0:1], 0xa8
	s_add_u32 s4, s0, 0xa8
	s_addc_u32 s5, s1, 0
	v_readfirstlane_b32 s66, v0
	v_writelane_b32 v240, s4, 0
	s_waitcnt lgkmcnt(0)
	s_and_b32 s3, s34, 7
	s_cmp_lg_u32 s3, 0
	s_mov_b32 s8, s2
	v_writelane_b32 v240, s5, 1
	s_cbranch_scc1 .LBB0_2
	s_ashr_i32 s4, s2, 31
	s_lshr_b32 s4, s4, 29
	s_add_i32 s4, s2, s4
	s_and_b32 s5, s4, -8
	s_ashr_i32 s3, s34, 3
	s_sub_i32 s5, s2, s5
	s_mul_i32 s3, s3, s5
	s_ashr_i32 s4, s4, 3
	s_add_i32 s8, s3, s4

;     __host__ __device__ bool next(int i, Unit& u) const { if (!so.next(i >> 1, u)) return false; u.k0 = (i & 1) * 512; return true; }
;     __host__ __device__ bool next(int i, Unit& u) const { if (!so.next(i, u)) return false; u.pe = main_tile(u.pn); return true; }
;     __host__ __device__ bool next(int i, Unit& u) const { if (start + i * stride >= limit) return false; if (!so.next(i, u)) return false; u.pe = late_tile(u.pn); return true; }
; #define PG8_STAGE(bufoff, gbase, voff) do { _Pragma("unroll") for (int _i = 0; _i < 2; ++_i) \
;         __builtin_amdgcn_global_load_lds((const unsigned*)((const char*)(gbase) + (voff)[_i]), (PG8_LAS unsigned*)(lds + (bufoff) + ldsw + _i * 8192), 16, 0, 0); } while (0)
; #define PG8_WAIT_V(n) asm volatile("s_waitcnt vmcnt(" #n ")" ::: "memory")
; #define PG8_WAIT_L(n) asm volatile("s_waitcnt lgkmcnt(" #n ")" ::: "memory")
; template <class Epi, class Sched, bool ALIGN_EPI = false, bool SP2 = false>
; __device__ __forceinline__ void gemm_phase(PG8_LAS unsigned char* lds, const Gemm g, const Sched& S, const Epi& E) {
;     ...
;         const bool has_next = S.next(ui + 1, nxt);
;         const char* nA = has_next ? (const char*)g.A + (size_t)nxt.pm * tstepA + (size_t)nxt.k0 * 2 : cA; const char* nB = has_next ? (const char*)g.Bt + (size_t)nxt.pn * tstepB + (size_t)nxt.k0 * 2 : cB;
;         for (int t = 0; t < nt; t += 2) {
;             const bool last = (t == nt - 2);
;             const char* a1 = cA + (size_t)(t + 1) * kstepA;
;             const char* a2 = last ? nA : cA + (size_t)(t + 2) * kstepA; const char* b2 = last ? nB : cB + (size_t)(t + 2) * kstep;
;             const char* a3 = a2 + kstepA; const char* b3 = b2 + kstep;
;             if (last && has_next) S.a_ready(nxt);
;             if constexpr (SP2) {
;             PG8_LDB(B0, 0, 0); PG8_LDB(B1, 0, 1); PG8_SCHED; PG8_LDA(At, 0, 0); PG8_STAGE(PG8_SA(1, 1), a1 + hstepA, voffA);
;             PG8_WAIT_V(8); PG8_WAIT_L(0); PG8_BAR; PG8_MMA(0, 0, At, B0); PG8_MMA(0, 1, At, B1); PG8_BAR; PG8_SCHED;
;     ...
;         if (!keep_) {
; #pragma unroll
;         for (int a = 0; a < 2; ++a)
; #pragma unroll
;             for (int b = 0; b < 2; ++b)
; #pragma unroll
;                 for (int m = 0; m < 4; ++m)
; #pragma unroll
;                     for (int n = 0; n < 2; ++n) acc[a][b][m][n] = (f32x4){0.f, 0.f, 0.f, 0.f};
;         }
.LBB0_134:
	s_ashr_i32 s51, s50, 31
	s_lshl_b64 s[16:17], s[50:51], 19
	s_add_u32 s66, s20, s16
	s_addc_u32 s67, s21, s17
	s_and_b64 s[16:17], s[8:9], exec
	s_cselect_b32 s11, s67, s13
	s_cselect_b32 s33, s66, s12
	s_ashr_i32 s49, s48, 31
	s_lshl_b64 s[16:17], s[48:49], 19
	s_add_u32 s68, s64, s16
	s_addc_u32 s69, s65, s17
	s_and_b64 s[16:17], s[8:9], exec
	s_cselect_b32 s36, s69, s15
	s_cselect_b32 s37, s68, s14
	s_add_u32 s12, s12, 0x40080
	s_addc_u32 s13, s13, 0
	s_add_u32 s38, s14, 0x100
	v_mov_b32_e32 v2, 0
	s_addc_u32 s49, s15, 0
	s_mov_b32 s51, -2
	v_mov_b32_e32 v3, v2
	v_mov_b32_e32 v4, v2
	v_mov_b32_e32 v5, v2
	v_mov_b32_e32 v10, v2
	v_mov_b32_e32 v11, v2
	v_mov_b32_e32 v12, v2
	v_mov_b32_e32 v13, v2
	v_mov_b32_e32 v18, v2
	v_mov_b32_e32 v19, v2
	v_mov_b32_e32 v20, v2
	v_mov_b32_e32 v21, v2
	v_mov_b32_e32 v26, v2
	v_mov_b32_e32 v27, v2
	v_mov_b32_e32 v28, v2
	v_mov_b32_e32 v29, v2
	v_mov_b32_e32 v34, v2
	v_mov_b32_e32 v35, v2
	v_mov_b32_e32 v36, v2
	v_mov_b32_e32 v37, v2
	v_mov_b32_e32 v42, v2
	v_mov_b32_e32 v43, v2
	v_mov_b32_e32 v44, v2
	v_mov_b32_e32 v45, v2
	v_mov_b32_e32 v50, v2
	v_mov_b32_e32 v51, v2
	v_mov_b32_e32 v52, v2
	v_mov_b32_e32 v53, v2
	v_mov_b32_e32 v58, v2
	v_mov_b32_e32 v59, v2
	v_mov_b32_e32 v60, v2
	v_mov_b32_e32 v61, v2
	v_mov_b32_e32 v6, v2
	v_mov_b32_e32 v7, v2
	v_mov_b32_e32 v8, v2
	v_mov_b32_e32 v9, v2
	v_mov_b32_e32 v14, v2
	v_mov_b32_e32 v15, v2
	v_mov_b32_e32 v16, v2
	v_mov_b32_e32 v17, v2
	v_mov_b32_e32 v22, v2
	v_mov_b32_e32 v23, v2
	v_mov_b32_e32 v24, v2
	v_mov_b32_e32 v25, v2
	v_mov_b32_e32 v30, v2
	v_mov_b32_e32 v31, v2
	v_mov_b32_e32 v32, v2
	v_mov_b32_e32 v33, v2
	v_mov_b32_e32 v38, v2
	v_mov_b32_e32 v39, v2
	v_mov_b32_e32 v40, v2
	v_mov_b32_e32 v41, v2
	v_mov_b32_e32 v46, v2
	v_mov_b32_e32 v47, v2
	v_mov_b32_e32 v48, v2
	v_mov_b32_e32 v49, v2
	v_mov_b32_e32 v54, v2
	v_mov_b32_e32 v55, v2
	v_mov_b32_e32 v56, v2
	v_mov_b32_e32 v57, v2
	v_mov_b32_e32 v62, v2
	v_mov_b32_e32 v63, v2
	v_mov_b32_e32 v64, v2
	v_mov_b32_e32 v65, v2
	v_mov_b32_e32 v66, v2
	v_mov_b32_e32 v67, v2
	v_mov_b32_e32 v68, v2
	v_mov_b32_e32 v69, v2
	v_mov_b32_e32 v74, v2
	v_mov_b32_e32 v75, v2
	v_mov_b32_e32 v76, v2
	v_mov_b32_e32 v77, v2
	v_mov_b32_e32 v82, v2
	v_mov_b32_e32 v83, v2
	v_mov_b32_e32 v84, v2
	v_mov_b32_e32 v85, v2
	v_mov_b32_e32 v90, v2
	v_mov_b32_e32 v91, v2
	v_mov_b32_e32 v92, v2
	v_mov_b32_e32 v93, v2
	v_mov_b32_e32 v98, v2
	v_mov_b32_e32 v99, v2
	v_mov_b32_e32 v100, v2
	v_mov_b32_e32 v101, v2
	v_mov_b32_e32 v106, v2
	v_mov_b32_e32 v107, v2
	v_mov_b32_e32 v108, v2
	v_mov_b32_e32 v109, v2
	v_mov_b32_e32 v114, v2
	v_mov_b32_e32 v115, v2
	v_mov_b32_e32 v116, v2
	v_mov_b32_e32 v117, v2
	v_mov_b32_e32 v122, v2
	v_mov_b32_e32 v123, v2
	v_mov_b32_e32 v124, v2
	v_mov_b32_e32 v125, v2
	v_mov_b32_e32 v70, v2
	v_mov_b32_e32 v71, v2
	v_mov_b32_e32 v72, v2
	v_mov_b32_e32 v73, v2
	v_mov_b32_e32 v78, v2
	v_mov_b32_e32 v79, v2
	v_mov_b32_e32 v80, v2
	v_mov_b32_e32 v81, v2
	v_mov_b32_e32 v86, v2
	v_mov_b32_e32 v87, v2
	v_mov_b32_e32 v88, v2
	v_mov_b32_e32 v89, v2
	v_mov_b32_e32 v94, v2
	v_mov_b32_e32 v95, v2
	v_mov_b32_e32 v96, v2
	v_mov_b32_e32 v97, v2
	v_mov_b32_e32 v102, v2
	v_mov_b32_e32 v103, v2
	v_mov_b32_e32 v104, v2
	v_mov_b32_e32 v105, v2
	v_mov_b32_e32 v110, v2
	v_mov_b32_e32 v111, v2
	v_mov_b32_e32 v112, v2
	v_mov_b32_e32 v113, v2
	v_mov_b32_e32 v118, v2
	v_mov_b32_e32 v119, v2
	v_mov_b32_e32 v120, v2
	v_mov_b32_e32 v121, v2
	v_mov_b32_e32 v126, v2
	v_mov_b32_e32 v127, v2
	v_mov_b32_e32 v128, v2
	v_mov_b32_e32 v129, v2
	s_cmp_lg_u32 s101, 0
	s_cbranch_scc1 .Lph135_y
.LBB0_135:
	ds_read_b128 v[130:133], v151
	ds_read_b128 v[134:137], v151 offset:1024
	ds_read_b128 v[168:171], v151 offset:2048
	ds_read_b128 v[172:175], v151 offset:3072
	ds_read_b128 v[176:179], v153
	ds_read_b128 v[180:183], v153 offset:1024
	ds_read_b128 v[186:189], v153 offset:2048
	ds_read_b128 v[190:193], v153 offset:3072
	s_add_u32 s4, s12, 0xfffc0080
	s_addc_u32 s14, s13, -1
	s_cmp_eq_u32 s51, 12
	s_cselect_b32 s17, s11, s14
	s_cselect_b32 s16, s33, s4
	s_cselect_b32 s15, s36, s49
	s_cselect_b32 s14, s37, s38
	v_lshl_add_u64 v[226:227], s[12:13], 0, v[160:161]
	s_add_i32 m0, s35, 0xc000
	ds_read_b128 v[194:197], v155
	ds_read_b128 v[198:201], v155 offset:1024
	ds_read_b128 v[202:205], v155 offset:2048
	ds_read_b128 v[206:209], v155 offset:3072
	ds_read_b128 v[210:213], v155 offset:4096
	ds_read_b128 v[214:217], v155 offset:5120
	ds_read_b128 v[218:221], v155 offset:6144
	ds_read_b128 v[222:225], v155 offset:7168
	global_load_lds_dwordx4 v[226:227], off
	v_lshl_add_u64 v[226:227], s[12:13], 0, v[162:163]
	s_add_i32 m0, s35, 0xe000
	s_nop 0
	global_load_lds_dwordx4 v[226:227], off
	s_waitcnt vmcnt(8)
	s_waitcnt lgkmcnt(0)
	s_setprio 1
	s_barrier
; #define PG8_STAGE(bufoff, gbase, voff) do { _Pragma("unroll") for (int _i = 0; _i < 2; ++_i) \
;         __builtin_amdgcn_global_load_lds((const unsigned*)((const char*)(gbase) + (voff)[_i]), (PG8_LAS unsigned*)(lds + (bufoff) + ldsw + _i * 8192), 16, 0, 0); } while (0)
; #define PG8_LDA(dst, b, h) do { _Pragma("unroll") for (int m = 0; m < 4; ++m) _Pragma("unroll") for (int k = 0; k < 2; ++k) dst[m][k] = *(const PG8_LAS bf16x8*)(lds + PG8_SA(b, h) + aoff + m * 2048 + k * 1024); } while (0)
; #define PG8_MMA(ai, bj, At, Bt) do { __builtin_amdgcn_s_setprio(1); _Pragma("unroll") for (int m = 0; m < 4; ++m) _Pragma("unroll") for (int n = 0; n < 2; ++n) _Pragma("unroll") for (int k = 0; k < 2; ++k) \
;         acc[ai][bj][m][n] = __builtin_amdgcn_mfma_f32_16x16x32_bf16(Bt[n][k], At[m][k], acc[ai][bj][m][n], 0, 0, 0); __builtin_amdgcn_s_setprio(0); } while (0)
; #define PG8_WAIT_V(n) asm volatile("s_waitcnt vmcnt(" #n ")" ::: "memory")
; #define PG8_WAIT_L(n) asm volatile("s_waitcnt lgkmcnt(" #n ")" ::: "memory")
; #define PG8_BAR __builtin_amdgcn_s_barrier()
; #define PG8_SCHED __builtin_amdgcn_sched_barrier(0)
; template <class Epi, class Sched, bool ALIGN_EPI = false, bool SP2 = false>
; __device__ __forceinline__ void gemm_phase(PG8_LAS unsigned char* lds, const Gemm g, const Sched& S, const Epi& E) {
;     ...
;             PG8_WAIT_V(8); PG8_WAIT_L(0); PG8_BAR; PG8_MMA(0, 0, At, B0); PG8_MMA(0, 1, At, B1); PG8_BAR; PG8_SCHED;
;             PG8_LDA(At, 0, 1); PG8_STAGE(PG8_SB(0, 0), b2, voffB); PG8_STAGE(PG8_SB(0, 1), b2 + hstepB, voffB); PG8_STAGE(PG8_SA(0, 0), a2, voffA);
;             PG8_WAIT_V(8); PG8_WAIT_L(0); PG8_BAR; PG8_MMA(1, 0, At, B0); PG8_MMA(1, 1, At, B1); PG8_BAR; PG8_SCHED;
	v_mfma_f32_16x16x32_bf16 v[126:129], v[130:133], v[194:197], v[126:129]
	v_mfma_f32_16x16x32_bf16 v[118:121], v[168:171], v[194:197], v[118:121]
	v_mfma_f32_16x16x32_bf16 v[110:113], v[130:133], v[202:205], v[110:113]
	v_mfma_f32_16x16x32_bf16 v[102:105], v[168:171], v[202:205], v[102:105]
	v_mfma_f32_16x16x32_bf16 v[94:97], v[130:133], v[210:213], v[94:97]
	v_mfma_f32_16x16x32_bf16 v[86:89], v[168:171], v[210:213], v[86:89]
	v_mfma_f32_16x16x32_bf16 v[78:81], v[130:133], v[218:221], v[78:81]
	v_mfma_f32_16x16x32_bf16 v[70:73], v[168:171], v[218:221], v[70:73]
	v_mfma_f32_16x16x32_bf16 v[126:129], v[134:137], v[198:201], v[126:129]
	v_mfma_f32_16x16x32_bf16 v[118:121], v[172:175], v[198:201], v[118:121]
	v_mfma_f32_16x16x32_bf16 v[110:113], v[134:137], v[206:209], v[110:113]
	v_mfma_f32_16x16x32_bf16 v[102:105], v[172:175], v[206:209], v[102:105]
	v_mfma_f32_16x16x32_bf16 v[94:97], v[134:137], v[214:217], v[94:97]
	v_mfma_f32_16x16x32_bf16 v[86:89], v[172:175], v[214:217], v[86:89]
	v_mfma_f32_16x16x32_bf16 v[78:81], v[134:137], v[222:225], v[78:81]
	v_mfma_f32_16x16x32_bf16 v[70:73], v[172:175], v[222:225], v[70:73]
	v_mfma_f32_16x16x32_bf16 v[122:125], v[176:179], v[194:197], v[122:125]
	v_mfma_f32_16x16x32_bf16 v[114:117], v[186:189], v[194:197], v[114:117]
	v_mfma_f32_16x16x32_bf16 v[106:109], v[176:179], v[202:205], v[106:109]
	v_mfma_f32_16x16x32_bf16 v[98:101], v[186:189], v[202:205], v[98:101]
	v_mfma_f32_16x16x32_bf16 v[90:93], v[176:179], v[210:213], v[90:93]
	v_mfma_f32_16x16x32_bf16 v[82:85], v[186:189], v[210:213], v[82:85]
	v_mfma_f32_16x16x32_bf16 v[74:77], v[176:179], v[218:221], v[74:77]
	v_mfma_f32_16x16x32_bf16 v[66:69], v[186:189], v[218:221], v[66:69]
	v_mfma_f32_16x16x32_bf16 v[122:125], v[180:183], v[198:201], v[122:125]
	v_mfma_f32_16x16x32_bf16 v[114:117], v[190:193], v[198:201], v[114:117]
	v_mfma_f32_16x16x32_bf16 v[106:109], v[180:183], v[206:209], v[106:109]
	v_mfma_f32_16x16x32_bf16 v[98:101], v[190:193], v[206:209], v[98:101]
	v_mfma_f32_16x16x32_bf16 v[90:93], v[180:183], v[214:217], v[90:93]
	v_mfma_f32_16x16x32_bf16 v[82:85], v[190:193], v[214:217], v[82:85]
	v_mfma_f32_16x16x32_bf16 v[74:77], v[180:183], v[222:225], v[74:77]
	v_mfma_f32_16x16x32_bf16 v[66:69], v[190:193], v[222:225], v[66:69]
	s_barrier
	s_setprio 0
	s_add_i32 s4, s89, s3
	v_lshl_add_u64 v[226:227], s[14:15], 0, v[140:141]
	s_mov_b32 m0, s4
	ds_read_b128 v[194:197], v155 offset:16384
	ds_read_b128 v[198:201], v155 offset:17408
	ds_read_b128 v[202:205], v155 offset:18432
	ds_read_b128 v[206:209], v155 offset:19456
	ds_read_b128 v[210:213], v155 offset:20480
	ds_read_b128 v[214:217], v155 offset:21504
	ds_read_b128 v[218:221], v155 offset:22528
	ds_read_b128 v[222:225], v155 offset:23552
	global_load_lds_dwordx4 v[226:227], off
	s_add_i32 m0, s4, 0x2000
	s_add_u32 s70, s14, 0x40000
	v_lshl_add_u64 v[228:229], s[14:15], 0, v[144:145]
	s_addc_u32 s71, s15, 0
	s_add_i32 s4, s90, s3
	global_load_lds_dwordx4 v[228:229], off
	v_lshl_add_u64 v[230:231], s[70:71], 0, v[140:141]
	s_mov_b32 m0, s4
	v_lshl_add_u64 v[232:233], s[16:17], 0, v[142:143]
	global_load_lds_dwordx4 v[230:231], off
	v_lshl_add_u64 v[230:231], s[70:71], 0, v[144:145]
	s_add_i32 m0, s4, 0x2000
	s_nop 0
	global_load_lds_dwordx4 v[230:231], off
	v_lshl_add_u64 v[230:231], s[16:17], 0, v[138:139]
	s_mov_b32 m0, s35
	s_nop 0
	global_load_lds_dwordx4 v[230:231], off
	s_mov_b32 m0, s47
	s_nop 0
	global_load_lds_dwordx4 v[232:233], off
	s_waitcnt vmcnt(8)
	s_waitcnt lgkmcnt(0)
	s_setprio 1
	s_barrier
	v_mfma_f32_16x16x32_bf16 v[62:65], v[130:133], v[194:197], v[62:65]
	v_mfma_f32_16x16x32_bf16 v[54:57], v[168:171], v[194:197], v[54:57]
	v_mfma_f32_16x16x32_bf16 v[46:49], v[130:133], v[202:205], v[46:49]
	v_mfma_f32_16x16x32_bf16 v[38:41], v[168:171], v[202:205], v[38:41]
	v_mfma_f32_16x16x32_bf16 v[30:33], v[130:133], v[210:213], v[30:33]
	v_mfma_f32_16x16x32_bf16 v[22:25], v[168:171], v[210:213], v[22:25]
	v_mfma_f32_16x16x32_bf16 v[14:17], v[130:133], v[218:221], v[14:17]
	v_mfma_f32_16x16x32_bf16 v[6:9], v[168:171], v[218:221], v[6:9]
	v_mfma_f32_16x16x32_bf16 v[62:65], v[134:137], v[198:201], v[62:65]
	v_mfma_f32_16x16x32_bf16 v[54:57], v[172:175], v[198:201], v[54:57]
	v_mfma_f32_16x16x32_bf16 v[46:49], v[134:137], v[206:209], v[46:49]
	v_mfma_f32_16x16x32_bf16 v[38:41], v[172:175], v[206:209], v[38:41]
	v_mfma_f32_16x16x32_bf16 v[30:33], v[134:137], v[214:217], v[30:33]
	v_mfma_f32_16x16x32_bf16 v[22:25], v[172:175], v[214:217], v[22:25]
	v_mfma_f32_16x16x32_bf16 v[14:17], v[134:137], v[222:225], v[14:17]
	v_mfma_f32_16x16x32_bf16 v[6:9], v[172:175], v[222:225], v[6:9]
	v_mfma_f32_16x16x32_bf16 v[58:61], v[176:179], v[194:197], v[58:61]
	v_mfma_f32_16x16x32_bf16 v[50:53], v[186:189], v[194:197], v[50:53]
	v_mfma_f32_16x16x32_bf16 v[42:45], v[176:179], v[202:205], v[42:45]
	v_mfma_f32_16x16x32_bf16 v[34:37], v[186:189], v[202:205], v[34:37]
	v_mfma_f32_16x16x32_bf16 v[26:29], v[176:179], v[210:213], v[26:29]
	v_mfma_f32_16x16x32_bf16 v[18:21], v[186:189], v[210:213], v[18:21]
	v_mfma_f32_16x16x32_bf16 v[10:13], v[176:179], v[218:221], v[10:13]
	v_mfma_f32_16x16x32_bf16 v[2:5], v[186:189], v[218:221], v[2:5]
	v_mfma_f32_16x16x32_bf16 v[58:61], v[180:183], v[198:201], v[58:61]
	v_mfma_f32_16x16x32_bf16 v[50:53], v[190:193], v[198:201], v[50:53]
	v_mfma_f32_16x16x32_bf16 v[42:45], v[180:183], v[206:209], v[42:45]
	v_mfma_f32_16x16x32_bf16 v[34:37], v[190:193], v[206:209], v[34:37]
	v_mfma_f32_16x16x32_bf16 v[26:29], v[180:183], v[214:217], v[26:29]
	v_mfma_f32_16x16x32_bf16 v[18:21], v[190:193], v[214:217], v[18:21]
	v_mfma_f32_16x16x32_bf16 v[10:13], v[180:183], v[222:225], v[10:13]
	v_mfma_f32_16x16x32_bf16 v[2:5], v[190:193], v[222:225], v[2:5]
	s_barrier
; #define PG8_STAGE(bufoff, gbase, voff) do { _Pragma("unroll") for (int _i = 0; _i < 2; ++_i) \
;         __builtin_amdgcn_global_load_lds((const unsigned*)((const char*)(gbase) + (voff)[_i]), (PG8_LAS unsigned*)(lds + (bufoff) + ldsw + _i * 8192), 16, 0, 0); } while (0)
; #define PG8_LDA(dst, b, h) do { _Pragma("unroll") for (int m = 0; m < 4; ++m) _Pragma("unroll") for (int k = 0; k < 2; ++k) dst[m][k] = *(const PG8_LAS bf16x8*)(lds + PG8_SA(b, h) + aoff + m * 2048 + k * 1024); } while (0)
; #define PG8_LDB(dst, b, h) do { _Pragma("unroll") for (int n = 0; n < 2; ++n) _Pragma("unroll") for (int k = 0; k < 2; ++k) dst[n][k] = *(const PG8_LAS bf16x8*)(lds + PG8_SB(b, h) + boff + n * 2048 + k * 1024); } while (0)
; #define PG8_MMA(ai, bj, At, Bt) do { __builtin_amdgcn_s_setprio(1); _Pragma("unroll") for (int m = 0; m < 4; ++m) _Pragma("unroll") for (int n = 0; n < 2; ++n) _Pragma("unroll") for (int k = 0; k < 2; ++k) \
;         acc[ai][bj][m][n] = __builtin_amdgcn_mfma_f32_16x16x32_bf16(Bt[n][k], At[m][k], acc[ai][bj][m][n], 0, 0, 0); __builtin_amdgcn_s_setprio(0); } while (0)
; #define PG8_WAIT_V(n) asm volatile("s_waitcnt vmcnt(" #n ")" ::: "memory")
; #define PG8_WAIT_L(n) asm volatile("s_waitcnt lgkmcnt(" #n ")" ::: "memory")
; #define PG8_BAR __builtin_amdgcn_s_barrier()
; #define PG8_SCHED __builtin_amdgcn_sched_barrier(0)
; template <class Epi, class Sched, bool ALIGN_EPI = false, bool SP2 = false>
; __device__ __forceinline__ void gemm_phase(PG8_LAS unsigned char* lds, const Gemm g, const Sched& S, const Epi& E) {
;     ...
;             PG8_LDB(B0, 1, 0); PG8_LDB(B1, 1, 1); PG8_SCHED; PG8_LDA(At, 1, 0); PG8_STAGE(PG8_SA(0, 1), a2 + hstepA, voffA);
;             PG8_WAIT_V(8); PG8_WAIT_L(0); PG8_BAR; PG8_MMA(0, 0, At, B0); PG8_MMA(0, 1, At, B1); PG8_BAR; PG8_SCHED;
;             PG8_LDA(At, 1, 1); PG8_STAGE(PG8_SB(1, 0), b3, voffB); PG8_STAGE(PG8_SB(1, 1), b3 + hstepB, voffB); PG8_STAGE(PG8_SA(1, 0), a3, voffA);
;             PG8_WAIT_V(8); PG8_WAIT_L(0); PG8_BAR; PG8_MMA(1, 0, At, B0); PG8_MMA(1, 1, At, B1); PG8_BAR; PG8_SCHED;
	s_setprio 0
	s_add_i32 s4, 0, 0x18000
	v_add_u32_e32 v146, s4, v149
	s_add_i32 s70, 0, 0x1c000
	ds_read_b128 v[130:133], v146
	ds_read_b128 v[134:137], v146 offset:1024
	ds_read_b128 v[168:171], v146 offset:2048
	ds_read_b128 v[172:175], v146 offset:3072
	v_add_u32_e32 v146, s70, v149
	ds_read_b128 v[176:179], v146
	ds_read_b128 v[180:183], v146 offset:1024
	ds_read_b128 v[186:189], v146 offset:2048
	ds_read_b128 v[190:193], v146 offset:3072
	s_add_u32 s16, s16, 0x40000
	s_addc_u32 s17, s17, 0
	s_mov_b32 m0, s82
	v_lshl_add_u64 v[236:237], s[16:17], 0, v[138:139]
	ds_read_b128 v[194:197], v155 offset:32768
	ds_read_b128 v[198:201], v155 offset:33792
	ds_read_b128 v[202:205], v155 offset:34816
	ds_read_b128 v[206:209], v155 offset:35840
	ds_read_b128 v[210:213], v155 offset:36864
	ds_read_b128 v[214:217], v155 offset:37888
	ds_read_b128 v[218:221], v155 offset:38912
	ds_read_b128 v[222:225], v155 offset:39936
	global_load_lds_dwordx4 v[236:237], off
	v_lshl_add_u64 v[236:237], s[16:17], 0, v[142:143]
	s_mov_b32 m0, s83
	s_nop 0
	global_load_lds_dwordx4 v[236:237], off
	s_waitcnt vmcnt(8)
	s_waitcnt lgkmcnt(0)
	s_setprio 1
	s_barrier
	v_mfma_f32_16x16x32_bf16 v[126:129], v[130:133], v[194:197], v[126:129]
	v_mfma_f32_16x16x32_bf16 v[118:121], v[168:171], v[194:197], v[118:121]
	v_mfma_f32_16x16x32_bf16 v[110:113], v[130:133], v[202:205], v[110:113]
	v_mfma_f32_16x16x32_bf16 v[102:105], v[168:171], v[202:205], v[102:105]
	v_mfma_f32_16x16x32_bf16 v[94:97], v[130:133], v[210:213], v[94:97]
	v_mfma_f32_16x16x32_bf16 v[86:89], v[168:171], v[210:213], v[86:89]
	v_mfma_f32_16x16x32_bf16 v[78:81], v[130:133], v[218:221], v[78:81]
	v_mfma_f32_16x16x32_bf16 v[70:73], v[168:171], v[218:221], v[70:73]
	v_mfma_f32_16x16x32_bf16 v[126:129], v[134:137], v[198:201], v[126:129]
	v_mfma_f32_16x16x32_bf16 v[118:121], v[172:175], v[198:201], v[118:121]
	v_mfma_f32_16x16x32_bf16 v[110:113], v[134:137], v[206:209], v[110:113]
	v_mfma_f32_16x16x32_bf16 v[102:105], v[172:175], v[206:209], v[102:105]
	v_mfma_f32_16x16x32_bf16 v[94:97], v[134:137], v[214:217], v[94:97]
	v_mfma_f32_16x16x32_bf16 v[86:89], v[172:175], v[214:217], v[86:89]
	v_mfma_f32_16x16x32_bf16 v[78:81], v[134:137], v[222:225], v[78:81]
	v_mfma_f32_16x16x32_bf16 v[70:73], v[172:175], v[222:225], v[70:73]
	v_mfma_f32_16x16x32_bf16 v[122:125], v[176:179], v[194:197], v[122:125]
	v_mfma_f32_16x16x32_bf16 v[114:117], v[186:189], v[194:197], v[114:117]
	v_mfma_f32_16x16x32_bf16 v[106:109], v[176:179], v[202:205], v[106:109]
	v_mfma_f32_16x16x32_bf16 v[98:101], v[186:189], v[202:205], v[98:101]
	v_mfma_f32_16x16x32_bf16 v[90:93], v[176:179], v[210:213], v[90:93]
	v_mfma_f32_16x16x32_bf16 v[82:85], v[186:189], v[210:213], v[82:85]
	v_mfma_f32_16x16x32_bf16 v[74:77], v[176:179], v[218:221], v[74:77]
	v_mfma_f32_16x16x32_bf16 v[66:69], v[186:189], v[218:221], v[66:69]
	v_mfma_f32_16x16x32_bf16 v[122:125], v[180:183], v[198:201], v[122:125]
	v_mfma_f32_16x16x32_bf16 v[114:117], v[190:193], v[198:201], v[114:117]
	v_mfma_f32_16x16x32_bf16 v[106:109], v[180:183], v[206:209], v[106:109]
	v_mfma_f32_16x16x32_bf16 v[98:101], v[190:193], v[206:209], v[98:101]
	v_mfma_f32_16x16x32_bf16 v[90:93], v[180:183], v[214:217], v[90:93]
	v_mfma_f32_16x16x32_bf16 v[82:85], v[190:193], v[214:217], v[82:85]
	v_mfma_f32_16x16x32_bf16 v[74:77], v[180:183], v[222:225], v[74:77]
	v_mfma_f32_16x16x32_bf16 v[66:69], v[190:193], v[222:225], v[66:69]
	s_barrier
	s_setprio 0
	s_add_i32 s4, s4, s3
	v_lshl_add_u64 v[226:227], v[226:227], 0, s[42:43]
	s_mov_b32 m0, s4
	ds_read_b128 v[194:197], v155 offset:49152
	ds_read_b128 v[198:201], v155 offset:50176
	ds_read_b128 v[202:205], v155 offset:51200
	ds_read_b128 v[206:209], v155 offset:52224
	ds_read_b128 v[210:213], v155 offset:53248
	ds_read_b128 v[214:217], v155 offset:54272
	ds_read_b128 v[218:221], v155 offset:55296
	ds_read_b128 v[222:225], v155 offset:56320
	global_load_lds_dwordx4 v[226:227], off
	s_add_i32 m0, s4, 0x2000
	s_add_u32 s14, s14, 0x40080
	v_lshl_add_u64 v[226:227], v[228:229], 0, s[42:43]
	s_addc_u32 s15, s15, 0
	s_add_i32 s4, s70, s3
	global_load_lds_dwordx4 v[226:227], off
	v_lshl_add_u64 v[226:227], s[14:15], 0, v[140:141]
	s_mov_b32 m0, s4
	s_nop 0
	global_load_lds_dwordx4 v[226:227], off
	v_lshl_add_u64 v[226:227], s[14:15], 0, v[144:145]
	s_add_i32 m0, s4, 0x2000
	s_nop 0
	global_load_lds_dwordx4 v[226:227], off
	v_lshl_add_u64 v[226:227], v[230:231], 0, s[42:43]
	s_mov_b32 m0, s87
	s_nop 0
	global_load_lds_dwordx4 v[226:227], off
	v_lshl_add_u64 v[226:227], v[232:233], 0, s[42:43]
	s_mov_b32 m0, s88
	s_nop 0
	global_load_lds_dwordx4 v[226:227], off
	s_waitcnt vmcnt(8)
	s_waitcnt lgkmcnt(0)
	s_setprio 1
	s_barrier
; #define PG8_STAGE(bufoff, gbase, voff) do { _Pragma("unroll") for (int _i = 0; _i < 2; ++_i) \
;         __builtin_amdgcn_global_load_lds((const unsigned*)((const char*)(gbase) + (voff)[_i]), (PG8_LAS unsigned*)(lds + (bufoff) + ldsw + _i * 8192), 16, 0, 0); } while (0)
; #define PG8_LDA(dst, b, h) do { _Pragma("unroll") for (int m = 0; m < 4; ++m) _Pragma("unroll") for (int k = 0; k < 2; ++k) dst[m][k] = *(const PG8_LAS bf16x8*)(lds + PG8_SA(b, h) + aoff + m * 2048 + k * 1024); } while (0)
; #define PG8_LDB(dst, b, h) do { _Pragma("unroll") for (int n = 0; n < 2; ++n) _Pragma("unroll") for (int k = 0; k < 2; ++k) dst[n][k] = *(const PG8_LAS bf16x8*)(lds + PG8_SB(b, h) + boff + n * 2048 + k * 1024); } while (0)
; #define PG8_MMA(ai, bj, At, Bt) do { __builtin_amdgcn_s_setprio(1); _Pragma("unroll") for (int m = 0; m < 4; ++m) _Pragma("unroll") for (int n = 0; n < 2; ++n) _Pragma("unroll") for (int k = 0; k < 2; ++k) \
;         acc[ai][bj][m][n] = __builtin_amdgcn_mfma_f32_16x16x32_bf16(Bt[n][k], At[m][k], acc[ai][bj][m][n], 0, 0, 0); __builtin_amdgcn_s_setprio(0); } while (0)
; template <class Epi, class Sched, bool ALIGN_EPI = false, bool SP2 = false>
; __device__ __forceinline__ void gemm_phase(PG8_LAS unsigned char* lds, const Gemm g, const Sched& S, const Epi& E) {
;     ...
;         for (int t = 0; t < nt; t += 2) {
;             const bool last = (t == nt - 2);
;             const char* a1 = cA + (size_t)(t + 1) * kstepA;
;             const char* a2 = last ? nA : cA + (size_t)(t + 2) * kstepA; const char* b2 = last ? nB : cB + (size_t)(t + 2) * kstep;
;             const char* a3 = a2 + kstepA; const char* b3 = b2 + kstep;
;             if (last && has_next) S.a_ready(nxt);
;             if constexpr (SP2) {
;             PG8_LDB(B0, 0, 0); PG8_LDB(B1, 0, 1); PG8_SCHED; PG8_LDA(At, 0, 0); PG8_STAGE(PG8_SA(1, 1), a1 + hstepA, voffA);
;             PG8_WAIT_V(8); PG8_WAIT_L(0); PG8_BAR; PG8_MMA(0, 0, At, B0); PG8_MMA(0, 1, At, B1); PG8_BAR; PG8_SCHED;
;             PG8_LDA(At, 0, 1); PG8_STAGE(PG8_SB(0, 0), b2, voffB); PG8_STAGE(PG8_SB(0, 1), b2 + hstepB, voffB); PG8_STAGE(PG8_SA(0, 0), a2, voffA);
;             PG8_WAIT_V(8); PG8_WAIT_L(0); PG8_BAR; PG8_MMA(1, 0, At, B0); PG8_MMA(1, 1, At, B1); PG8_BAR; PG8_SCHED;
;     ...
;             PG8_WAIT_V(8); PG8_WAIT_L(0); PG8_BAR; PG8_MMA(1, 0, At, B0); PG8_MMA(1, 1, At, B1); PG8_BAR; PG8_SCHED;
	v_mfma_f32_16x16x32_bf16 v[62:65], v[130:133], v[194:197], v[62:65]
	v_mfma_f32_16x16x32_bf16 v[54:57], v[168:171], v[194:197], v[54:57]
	v_mfma_f32_16x16x32_bf16 v[46:49], v[130:133], v[202:205], v[46:49]
	v_mfma_f32_16x16x32_bf16 v[38:41], v[168:171], v[202:205], v[38:41]
	v_mfma_f32_16x16x32_bf16 v[30:33], v[130:133], v[210:213], v[30:33]
	v_mfma_f32_16x16x32_bf16 v[22:25], v[168:171], v[210:213], v[22:25]
	v_mfma_f32_16x16x32_bf16 v[14:17], v[130:133], v[218:221], v[14:17]
	v_mfma_f32_16x16x32_bf16 v[6:9], v[168:171], v[218:221], v[6:9]
	v_mfma_f32_16x16x32_bf16 v[62:65], v[134:137], v[198:201], v[62:65]
	v_mfma_f32_16x16x32_bf16 v[54:57], v[172:175], v[198:201], v[54:57]
	v_mfma_f32_16x16x32_bf16 v[46:49], v[134:137], v[206:209], v[46:49]
	v_mfma_f32_16x16x32_bf16 v[38:41], v[172:175], v[206:209], v[38:41]
	v_mfma_f32_16x16x32_bf16 v[30:33], v[134:137], v[214:217], v[30:33]
	v_mfma_f32_16x16x32_bf16 v[22:25], v[172:175], v[214:217], v[22:25]
	v_mfma_f32_16x16x32_bf16 v[14:17], v[134:137], v[222:225], v[14:17]
	v_mfma_f32_16x16x32_bf16 v[6:9], v[172:175], v[222:225], v[6:9]
	v_mfma_f32_16x16x32_bf16 v[58:61], v[176:179], v[194:197], v[58:61]
	v_mfma_f32_16x16x32_bf16 v[50:53], v[186:189], v[194:197], v[50:53]
	v_mfma_f32_16x16x32_bf16 v[42:45], v[176:179], v[202:205], v[42:45]
	v_mfma_f32_16x16x32_bf16 v[34:37], v[186:189], v[202:205], v[34:37]
	v_mfma_f32_16x16x32_bf16 v[26:29], v[176:179], v[210:213], v[26:29]
	v_mfma_f32_16x16x32_bf16 v[18:21], v[186:189], v[210:213], v[18:21]
	v_mfma_f32_16x16x32_bf16 v[10:13], v[176:179], v[218:221], v[10:13]
	v_mfma_f32_16x16x32_bf16 v[2:5], v[186:189], v[218:221], v[2:5]
	v_mfma_f32_16x16x32_bf16 v[58:61], v[180:183], v[198:201], v[58:61]
	v_mfma_f32_16x16x32_bf16 v[50:53], v[190:193], v[198:201], v[50:53]
	v_mfma_f32_16x16x32_bf16 v[42:45], v[180:183], v[206:209], v[42:45]
	v_mfma_f32_16x16x32_bf16 v[34:37], v[190:193], v[206:209], v[34:37]
	v_mfma_f32_16x16x32_bf16 v[26:29], v[180:183], v[214:217], v[26:29]
	v_mfma_f32_16x16x32_bf16 v[18:21], v[190:193], v[214:217], v[18:21]
	v_mfma_f32_16x16x32_bf16 v[10:13], v[180:183], v[222:225], v[10:13]
	v_mfma_f32_16x16x32_bf16 v[2:5], v[190:193], v[222:225], v[2:5]
	s_barrier
	s_setprio 0
	s_add_i32 s51, s51, 2
	s_add_u32 s12, s12, 0x100
	s_addc_u32 s13, s13, 0
	s_add_u32 s38, s38, 0x100
	s_addc_u32 s49, s49, 0
	s_cmp_gt_u32 s51, 13
	s_cbranch_scc0 .LBB0_135
	s_branch .Lph135_x
.Lph135_y:
	ds_read_b128 v[130:133], v151
	ds_read_b128 v[134:137], v151 offset:1024
	ds_read_b128 v[168:171], v151 offset:2048
	ds_read_b128 v[172:175], v151 offset:3072
	ds_read_b128 v[176:179], v153
	ds_read_b128 v[180:183], v153 offset:1024
	ds_read_b128 v[186:189], v153 offset:2048
	ds_read_b128 v[190:193], v153 offset:3072
	s_add_u32 s4, s12, 0xfffc0080
	s_addc_u32 s14, s13, -1
	s_cmp_eq_u32 s51, 12
	s_cselect_b32 s17, s11, s14
	s_cselect_b32 s16, s33, s4
	s_cselect_b32 s15, s36, s49
	s_cselect_b32 s14, s37, s38
	v_lshl_add_u64 v[226:227], s[12:13], 0, v[160:161]
	s_add_i32 m0, s35, 0xc000
	ds_read_b128 v[194:197], v155
	ds_read_b128 v[198:201], v155 offset:1024
	ds_read_b128 v[202:205], v155 offset:2048
	ds_read_b128 v[206:209], v155 offset:3072
	ds_read_b128 v[210:213], v155 offset:4096
	ds_read_b128 v[214:217], v155 offset:5120
	ds_read_b128 v[218:221], v155 offset:6144
	ds_read_b128 v[222:225], v155 offset:7168
	global_load_lds_dwordx4 v[226:227], off
	v_lshl_add_u64 v[226:227], s[12:13], 0, v[162:163]
	s_add_i32 m0, s35, 0xe000
	s_nop 0
	global_load_lds_dwordx4 v[226:227], off
	s_waitcnt vmcnt(8)
	s_waitcnt lgkmcnt(0)
	s_setprio 2
	s_barrier
	v_mfma_f32_16x16x32_bf16 v[126:129], v[130:133], v[194:197], v[126:129]
	v_mfma_f32_16x16x32_bf16 v[118:121], v[168:171], v[194:197], v[118:121]
	v_mfma_f32_16x16x32_bf16 v[110:113], v[130:133], v[202:205], v[110:113]
	v_mfma_f32_16x16x32_bf16 v[102:105], v[168:171], v[202:205], v[102:105]
	v_mfma_f32_16x16x32_bf16 v[94:97], v[130:133], v[210:213], v[94:97]
	v_mfma_f32_16x16x32_bf16 v[86:89], v[168:171], v[210:213], v[86:89]
	v_mfma_f32_16x16x32_bf16 v[78:81], v[130:133], v[218:221], v[78:81]
	v_mfma_f32_16x16x32_bf16 v[70:73], v[168:171], v[218:221], v[70:73]
	v_mfma_f32_16x16x32_bf16 v[126:129], v[134:137], v[198:201], v[126:129]
	v_mfma_f32_16x16x32_bf16 v[118:121], v[172:175], v[198:201], v[118:121]
	v_mfma_f32_16x16x32_bf16 v[110:113], v[134:137], v[206:209], v[110:113]
	v_mfma_f32_16x16x32_bf16 v[102:105], v[172:175], v[206:209], v[102:105]
	v_mfma_f32_16x16x32_bf16 v[94:97], v[134:137], v[214:217], v[94:97]
	v_mfma_f32_16x16x32_bf16 v[86:89], v[172:175], v[214:217], v[86:89]
	v_mfma_f32_16x16x32_bf16 v[78:81], v[134:137], v[222:225], v[78:81]
	v_mfma_f32_16x16x32_bf16 v[70:73], v[172:175], v[222:225], v[70:73]
	v_mfma_f32_16x16x32_bf16 v[122:125], v[176:179], v[194:197], v[122:125]
	v_mfma_f32_16x16x32_bf16 v[114:117], v[186:189], v[194:197], v[114:117]
	v_mfma_f32_16x16x32_bf16 v[106:109], v[176:179], v[202:205], v[106:109]
	v_mfma_f32_16x16x32_bf16 v[98:101], v[186:189], v[202:205], v[98:101]
	v_mfma_f32_16x16x32_bf16 v[90:93], v[176:179], v[210:213], v[90:93]
	v_mfma_f32_16x16x32_bf16 v[82:85], v[186:189], v[210:213], v[82:85]
	v_mfma_f32_16x16x32_bf16 v[74:77], v[176:179], v[218:221], v[74:77]
	v_mfma_f32_16x16x32_bf16 v[66:69], v[186:189], v[218:221], v[66:69]
	v_mfma_f32_16x16x32_bf16 v[122:125], v[180:183], v[198:201], v[122:125]
	v_mfma_f32_16x16x32_bf16 v[114:117], v[190:193], v[198:201], v[114:117]
	v_mfma_f32_16x16x32_bf16 v[106:109], v[180:183], v[206:209], v[106:109]
	v_mfma_f32_16x16x32_bf16 v[98:101], v[190:193], v[206:209], v[98:101]
	v_mfma_f32_16x16x32_bf16 v[90:93], v[180:183], v[214:217], v[90:93]
	v_mfma_f32_16x16x32_bf16 v[82:85], v[190:193], v[214:217], v[82:85]
	v_mfma_f32_16x16x32_bf16 v[74:77], v[180:183], v[222:225], v[74:77]
	v_mfma_f32_16x16x32_bf16 v[66:69], v[190:193], v[222:225], v[66:69]
	s_barrier
; #define PG8_STAGE(bufoff, gbase, voff) do { _Pragma("unroll") for (int _i = 0; _i < 2; ++_i) \
;         __builtin_amdgcn_global_load_lds((const unsigned*)((const char*)(gbase) + (voff)[_i]), (PG8_LAS unsigned*)(lds + (bufoff) + ldsw + _i * 8192), 16, 0, 0); } while (0)
; #define PG8_LDA(dst, b, h) do { _Pragma("unroll") for (int m = 0; m < 4; ++m) _Pragma("unroll") for (int k = 0; k < 2; ++k) dst[m][k] = *(const PG8_LAS bf16x8*)(lds + PG8_SA(b, h) + aoff + m * 2048 + k * 1024); } while (0)
; #define PG8_LDB(dst, b, h) do { _Pragma("unroll") for (int n = 0; n < 2; ++n) _Pragma("unroll") for (int k = 0; k < 2; ++k) dst[n][k] = *(const PG8_LAS bf16x8*)(lds + PG8_SB(b, h) + boff + n * 2048 + k * 1024); } while (0)
; #define PG8_MMA(ai, bj, At, Bt) do { __builtin_amdgcn_s_setprio(1); _Pragma("unroll") for (int m = 0; m < 4; ++m) _Pragma("unroll") for (int n = 0; n < 2; ++n) _Pragma("unroll") for (int k = 0; k < 2; ++k) \
;         acc[ai][bj][m][n] = __builtin_amdgcn_mfma_f32_16x16x32_bf16(Bt[n][k], At[m][k], acc[ai][bj][m][n], 0, 0, 0); __builtin_amdgcn_s_setprio(0); } while (0)
; #define PG8_WAIT_V(n) asm volatile("s_waitcnt vmcnt(" #n ")" ::: "memory")
; #define PG8_WAIT_L(n) asm volatile("s_waitcnt lgkmcnt(" #n ")" ::: "memory")
; #define PG8_BAR __builtin_amdgcn_s_barrier()
; #define PG8_SCHED __builtin_amdgcn_sched_barrier(0)
; template <class Epi, class Sched, bool ALIGN_EPI = false, bool SP2 = false>
; __device__ __forceinline__ void gemm_phase(PG8_LAS unsigned char* lds, const Gemm g, const Sched& S, const Epi& E) {
;     ...
;             PG8_LDA(At, 0, 1); PG8_STAGE(PG8_SB(0, 0), b2, voffB); PG8_STAGE(PG8_SB(0, 1), b2 + hstepB, voffB); PG8_STAGE(PG8_SA(0, 0), a2, voffA);
;             PG8_WAIT_V(8); PG8_WAIT_L(0); PG8_BAR; PG8_MMA(1, 0, At, B0); PG8_MMA(1, 1, At, B1); PG8_BAR; PG8_SCHED;
;             PG8_LDB(B0, 1, 0); PG8_LDB(B1, 1, 1); PG8_SCHED; PG8_LDA(At, 1, 0); PG8_STAGE(PG8_SA(0, 1), a2 + hstepA, voffA);
;             PG8_WAIT_V(8); PG8_WAIT_L(0); PG8_BAR; PG8_MMA(0, 0, At, B0); PG8_MMA(0, 1, At, B1); PG8_BAR; PG8_SCHED;
;             PG8_LDA(At, 1, 1); PG8_STAGE(PG8_SB(1, 0), b3, voffB); PG8_STAGE(PG8_SB(1, 1), b3 + hstepB, voffB); PG8_STAGE(PG8_SA(1, 0), a3, voffA);
	s_setprio 1
	s_add_i32 s4, s89, s3
	v_lshl_add_u64 v[226:227], s[14:15], 0, v[140:141]
	s_mov_b32 m0, s4
	ds_read_b128 v[194:197], v155 offset:16384
	ds_read_b128 v[198:201], v155 offset:17408
	ds_read_b128 v[202:205], v155 offset:18432
	ds_read_b128 v[206:209], v155 offset:19456
	ds_read_b128 v[210:213], v155 offset:20480
	ds_read_b128 v[214:217], v155 offset:21504
	ds_read_b128 v[218:221], v155 offset:22528
	ds_read_b128 v[222:225], v155 offset:23552
	global_load_lds_dwordx4 v[226:227], off
	s_add_i32 m0, s4, 0x2000
	s_add_u32 s70, s14, 0x40000
	v_lshl_add_u64 v[228:229], s[14:15], 0, v[144:145]
	s_addc_u32 s71, s15, 0
	s_add_i32 s4, s90, s3
	global_load_lds_dwordx4 v[228:229], off
	v_lshl_add_u64 v[230:231], s[70:71], 0, v[140:141]
	s_mov_b32 m0, s4
	v_lshl_add_u64 v[232:233], s[16:17], 0, v[142:143]
	global_load_lds_dwordx4 v[230:231], off
	v_lshl_add_u64 v[230:231], s[70:71], 0, v[144:145]
	s_add_i32 m0, s4, 0x2000
	s_nop 0
	global_load_lds_dwordx4 v[230:231], off
	v_lshl_add_u64 v[230:231], s[16:17], 0, v[138:139]
	s_mov_b32 m0, s35
	s_nop 0
	global_load_lds_dwordx4 v[230:231], off
	s_mov_b32 m0, s47
	s_nop 0
	global_load_lds_dwordx4 v[232:233], off
	s_waitcnt vmcnt(8)
	s_waitcnt lgkmcnt(0)
	s_setprio 2
	s_barrier
	v_mfma_f32_16x16x32_bf16 v[62:65], v[130:133], v[194:197], v[62:65]
	v_mfma_f32_16x16x32_bf16 v[54:57], v[168:171], v[194:197], v[54:57]
	v_mfma_f32_16x16x32_bf16 v[46:49], v[130:133], v[202:205], v[46:49]
	v_mfma_f32_16x16x32_bf16 v[38:41], v[168:171], v[202:205], v[38:41]
	v_mfma_f32_16x16x32_bf16 v[30:33], v[130:133], v[210:213], v[30:33]
	v_mfma_f32_16x16x32_bf16 v[22:25], v[168:171], v[210:213], v[22:25]
	v_mfma_f32_16x16x32_bf16 v[14:17], v[130:133], v[218:221], v[14:17]
	v_mfma_f32_16x16x32_bf16 v[6:9], v[168:171], v[218:221], v[6:9]
	v_mfma_f32_16x16x32_bf16 v[62:65], v[134:137], v[198:201], v[62:65]
	v_mfma_f32_16x16x32_bf16 v[54:57], v[172:175], v[198:201], v[54:57]
	v_mfma_f32_16x16x32_bf16 v[46:49], v[134:137], v[206:209], v[46:49]
	v_mfma_f32_16x16x32_bf16 v[38:41], v[172:175], v[206:209], v[38:41]
	v_mfma_f32_16x16x32_bf16 v[30:33], v[134:137], v[214:217], v[30:33]
	v_mfma_f32_16x16x32_bf16 v[22:25], v[172:175], v[214:217], v[22:25]
	v_mfma_f32_16x16x32_bf16 v[14:17], v[134:137], v[222:225], v[14:17]
	v_mfma_f32_16x16x32_bf16 v[6:9], v[172:175], v[222:225], v[6:9]
	v_mfma_f32_16x16x32_bf16 v[58:61], v[176:179], v[194:197], v[58:61]
	v_mfma_f32_16x16x32_bf16 v[50:53], v[186:189], v[194:197], v[50:53]
	v_mfma_f32_16x16x32_bf16 v[42:45], v[176:179], v[202:205], v[42:45]
	v_mfma_f32_16x16x32_bf16 v[34:37], v[186:189], v[202:205], v[34:37]
	v_mfma_f32_16x16x32_bf16 v[26:29], v[176:179], v[210:213], v[26:29]
	v_mfma_f32_16x16x32_bf16 v[18:21], v[186:189], v[210:213], v[18:21]
	v_mfma_f32_16x16x32_bf16 v[10:13], v[176:179], v[218:221], v[10:13]
	v_mfma_f32_16x16x32_bf16 v[2:5], v[186:189], v[218:221], v[2:5]
	v_mfma_f32_16x16x32_bf16 v[58:61], v[180:183], v[198:201], v[58:61]
	v_mfma_f32_16x16x32_bf16 v[50:53], v[190:193], v[198:201], v[50:53]
	v_mfma_f32_16x16x32_bf16 v[42:45], v[180:183], v[206:209], v[42:45]
	v_mfma_f32_16x16x32_bf16 v[34:37], v[190:193], v[206:209], v[34:37]
	v_mfma_f32_16x16x32_bf16 v[26:29], v[180:183], v[214:217], v[26:29]
	v_mfma_f32_16x16x32_bf16 v[18:21], v[190:193], v[214:217], v[18:21]
	v_mfma_f32_16x16x32_bf16 v[10:13], v[180:183], v[222:225], v[10:13]
	v_mfma_f32_16x16x32_bf16 v[2:5], v[190:193], v[222:225], v[2:5]
	s_barrier
	s_setprio 1
	s_add_i32 s4, 0, 0x18000
	v_add_u32_e32 v146, s4, v149
	s_add_i32 s70, 0, 0x1c000
	ds_read_b128 v[130:133], v146
	ds_read_b128 v[134:137], v146 offset:1024
	ds_read_b128 v[168:171], v146 offset:2048
	ds_read_b128 v[172:175], v146 offset:3072
	v_add_u32_e32 v146, s70, v149
	ds_read_b128 v[176:179], v146
	ds_read_b128 v[180:183], v146 offset:1024
	ds_read_b128 v[186:189], v146 offset:2048
	ds_read_b128 v[190:193], v146 offset:3072
	s_add_u32 s16, s16, 0x40000
	s_addc_u32 s17, s17, 0
	s_mov_b32 m0, s82
	v_lshl_add_u64 v[236:237], s[16:17], 0, v[138:139]
	ds_read_b128 v[194:197], v155 offset:32768
	ds_read_b128 v[198:201], v155 offset:33792
	ds_read_b128 v[202:205], v155 offset:34816
	ds_read_b128 v[206:209], v155 offset:35840
	ds_read_b128 v[210:213], v155 offset:36864
	ds_read_b128 v[214:217], v155 offset:37888
	ds_read_b128 v[218:221], v155 offset:38912
	ds_read_b128 v[222:225], v155 offset:39936
	global_load_lds_dwordx4 v[236:237], off
	v_lshl_add_u64 v[236:237], s[16:17], 0, v[142:143]
	s_mov_b32 m0, s83
	s_nop 0
	global_load_lds_dwordx4 v[236:237], off
	s_waitcnt vmcnt(8)
	s_waitcnt lgkmcnt(0)
	s_setprio 2
	s_barrier
; #define PG8_STAGE(bufoff, gbase, voff) do { _Pragma("unroll") for (int _i = 0; _i < 2; ++_i) \
;         __builtin_amdgcn_global_load_lds((const unsigned*)((const char*)(gbase) + (voff)[_i]), (PG8_LAS unsigned*)(lds + (bufoff) + ldsw + _i * 8192), 16, 0, 0); } while (0)
; #define PG8_LDA(dst, b, h) do { _Pragma("unroll") for (int m = 0; m < 4; ++m) _Pragma("unroll") for (int k = 0; k < 2; ++k) dst[m][k] = *(const PG8_LAS bf16x8*)(lds + PG8_SA(b, h) + aoff + m * 2048 + k * 1024); } while (0)
; #define PG8_MMA(ai, bj, At, Bt) do { __builtin_amdgcn_s_setprio(1); _Pragma("unroll") for (int m = 0; m < 4; ++m) _Pragma("unroll") for (int n = 0; n < 2; ++n) _Pragma("unroll") for (int k = 0; k < 2; ++k) \
;         acc[ai][bj][m][n] = __builtin_amdgcn_mfma_f32_16x16x32_bf16(Bt[n][k], At[m][k], acc[ai][bj][m][n], 0, 0, 0); __builtin_amdgcn_s_setprio(0); } while (0)
; #define PG8_WAIT_V(n) asm volatile("s_waitcnt vmcnt(" #n ")" ::: "memory")
; #define PG8_WAIT_L(n) asm volatile("s_waitcnt lgkmcnt(" #n ")" ::: "memory")
; #define PG8_BAR __builtin_amdgcn_s_barrier()
; #define PG8_SCHED __builtin_amdgcn_sched_barrier(0)
; template <class Epi, class Sched, bool ALIGN_EPI = false, bool SP2 = false>
; __device__ __forceinline__ void gemm_phase(PG8_LAS unsigned char* lds, const Gemm g, const Sched& S, const Epi& E) {
;     ...
;             PG8_LDA(At, 1, 1); PG8_STAGE(PG8_SB(1, 0), b3, voffB); PG8_STAGE(PG8_SB(1, 1), b3 + hstepB, voffB); PG8_STAGE(PG8_SA(1, 0), a3, voffA);
;             PG8_WAIT_V(8); PG8_WAIT_L(0); PG8_BAR; PG8_MMA(1, 0, At, B0); PG8_MMA(1, 1, At, B1); PG8_BAR; PG8_SCHED;
;     ...
;         if constexpr (ALIGN_EPI) { if (wr == 0) PG8_BAR; }
	v_mfma_f32_16x16x32_bf16 v[126:129], v[130:133], v[194:197], v[126:129]
	v_mfma_f32_16x16x32_bf16 v[118:121], v[168:171], v[194:197], v[118:121]
	v_mfma_f32_16x16x32_bf16 v[110:113], v[130:133], v[202:205], v[110:113]
	v_mfma_f32_16x16x32_bf16 v[102:105], v[168:171], v[202:205], v[102:105]
	v_mfma_f32_16x16x32_bf16 v[94:97], v[130:133], v[210:213], v[94:97]
	v_mfma_f32_16x16x32_bf16 v[86:89], v[168:171], v[210:213], v[86:89]
	v_mfma_f32_16x16x32_bf16 v[78:81], v[130:133], v[218:221], v[78:81]
	v_mfma_f32_16x16x32_bf16 v[70:73], v[168:171], v[218:221], v[70:73]
	v_mfma_f32_16x16x32_bf16 v[126:129], v[134:137], v[198:201], v[126:129]
	v_mfma_f32_16x16x32_bf16 v[118:121], v[172:175], v[198:201], v[118:121]
	v_mfma_f32_16x16x32_bf16 v[110:113], v[134:137], v[206:209], v[110:113]
	v_mfma_f32_16x16x32_bf16 v[102:105], v[172:175], v[206:209], v[102:105]
	v_mfma_f32_16x16x32_bf16 v[94:97], v[134:137], v[214:217], v[94:97]
	v_mfma_f32_16x16x32_bf16 v[86:89], v[172:175], v[214:217], v[86:89]
	v_mfma_f32_16x16x32_bf16 v[78:81], v[134:137], v[222:225], v[78:81]
	v_mfma_f32_16x16x32_bf16 v[70:73], v[172:175], v[222:225], v[70:73]
	v_mfma_f32_16x16x32_bf16 v[122:125], v[176:179], v[194:197], v[122:125]
	v_mfma_f32_16x16x32_bf16 v[114:117], v[186:189], v[194:197], v[114:117]
	v_mfma_f32_16x16x32_bf16 v[106:109], v[176:179], v[202:205], v[106:109]
	v_mfma_f32_16x16x32_bf16 v[98:101], v[186:189], v[202:205], v[98:101]
	v_mfma_f32_16x16x32_bf16 v[90:93], v[176:179], v[210:213], v[90:93]
	v_mfma_f32_16x16x32_bf16 v[82:85], v[186:189], v[210:213], v[82:85]
	v_mfma_f32_16x16x32_bf16 v[74:77], v[176:179], v[218:221], v[74:77]
	v_mfma_f32_16x16x32_bf16 v[66:69], v[186:189], v[218:221], v[66:69]
	v_mfma_f32_16x16x32_bf16 v[122:125], v[180:183], v[198:201], v[122:125]
	v_mfma_f32_16x16x32_bf16 v[114:117], v[190:193], v[198:201], v[114:117]
	v_mfma_f32_16x16x32_bf16 v[106:109], v[180:183], v[206:209], v[106:109]
	v_mfma_f32_16x16x32_bf16 v[98:101], v[190:193], v[206:209], v[98:101]
	v_mfma_f32_16x16x32_bf16 v[90:93], v[180:183], v[214:217], v[90:93]
	v_mfma_f32_16x16x32_bf16 v[82:85], v[190:193], v[214:217], v[82:85]
	v_mfma_f32_16x16x32_bf16 v[74:77], v[180:183], v[222:225], v[74:77]
	v_mfma_f32_16x16x32_bf16 v[66:69], v[190:193], v[222:225], v[66:69]
	s_barrier
	s_setprio 1
	s_add_i32 s4, s4, s3
	v_lshl_add_u64 v[226:227], v[226:227], 0, s[42:43]
	s_mov_b32 m0, s4
	ds_read_b128 v[194:197], v155 offset:49152
	ds_read_b128 v[198:201], v155 offset:50176
	ds_read_b128 v[202:205], v155 offset:51200
	ds_read_b128 v[206:209], v155 offset:52224
	ds_read_b128 v[210:213], v155 offset:53248
	ds_read_b128 v[214:217], v155 offset:54272
	ds_read_b128 v[218:221], v155 offset:55296
	ds_read_b128 v[222:225], v155 offset:56320
	global_load_lds_dwordx4 v[226:227], off
	s_add_i32 m0, s4, 0x2000
	s_add_u32 s14, s14, 0x40080
	v_lshl_add_u64 v[226:227], v[228:229], 0, s[42:43]
	s_addc_u32 s15, s15, 0
	s_add_i32 s4, s70, s3
	global_load_lds_dwordx4 v[226:227], off
	v_lshl_add_u64 v[226:227], s[14:15], 0, v[140:141]
	s_mov_b32 m0, s4
	s_nop 0
	global_load_lds_dwordx4 v[226:227], off
	v_lshl_add_u64 v[226:227], s[14:15], 0, v[144:145]
	s_add_i32 m0, s4, 0x2000
	s_nop 0
	global_load_lds_dwordx4 v[226:227], off
	v_lshl_add_u64 v[226:227], v[230:231], 0, s[42:43]
	s_mov_b32 m0, s87
	s_nop 0
	global_load_lds_dwordx4 v[226:227], off
	v_lshl_add_u64 v[226:227], v[232:233], 0, s[42:43]
	s_mov_b32 m0, s88
	s_nop 0
	global_load_lds_dwordx4 v[226:227], off
	s_waitcnt vmcnt(8)
	s_waitcnt lgkmcnt(0)
	s_setprio 2
	s_barrier
	v_mfma_f32_16x16x32_bf16 v[62:65], v[130:133], v[194:197], v[62:65]
	v_mfma_f32_16x16x32_bf16 v[54:57], v[168:171], v[194:197], v[54:57]
	v_mfma_f32_16x16x32_bf16 v[46:49], v[130:133], v[202:205], v[46:49]
	v_mfma_f32_16x16x32_bf16 v[38:41], v[168:171], v[202:205], v[38:41]
	v_mfma_f32_16x16x32_bf16 v[30:33], v[130:133], v[210:213], v[30:33]
	v_mfma_f32_16x16x32_bf16 v[22:25], v[168:171], v[210:213], v[22:25]
	v_mfma_f32_16x16x32_bf16 v[14:17], v[130:133], v[218:221], v[14:17]
	v_mfma_f32_16x16x32_bf16 v[6:9], v[168:171], v[218:221], v[6:9]
	v_mfma_f32_16x16x32_bf16 v[62:65], v[134:137], v[198:201], v[62:65]
	v_mfma_f32_16x16x32_bf16 v[54:57], v[172:175], v[198:201], v[54:57]
	v_mfma_f32_16x16x32_bf16 v[46:49], v[134:137], v[206:209], v[46:49]
	v_mfma_f32_16x16x32_bf16 v[38:41], v[172:175], v[206:209], v[38:41]
	v_mfma_f32_16x16x32_bf16 v[30:33], v[134:137], v[214:217], v[30:33]
	v_mfma_f32_16x16x32_bf16 v[22:25], v[172:175], v[214:217], v[22:25]
	v_mfma_f32_16x16x32_bf16 v[14:17], v[134:137], v[222:225], v[14:17]
	v_mfma_f32_16x16x32_bf16 v[6:9], v[172:175], v[222:225], v[6:9]
	v_mfma_f32_16x16x32_bf16 v[58:61], v[176:179], v[194:197], v[58:61]
	v_mfma_f32_16x16x32_bf16 v[50:53], v[186:189], v[194:197], v[50:53]
	v_mfma_f32_16x16x32_bf16 v[42:45], v[176:179], v[202:205], v[42:45]
	v_mfma_f32_16x16x32_bf16 v[34:37], v[186:189], v[202:205], v[34:37]
	v_mfma_f32_16x16x32_bf16 v[26:29], v[176:179], v[210:213], v[26:29]
	v_mfma_f32_16x16x32_bf16 v[18:21], v[186:189], v[210:213], v[18:21]
	v_mfma_f32_16x16x32_bf16 v[10:13], v[176:179], v[218:221], v[10:13]
	v_mfma_f32_16x16x32_bf16 v[2:5], v[186:189], v[218:221], v[2:5]
	v_mfma_f32_16x16x32_bf16 v[58:61], v[180:183], v[198:201], v[58:61]
	v_mfma_f32_16x16x32_bf16 v[50:53], v[190:193], v[198:201], v[50:53]
	v_mfma_f32_16x16x32_bf16 v[42:45], v[180:183], v[206:209], v[42:45]
	v_mfma_f32_16x16x32_bf16 v[34:37], v[190:193], v[206:209], v[34:37]
	v_mfma_f32_16x16x32_bf16 v[26:29], v[180:183], v[214:217], v[26:29]
	v_mfma_f32_16x16x32_bf16 v[18:21], v[190:193], v[214:217], v[18:21]
	v_mfma_f32_16x16x32_bf16 v[10:13], v[180:183], v[222:225], v[10:13]
	v_mfma_f32_16x16x32_bf16 v[2:5], v[190:193], v[222:225], v[2:5]
	s_barrier
	s_setprio 1
	s_add_i32 s51, s51, 2
	s_add_u32 s12, s12, 0x100
	s_addc_u32 s13, s13, 0
	s_add_u32 s38, s38, 0x100
	s_addc_u32 s49, s49, 0
	s_cmp_gt_u32 s51, 13
	s_cbranch_scc0 .Lph135_y
	s_setprio 0
.Lph135_x:
	s_and_b64 vcc, exec, s[44:45]
	s_cbranch_vccz .LBB0_138
	s_barrier

;     __host__ __device__ bool next(int i, Unit& u) const { if (!so.next(i >> 1, u)) return false; u.k0 = (i & 1) * 512; return true; }
;     __host__ __device__ bool next(int i, Unit& u) const { if (!so.next(i, u)) return false; u.pe = main_tile(u.pn); return true; }
;     __host__ __device__ bool next(int i, Unit& u) const { if (start + i * stride >= limit) return false; if (!so.next(i, u)) return false; u.pe = late_tile(u.pn); return true; }
; #define PG8_STAGE(bufoff, gbase, voff) do { _Pragma("unroll") for (int _i = 0; _i < 2; ++_i) \
;         __builtin_amdgcn_global_load_lds((const unsigned*)((const char*)(gbase) + (voff)[_i]), (PG8_LAS unsigned*)(lds + (bufoff) + ldsw + _i * 8192), 16, 0, 0); } while (0)
; #define PG8_WAIT_V(n) asm volatile("s_waitcnt vmcnt(" #n ")" ::: "memory")
; #define PG8_WAIT_L(n) asm volatile("s_waitcnt lgkmcnt(" #n ")" ::: "memory")
; template <class Epi, class Sched, bool ALIGN_EPI = false, bool SP2 = false>
; __device__ __forceinline__ void gemm_phase(PG8_LAS unsigned char* lds, const Gemm g, const Sched& S, const Epi& E) {
;     ...
;         const bool has_next = S.next(ui + 1, nxt);
;         const char* nA = has_next ? (const char*)g.A + (size_t)nxt.pm * tstepA + (size_t)nxt.k0 * 2 : cA; const char* nB = has_next ? (const char*)g.Bt + (size_t)nxt.pn * tstepB + (size_t)nxt.k0 * 2 : cB;
;         for (int t = 0; t < nt; t += 2) {
;             const bool last = (t == nt - 2);
;             const char* a1 = cA + (size_t)(t + 1) * kstepA;
;             const char* a2 = last ? nA : cA + (size_t)(t + 2) * kstepA; const char* b2 = last ? nB : cB + (size_t)(t + 2) * kstep;
;             const char* a3 = a2 + kstepA; const char* b3 = b2 + kstep;
;             if (last && has_next) S.a_ready(nxt);
;             if constexpr (SP2) {
;             PG8_LDB(B0, 0, 0); PG8_LDB(B1, 0, 1); PG8_SCHED; PG8_LDA(At, 0, 0); PG8_STAGE(PG8_SA(1, 1), a1 + hstepA, voffA);
;             PG8_WAIT_V(8); PG8_WAIT_L(0); PG8_BAR; PG8_MMA(0, 0, At, B0); PG8_MMA(0, 1, At, B1); PG8_BAR; PG8_SCHED;
;     ...
;         if (!keep_) {
; #pragma unroll
;         for (int a = 0; a < 2; ++a)
; #pragma unroll
;             for (int b = 0; b < 2; ++b)
; #pragma unroll
;                 for (int m = 0; m < 4; ++m)
; #pragma unroll
;                     for (int n = 0; n < 2; ++n) acc[a][b][m][n] = (f32x4){0.f, 0.f, 0.f, 0.f};
;         }
.LBB0_690:
	s_ashr_i32 s79, s78, 31
	s_lshl_b64 s[66:67], s[78:79], 19
	s_add_u32 s82, s20, s66
	s_addc_u32 s83, s21, s67
	s_and_b64 s[66:67], s[80:81], exec
	s_cselect_b32 s3, s83, s9
	s_cselect_b32 s7, s82, s8
	s_ashr_i32 s77, s76, 31
	s_lshl_b64 s[66:67], s[76:77], 19
	s_mov_b32 s42, s84
	s_add_u32 s84, s84, s66
	s_addc_u32 s85, s5, s67
	s_and_b64 s[66:67], s[80:81], exec
	s_cselect_b32 s33, s85, s11
	s_cselect_b32 s35, s84, s10
	s_add_u32 s8, s8, 0x40080
	s_addc_u32 s9, s9, 0
	s_add_u32 s46, s10, 0x100
	v_mov_b32_e32 v2, 0
	s_addc_u32 s66, s11, 0
	s_mov_b32 s67, -2
	v_mov_b32_e32 v3, v2
	v_mov_b32_e32 v4, v2
	v_mov_b32_e32 v5, v2
	v_mov_b32_e32 v10, v2
	v_mov_b32_e32 v11, v2
	v_mov_b32_e32 v12, v2
	v_mov_b32_e32 v13, v2
	s_waitcnt vmcnt(0)
	v_mov_b32_e32 v18, v2
	v_mov_b32_e32 v19, v2
	v_mov_b32_e32 v20, v2
	v_mov_b32_e32 v21, v2
	v_mov_b32_e32 v26, v2
	v_mov_b32_e32 v27, v2
	v_mov_b32_e32 v28, v2
	v_mov_b32_e32 v29, v2
	v_mov_b32_e32 v34, v2
	v_mov_b32_e32 v35, v2
	v_mov_b32_e32 v36, v2
	v_mov_b32_e32 v37, v2
	v_mov_b32_e32 v42, v2
	v_mov_b32_e32 v43, v2
	v_mov_b32_e32 v44, v2
	v_mov_b32_e32 v45, v2
	v_mov_b32_e32 v50, v2
	v_mov_b32_e32 v51, v2
	v_mov_b32_e32 v52, v2
	v_mov_b32_e32 v53, v2
	v_mov_b32_e32 v58, v2
	v_mov_b32_e32 v59, v2
	v_mov_b32_e32 v60, v2
	v_mov_b32_e32 v61, v2
	v_mov_b32_e32 v6, v2
	v_mov_b32_e32 v7, v2
	v_mov_b32_e32 v8, v2
	v_mov_b32_e32 v9, v2
	v_mov_b32_e32 v14, v2
	v_mov_b32_e32 v15, v2
	v_mov_b32_e32 v16, v2
	v_mov_b32_e32 v17, v2
	v_mov_b32_e32 v22, v2
	v_mov_b32_e32 v23, v2
	v_mov_b32_e32 v24, v2
	v_mov_b32_e32 v25, v2
	v_mov_b32_e32 v30, v2
	v_mov_b32_e32 v31, v2
	v_mov_b32_e32 v32, v2
	v_mov_b32_e32 v33, v2
	v_mov_b32_e32 v38, v2
	v_mov_b32_e32 v39, v2
	v_mov_b32_e32 v40, v2
	v_mov_b32_e32 v41, v2
	v_mov_b32_e32 v46, v2
	v_mov_b32_e32 v47, v2
	v_mov_b32_e32 v48, v2
	v_mov_b32_e32 v49, v2
	v_mov_b32_e32 v54, v2
	v_mov_b32_e32 v55, v2
	v_mov_b32_e32 v56, v2
	v_mov_b32_e32 v57, v2
	v_mov_b32_e32 v62, v2
	v_mov_b32_e32 v63, v2
	v_mov_b32_e32 v64, v2
	v_mov_b32_e32 v65, v2
	v_mov_b32_e32 v66, v2
	v_mov_b32_e32 v67, v2
	v_mov_b32_e32 v68, v2
	v_mov_b32_e32 v69, v2
	v_mov_b32_e32 v74, v2
	v_mov_b32_e32 v75, v2
	v_mov_b32_e32 v76, v2
	v_mov_b32_e32 v77, v2
	v_mov_b32_e32 v82, v2
	v_mov_b32_e32 v83, v2
	v_mov_b32_e32 v84, v2
	v_mov_b32_e32 v85, v2
	v_mov_b32_e32 v90, v2
	v_mov_b32_e32 v91, v2
	v_mov_b32_e32 v92, v2
	v_mov_b32_e32 v93, v2
	v_mov_b32_e32 v98, v2
	v_mov_b32_e32 v99, v2
	v_mov_b32_e32 v100, v2
	v_mov_b32_e32 v101, v2
	v_mov_b32_e32 v106, v2
	v_mov_b32_e32 v107, v2
	v_mov_b32_e32 v108, v2
	v_mov_b32_e32 v109, v2
	v_mov_b32_e32 v114, v2
	v_mov_b32_e32 v115, v2
	v_mov_b32_e32 v116, v2
	v_mov_b32_e32 v117, v2
	v_mov_b32_e32 v122, v2
	v_mov_b32_e32 v123, v2
	v_mov_b32_e32 v124, v2
	v_mov_b32_e32 v125, v2
	v_mov_b32_e32 v70, v2
	v_mov_b32_e32 v71, v2
	v_mov_b32_e32 v72, v2
	v_mov_b32_e32 v73, v2
	v_mov_b32_e32 v78, v2
	v_mov_b32_e32 v79, v2
	v_mov_b32_e32 v80, v2
	v_mov_b32_e32 v81, v2
	v_mov_b32_e32 v86, v2
	v_mov_b32_e32 v87, v2
	v_mov_b32_e32 v88, v2
	v_mov_b32_e32 v89, v2
	v_mov_b32_e32 v94, v2
	v_mov_b32_e32 v95, v2
	v_mov_b32_e32 v96, v2
	v_mov_b32_e32 v97, v2
	v_mov_b32_e32 v102, v2
	v_mov_b32_e32 v103, v2
	v_mov_b32_e32 v104, v2
	v_mov_b32_e32 v105, v2
	v_mov_b32_e32 v110, v2
	v_mov_b32_e32 v111, v2
	v_mov_b32_e32 v112, v2
	v_mov_b32_e32 v113, v2
	v_mov_b32_e32 v118, v2
	v_mov_b32_e32 v119, v2
	v_mov_b32_e32 v120, v2
	v_mov_b32_e32 v121, v2
	v_mov_b32_e32 v126, v2
	v_mov_b32_e32 v127, v2
	v_mov_b32_e32 v128, v2
	v_mov_b32_e32 v129, v2
	s_cmp_lg_u32 s101, 0
	s_cbranch_scc1 .Lph691_y
.LBB0_691:
	ds_read_b128 v[130:133], v151
	ds_read_b128 v[134:137], v151 offset:1024
	ds_read_b128 v[166:169], v151 offset:2048
	ds_read_b128 v[170:173], v151 offset:3072
	ds_read_b128 v[174:177], v153
	ds_read_b128 v[178:181], v153 offset:1024
	ds_read_b128 v[182:185], v153 offset:2048
	ds_read_b128 v[186:189], v153 offset:3072
	s_add_u32 s4, s8, 0xfffc0080
	s_addc_u32 s10, s9, -1
	s_cmp_eq_u32 s67, 12
	s_cselect_b32 s87, s3, s10
	s_cselect_b32 s86, s7, s4
	s_cselect_b32 s11, s33, s66
	s_cselect_b32 s10, s35, s46
	v_lshl_add_u64 v[222:223], s[8:9], 0, v[160:161]
	s_add_i32 m0, s38, 0xc000
	ds_read_b128 v[190:193], v155
	ds_read_b128 v[194:197], v155 offset:1024
	ds_read_b128 v[198:201], v155 offset:2048
	ds_read_b128 v[202:205], v155 offset:3072
	ds_read_b128 v[206:209], v155 offset:4096
	ds_read_b128 v[210:213], v155 offset:5120
	ds_read_b128 v[214:217], v155 offset:6144
	ds_read_b128 v[218:221], v155 offset:7168
	global_load_lds_dwordx4 v[222:223], off
	v_lshl_add_u64 v[222:223], s[8:9], 0, v[162:163]
	s_add_i32 m0, s38, 0xe000
	s_nop 0
	global_load_lds_dwordx4 v[222:223], off
	s_waitcnt vmcnt(8)
	s_waitcnt lgkmcnt(0)
	s_setprio 1
	s_barrier
; #define PG8_STAGE(bufoff, gbase, voff) do { _Pragma("unroll") for (int _i = 0; _i < 2; ++_i) \
;         __builtin_amdgcn_global_load_lds((const unsigned*)((const char*)(gbase) + (voff)[_i]), (PG8_LAS unsigned*)(lds + (bufoff) + ldsw + _i * 8192), 16, 0, 0); } while (0)
; #define PG8_LDA(dst, b, h) do { _Pragma("unroll") for (int m = 0; m < 4; ++m) _Pragma("unroll") for (int k = 0; k < 2; ++k) dst[m][k] = *(const PG8_LAS bf16x8*)(lds + PG8_SA(b, h) + aoff + m * 2048 + k * 1024); } while (0)
; #define PG8_MMA(ai, bj, At, Bt) do { __builtin_amdgcn_s_setprio(1); _Pragma("unroll") for (int m = 0; m < 4; ++m) _Pragma("unroll") for (int n = 0; n < 2; ++n) _Pragma("unroll") for (int k = 0; k < 2; ++k) \
;         acc[ai][bj][m][n] = __builtin_amdgcn_mfma_f32_16x16x32_bf16(Bt[n][k], At[m][k], acc[ai][bj][m][n], 0, 0, 0); __builtin_amdgcn_s_setprio(0); } while (0)
; #define PG8_WAIT_V(n) asm volatile("s_waitcnt vmcnt(" #n ")" ::: "memory")
; #define PG8_WAIT_L(n) asm volatile("s_waitcnt lgkmcnt(" #n ")" ::: "memory")
; #define PG8_BAR __builtin_amdgcn_s_barrier()
; #define PG8_SCHED __builtin_amdgcn_sched_barrier(0)
; template <class Epi, class Sched, bool ALIGN_EPI = false, bool SP2 = false>
; __device__ __forceinline__ void gemm_phase(PG8_LAS unsigned char* lds, const Gemm g, const Sched& S, const Epi& E) {
;     ...
;             PG8_WAIT_V(8); PG8_WAIT_L(0); PG8_BAR; PG8_MMA(0, 0, At, B0); PG8_MMA(0, 1, At, B1); PG8_BAR; PG8_SCHED;
;             PG8_LDA(At, 0, 1); PG8_STAGE(PG8_SB(0, 0), b2, voffB); PG8_STAGE(PG8_SB(0, 1), b2 + hstepB, voffB); PG8_STAGE(PG8_SA(0, 0), a2, voffA);
;             PG8_WAIT_V(8); PG8_WAIT_L(0); PG8_BAR; PG8_MMA(1, 0, At, B0); PG8_MMA(1, 1, At, B1); PG8_BAR; PG8_SCHED;
	v_mfma_f32_16x16x32_bf16 v[126:129], v[130:133], v[190:193], v[126:129]
	v_mfma_f32_16x16x32_bf16 v[118:121], v[166:169], v[190:193], v[118:121]
	v_mfma_f32_16x16x32_bf16 v[110:113], v[130:133], v[198:201], v[110:113]
	v_mfma_f32_16x16x32_bf16 v[102:105], v[166:169], v[198:201], v[102:105]
	v_mfma_f32_16x16x32_bf16 v[94:97], v[130:133], v[206:209], v[94:97]
	v_mfma_f32_16x16x32_bf16 v[86:89], v[166:169], v[206:209], v[86:89]
	v_mfma_f32_16x16x32_bf16 v[78:81], v[130:133], v[214:217], v[78:81]
	v_mfma_f32_16x16x32_bf16 v[70:73], v[166:169], v[214:217], v[70:73]
	v_mfma_f32_16x16x32_bf16 v[126:129], v[134:137], v[194:197], v[126:129]
	v_mfma_f32_16x16x32_bf16 v[118:121], v[170:173], v[194:197], v[118:121]
	v_mfma_f32_16x16x32_bf16 v[110:113], v[134:137], v[202:205], v[110:113]
	v_mfma_f32_16x16x32_bf16 v[102:105], v[170:173], v[202:205], v[102:105]
	v_mfma_f32_16x16x32_bf16 v[94:97], v[134:137], v[210:213], v[94:97]
	v_mfma_f32_16x16x32_bf16 v[86:89], v[170:173], v[210:213], v[86:89]
	v_mfma_f32_16x16x32_bf16 v[78:81], v[134:137], v[218:221], v[78:81]
	v_mfma_f32_16x16x32_bf16 v[70:73], v[170:173], v[218:221], v[70:73]
	v_mfma_f32_16x16x32_bf16 v[122:125], v[174:177], v[190:193], v[122:125]
	v_mfma_f32_16x16x32_bf16 v[114:117], v[182:185], v[190:193], v[114:117]
	v_mfma_f32_16x16x32_bf16 v[106:109], v[174:177], v[198:201], v[106:109]
	v_mfma_f32_16x16x32_bf16 v[98:101], v[182:185], v[198:201], v[98:101]
	v_mfma_f32_16x16x32_bf16 v[90:93], v[174:177], v[206:209], v[90:93]
	v_mfma_f32_16x16x32_bf16 v[82:85], v[182:185], v[206:209], v[82:85]
	v_mfma_f32_16x16x32_bf16 v[74:77], v[174:177], v[214:217], v[74:77]
	v_mfma_f32_16x16x32_bf16 v[66:69], v[182:185], v[214:217], v[66:69]
	v_mfma_f32_16x16x32_bf16 v[122:125], v[178:181], v[194:197], v[122:125]
	v_mfma_f32_16x16x32_bf16 v[114:117], v[186:189], v[194:197], v[114:117]
	v_mfma_f32_16x16x32_bf16 v[106:109], v[178:181], v[202:205], v[106:109]
	v_mfma_f32_16x16x32_bf16 v[98:101], v[186:189], v[202:205], v[98:101]
	v_mfma_f32_16x16x32_bf16 v[90:93], v[178:181], v[210:213], v[90:93]
	v_mfma_f32_16x16x32_bf16 v[82:85], v[186:189], v[210:213], v[82:85]
	v_mfma_f32_16x16x32_bf16 v[74:77], v[178:181], v[218:221], v[74:77]
	v_mfma_f32_16x16x32_bf16 v[66:69], v[186:189], v[218:221], v[66:69]
	s_barrier
	s_setprio 0
	s_add_i32 s4, s47, s37
	v_lshl_add_u64 v[222:223], s[10:11], 0, v[140:141]
	s_mov_b32 m0, s4
	ds_read_b128 v[190:193], v155 offset:16384
	ds_read_b128 v[194:197], v155 offset:17408
	ds_read_b128 v[198:201], v155 offset:18432
	ds_read_b128 v[202:205], v155 offset:19456
	ds_read_b128 v[206:209], v155 offset:20480
	ds_read_b128 v[210:213], v155 offset:21504
	ds_read_b128 v[214:217], v155 offset:22528
	ds_read_b128 v[218:221], v155 offset:23552
	global_load_lds_dwordx4 v[222:223], off
	s_add_i32 m0, s4, 0x2000
	s_add_u32 s88, s10, 0x40000
	v_lshl_add_u64 v[224:225], s[10:11], 0, v[144:145]
	s_addc_u32 s89, s11, 0
	s_add_i32 s4, s48, s37
	global_load_lds_dwordx4 v[224:225], off
	v_lshl_add_u64 v[226:227], s[88:89], 0, v[140:141]
	s_mov_b32 m0, s4
	v_lshl_add_u64 v[228:229], s[86:87], 0, v[142:143]
	global_load_lds_dwordx4 v[226:227], off
	v_lshl_add_u64 v[226:227], s[88:89], 0, v[144:145]
	s_add_i32 m0, s4, 0x2000
	s_nop 0
	global_load_lds_dwordx4 v[226:227], off
	v_lshl_add_u64 v[226:227], s[86:87], 0, v[138:139]
	s_mov_b32 m0, s38
	s_nop 0
	global_load_lds_dwordx4 v[226:227], off
	s_mov_b32 m0, s39
	s_nop 0
	global_load_lds_dwordx4 v[228:229], off
	s_waitcnt vmcnt(8)
	s_waitcnt lgkmcnt(0)
	s_setprio 1
	s_barrier
	v_mfma_f32_16x16x32_bf16 v[62:65], v[130:133], v[190:193], v[62:65]
	v_mfma_f32_16x16x32_bf16 v[54:57], v[166:169], v[190:193], v[54:57]
	v_mfma_f32_16x16x32_bf16 v[46:49], v[130:133], v[198:201], v[46:49]
	v_mfma_f32_16x16x32_bf16 v[38:41], v[166:169], v[198:201], v[38:41]
	v_mfma_f32_16x16x32_bf16 v[30:33], v[130:133], v[206:209], v[30:33]
	v_mfma_f32_16x16x32_bf16 v[22:25], v[166:169], v[206:209], v[22:25]
	v_mfma_f32_16x16x32_bf16 v[14:17], v[130:133], v[214:217], v[14:17]
	v_mfma_f32_16x16x32_bf16 v[6:9], v[166:169], v[214:217], v[6:9]
	v_mfma_f32_16x16x32_bf16 v[62:65], v[134:137], v[194:197], v[62:65]
	v_mfma_f32_16x16x32_bf16 v[54:57], v[170:173], v[194:197], v[54:57]
	v_mfma_f32_16x16x32_bf16 v[46:49], v[134:137], v[202:205], v[46:49]
	v_mfma_f32_16x16x32_bf16 v[38:41], v[170:173], v[202:205], v[38:41]
	v_mfma_f32_16x16x32_bf16 v[30:33], v[134:137], v[210:213], v[30:33]
	v_mfma_f32_16x16x32_bf16 v[22:25], v[170:173], v[210:213], v[22:25]
	v_mfma_f32_16x16x32_bf16 v[14:17], v[134:137], v[218:221], v[14:17]
	v_mfma_f32_16x16x32_bf16 v[6:9], v[170:173], v[218:221], v[6:9]
	v_mfma_f32_16x16x32_bf16 v[58:61], v[174:177], v[190:193], v[58:61]
	v_mfma_f32_16x16x32_bf16 v[50:53], v[182:185], v[190:193], v[50:53]
	v_mfma_f32_16x16x32_bf16 v[42:45], v[174:177], v[198:201], v[42:45]
	v_mfma_f32_16x16x32_bf16 v[34:37], v[182:185], v[198:201], v[34:37]
	v_mfma_f32_16x16x32_bf16 v[26:29], v[174:177], v[206:209], v[26:29]
	v_mfma_f32_16x16x32_bf16 v[18:21], v[182:185], v[206:209], v[18:21]
	v_mfma_f32_16x16x32_bf16 v[10:13], v[174:177], v[214:217], v[10:13]
	v_mfma_f32_16x16x32_bf16 v[2:5], v[182:185], v[214:217], v[2:5]
	v_mfma_f32_16x16x32_bf16 v[58:61], v[178:181], v[194:197], v[58:61]
	v_mfma_f32_16x16x32_bf16 v[50:53], v[186:189], v[194:197], v[50:53]
	v_mfma_f32_16x16x32_bf16 v[42:45], v[178:181], v[202:205], v[42:45]
	v_mfma_f32_16x16x32_bf16 v[34:37], v[186:189], v[202:205], v[34:37]
	v_mfma_f32_16x16x32_bf16 v[26:29], v[178:181], v[210:213], v[26:29]
	v_mfma_f32_16x16x32_bf16 v[18:21], v[186:189], v[210:213], v[18:21]
	v_mfma_f32_16x16x32_bf16 v[10:13], v[178:181], v[218:221], v[10:13]
	v_mfma_f32_16x16x32_bf16 v[2:5], v[186:189], v[218:221], v[2:5]
	s_barrier
; #define PG8_STAGE(bufoff, gbase, voff) do { _Pragma("unroll") for (int _i = 0; _i < 2; ++_i) \
;         __builtin_amdgcn_global_load_lds((const unsigned*)((const char*)(gbase) + (voff)[_i]), (PG8_LAS unsigned*)(lds + (bufoff) + ldsw + _i * 8192), 16, 0, 0); } while (0)
; #define PG8_LDA(dst, b, h) do { _Pragma("unroll") for (int m = 0; m < 4; ++m) _Pragma("unroll") for (int k = 0; k < 2; ++k) dst[m][k] = *(const PG8_LAS bf16x8*)(lds + PG8_SA(b, h) + aoff + m * 2048 + k * 1024); } while (0)
; #define PG8_LDB(dst, b, h) do { _Pragma("unroll") for (int n = 0; n < 2; ++n) _Pragma("unroll") for (int k = 0; k < 2; ++k) dst[n][k] = *(const PG8_LAS bf16x8*)(lds + PG8_SB(b, h) + boff + n * 2048 + k * 1024); } while (0)
; #define PG8_MMA(ai, bj, At, Bt) do { __builtin_amdgcn_s_setprio(1); _Pragma("unroll") for (int m = 0; m < 4; ++m) _Pragma("unroll") for (int n = 0; n < 2; ++n) _Pragma("unroll") for (int k = 0; k < 2; ++k) \
;         acc[ai][bj][m][n] = __builtin_amdgcn_mfma_f32_16x16x32_bf16(Bt[n][k], At[m][k], acc[ai][bj][m][n], 0, 0, 0); __builtin_amdgcn_s_setprio(0); } while (0)
; #define PG8_WAIT_V(n) asm volatile("s_waitcnt vmcnt(" #n ")" ::: "memory")
; #define PG8_WAIT_L(n) asm volatile("s_waitcnt lgkmcnt(" #n ")" ::: "memory")
; #define PG8_BAR __builtin_amdgcn_s_barrier()
; #define PG8_SCHED __builtin_amdgcn_sched_barrier(0)
; template <class Epi, class Sched, bool ALIGN_EPI = false, bool SP2 = false>
; __device__ __forceinline__ void gemm_phase(PG8_LAS unsigned char* lds, const Gemm g, const Sched& S, const Epi& E) {
;     ...
;             PG8_LDB(B0, 1, 0); PG8_LDB(B1, 1, 1); PG8_SCHED; PG8_LDA(At, 1, 0); PG8_STAGE(PG8_SA(0, 1), a2 + hstepA, voffA);
;             PG8_WAIT_V(8); PG8_WAIT_L(0); PG8_BAR; PG8_MMA(0, 0, At, B0); PG8_MMA(0, 1, At, B1); PG8_BAR; PG8_SCHED;
;             PG8_LDA(At, 1, 1); PG8_STAGE(PG8_SB(1, 0), b3, voffB); PG8_STAGE(PG8_SB(1, 1), b3 + hstepB, voffB); PG8_STAGE(PG8_SA(1, 0), a3, voffA);
;             PG8_WAIT_V(8); PG8_WAIT_L(0); PG8_BAR; PG8_MMA(1, 0, At, B0); PG8_MMA(1, 1, At, B1); PG8_BAR; PG8_SCHED;
	s_setprio 0
	s_add_i32 s4, 0, 0x18000
	v_add_u32_e32 v146, s4, v149
	s_add_i32 s68, 0, 0x1c000
	ds_read_b128 v[130:133], v146
	ds_read_b128 v[134:137], v146 offset:1024
	ds_read_b128 v[166:169], v146 offset:2048
	ds_read_b128 v[170:173], v146 offset:3072
	v_add_u32_e32 v146, s68, v149
	ds_read_b128 v[174:177], v146
	ds_read_b128 v[178:181], v146 offset:1024
	ds_read_b128 v[182:185], v146 offset:2048
	ds_read_b128 v[186:189], v146 offset:3072
	s_add_u32 s86, s86, 0x40000
	s_addc_u32 s87, s87, 0
	s_mov_b32 m0, s40
	v_lshl_add_u64 v[230:231], s[86:87], 0, v[138:139]
	ds_read_b128 v[190:193], v155 offset:32768
	ds_read_b128 v[194:197], v155 offset:33792
	ds_read_b128 v[198:201], v155 offset:34816
	ds_read_b128 v[202:205], v155 offset:35840
	ds_read_b128 v[206:209], v155 offset:36864
	ds_read_b128 v[210:213], v155 offset:37888
	ds_read_b128 v[214:217], v155 offset:38912
	ds_read_b128 v[218:221], v155 offset:39936
	global_load_lds_dwordx4 v[230:231], off
	v_lshl_add_u64 v[230:231], s[86:87], 0, v[142:143]
	s_mov_b32 m0, s41
	s_nop 0
	global_load_lds_dwordx4 v[230:231], off
	s_waitcnt vmcnt(8)
	s_waitcnt lgkmcnt(0)
	s_setprio 1
	s_barrier
	v_mfma_f32_16x16x32_bf16 v[126:129], v[130:133], v[190:193], v[126:129]
	v_mfma_f32_16x16x32_bf16 v[118:121], v[166:169], v[190:193], v[118:121]
	v_mfma_f32_16x16x32_bf16 v[110:113], v[130:133], v[198:201], v[110:113]
	v_mfma_f32_16x16x32_bf16 v[102:105], v[166:169], v[198:201], v[102:105]
	v_mfma_f32_16x16x32_bf16 v[94:97], v[130:133], v[206:209], v[94:97]
	v_mfma_f32_16x16x32_bf16 v[86:89], v[166:169], v[206:209], v[86:89]
	v_mfma_f32_16x16x32_bf16 v[78:81], v[130:133], v[214:217], v[78:81]
	v_mfma_f32_16x16x32_bf16 v[70:73], v[166:169], v[214:217], v[70:73]
	v_mfma_f32_16x16x32_bf16 v[126:129], v[134:137], v[194:197], v[126:129]
	v_mfma_f32_16x16x32_bf16 v[118:121], v[170:173], v[194:197], v[118:121]
	v_mfma_f32_16x16x32_bf16 v[110:113], v[134:137], v[202:205], v[110:113]
	v_mfma_f32_16x16x32_bf16 v[102:105], v[170:173], v[202:205], v[102:105]
	v_mfma_f32_16x16x32_bf16 v[94:97], v[134:137], v[210:213], v[94:97]
	v_mfma_f32_16x16x32_bf16 v[86:89], v[170:173], v[210:213], v[86:89]
	v_mfma_f32_16x16x32_bf16 v[78:81], v[134:137], v[218:221], v[78:81]
	v_mfma_f32_16x16x32_bf16 v[70:73], v[170:173], v[218:221], v[70:73]
	v_mfma_f32_16x16x32_bf16 v[122:125], v[174:177], v[190:193], v[122:125]
	v_mfma_f32_16x16x32_bf16 v[114:117], v[182:185], v[190:193], v[114:117]
	v_mfma_f32_16x16x32_bf16 v[106:109], v[174:177], v[198:201], v[106:109]
	v_mfma_f32_16x16x32_bf16 v[98:101], v[182:185], v[198:201], v[98:101]
	v_mfma_f32_16x16x32_bf16 v[90:93], v[174:177], v[206:209], v[90:93]
	v_mfma_f32_16x16x32_bf16 v[82:85], v[182:185], v[206:209], v[82:85]
	v_mfma_f32_16x16x32_bf16 v[74:77], v[174:177], v[214:217], v[74:77]
	v_mfma_f32_16x16x32_bf16 v[66:69], v[182:185], v[214:217], v[66:69]
	v_mfma_f32_16x16x32_bf16 v[122:125], v[178:181], v[194:197], v[122:125]
	v_mfma_f32_16x16x32_bf16 v[114:117], v[186:189], v[194:197], v[114:117]
	v_mfma_f32_16x16x32_bf16 v[106:109], v[178:181], v[202:205], v[106:109]
	v_mfma_f32_16x16x32_bf16 v[98:101], v[186:189], v[202:205], v[98:101]
	v_mfma_f32_16x16x32_bf16 v[90:93], v[178:181], v[210:213], v[90:93]
	v_mfma_f32_16x16x32_bf16 v[82:85], v[186:189], v[210:213], v[82:85]
	v_mfma_f32_16x16x32_bf16 v[74:77], v[178:181], v[218:221], v[74:77]
	v_mfma_f32_16x16x32_bf16 v[66:69], v[186:189], v[218:221], v[66:69]
	s_barrier
	s_setprio 0
	s_add_i32 s4, s4, s37
	v_lshl_add_u64 v[222:223], v[222:223], 0, s[72:73]
	s_mov_b32 m0, s4
	ds_read_b128 v[190:193], v155 offset:49152
	ds_read_b128 v[194:197], v155 offset:50176
	ds_read_b128 v[198:201], v155 offset:51200
	ds_read_b128 v[202:205], v155 offset:52224
	ds_read_b128 v[206:209], v155 offset:53248
	ds_read_b128 v[210:213], v155 offset:54272
	ds_read_b128 v[214:217], v155 offset:55296
	ds_read_b128 v[218:221], v155 offset:56320
	global_load_lds_dwordx4 v[222:223], off
	s_add_i32 m0, s4, 0x2000
	s_add_u32 s10, s10, 0x40080
	v_lshl_add_u64 v[222:223], v[224:225], 0, s[72:73]
	s_addc_u32 s11, s11, 0
	s_add_i32 s4, s68, s37
	global_load_lds_dwordx4 v[222:223], off
	v_lshl_add_u64 v[222:223], s[10:11], 0, v[140:141]
	s_mov_b32 m0, s4
	s_nop 0
	global_load_lds_dwordx4 v[222:223], off
	v_lshl_add_u64 v[222:223], s[10:11], 0, v[144:145]
	s_add_i32 m0, s4, 0x2000
	s_nop 0
	global_load_lds_dwordx4 v[222:223], off
	v_lshl_add_u64 v[222:223], v[226:227], 0, s[72:73]
	s_mov_b32 m0, s44
	s_nop 0
	global_load_lds_dwordx4 v[222:223], off
	v_lshl_add_u64 v[222:223], v[228:229], 0, s[72:73]
	s_mov_b32 m0, s45
	s_nop 0
	global_load_lds_dwordx4 v[222:223], off
	s_waitcnt vmcnt(8)
	s_waitcnt lgkmcnt(0)
	s_setprio 1
	s_barrier
; #define PG8_STAGE(bufoff, gbase, voff) do { _Pragma("unroll") for (int _i = 0; _i < 2; ++_i) \
;         __builtin_amdgcn_global_load_lds((const unsigned*)((const char*)(gbase) + (voff)[_i]), (PG8_LAS unsigned*)(lds + (bufoff) + ldsw + _i * 8192), 16, 0, 0); } while (0)
; #define PG8_LDA(dst, b, h) do { _Pragma("unroll") for (int m = 0; m < 4; ++m) _Pragma("unroll") for (int k = 0; k < 2; ++k) dst[m][k] = *(const PG8_LAS bf16x8*)(lds + PG8_SA(b, h) + aoff + m * 2048 + k * 1024); } while (0)
; #define PG8_LDB(dst, b, h) do { _Pragma("unroll") for (int n = 0; n < 2; ++n) _Pragma("unroll") for (int k = 0; k < 2; ++k) dst[n][k] = *(const PG8_LAS bf16x8*)(lds + PG8_SB(b, h) + boff + n * 2048 + k * 1024); } while (0)
; #define PG8_MMA(ai, bj, At, Bt) do { __builtin_amdgcn_s_setprio(1); _Pragma("unroll") for (int m = 0; m < 4; ++m) _Pragma("unroll") for (int n = 0; n < 2; ++n) _Pragma("unroll") for (int k = 0; k < 2; ++k) \
;         acc[ai][bj][m][n] = __builtin_amdgcn_mfma_f32_16x16x32_bf16(Bt[n][k], At[m][k], acc[ai][bj][m][n], 0, 0, 0); __builtin_amdgcn_s_setprio(0); } while (0)
; template <class Epi, class Sched, bool ALIGN_EPI = false, bool SP2 = false>
; __device__ __forceinline__ void gemm_phase(PG8_LAS unsigned char* lds, const Gemm g, const Sched& S, const Epi& E) {
;     ...
;         for (int t = 0; t < nt; t += 2) {
;             const bool last = (t == nt - 2);
;             const char* a1 = cA + (size_t)(t + 1) * kstepA;
;             const char* a2 = last ? nA : cA + (size_t)(t + 2) * kstepA; const char* b2 = last ? nB : cB + (size_t)(t + 2) * kstep;
;             const char* a3 = a2 + kstepA; const char* b3 = b2 + kstep;
;             if (last && has_next) S.a_ready(nxt);
;             if constexpr (SP2) {
;             PG8_LDB(B0, 0, 0); PG8_LDB(B1, 0, 1); PG8_SCHED; PG8_LDA(At, 0, 0); PG8_STAGE(PG8_SA(1, 1), a1 + hstepA, voffA);
;             PG8_WAIT_V(8); PG8_WAIT_L(0); PG8_BAR; PG8_MMA(0, 0, At, B0); PG8_MMA(0, 1, At, B1); PG8_BAR; PG8_SCHED;
;             PG8_LDA(At, 0, 1); PG8_STAGE(PG8_SB(0, 0), b2, voffB); PG8_STAGE(PG8_SB(0, 1), b2 + hstepB, voffB); PG8_STAGE(PG8_SA(0, 0), a2, voffA);
;             PG8_WAIT_V(8); PG8_WAIT_L(0); PG8_BAR; PG8_MMA(1, 0, At, B0); PG8_MMA(1, 1, At, B1); PG8_BAR; PG8_SCHED;
;     ...
;             PG8_WAIT_V(8); PG8_WAIT_L(0); PG8_BAR; PG8_MMA(1, 0, At, B0); PG8_MMA(1, 1, At, B1); PG8_BAR; PG8_SCHED;
	v_mfma_f32_16x16x32_bf16 v[62:65], v[130:133], v[190:193], v[62:65]
	v_mfma_f32_16x16x32_bf16 v[54:57], v[166:169], v[190:193], v[54:57]
	v_mfma_f32_16x16x32_bf16 v[46:49], v[130:133], v[198:201], v[46:49]
	v_mfma_f32_16x16x32_bf16 v[38:41], v[166:169], v[198:201], v[38:41]
	v_mfma_f32_16x16x32_bf16 v[30:33], v[130:133], v[206:209], v[30:33]
	v_mfma_f32_16x16x32_bf16 v[22:25], v[166:169], v[206:209], v[22:25]
	v_mfma_f32_16x16x32_bf16 v[14:17], v[130:133], v[214:217], v[14:17]
	v_mfma_f32_16x16x32_bf16 v[6:9], v[166:169], v[214:217], v[6:9]
	v_mfma_f32_16x16x32_bf16 v[62:65], v[134:137], v[194:197], v[62:65]
	v_mfma_f32_16x16x32_bf16 v[54:57], v[170:173], v[194:197], v[54:57]
	v_mfma_f32_16x16x32_bf16 v[46:49], v[134:137], v[202:205], v[46:49]
	v_mfma_f32_16x16x32_bf16 v[38:41], v[170:173], v[202:205], v[38:41]
	v_mfma_f32_16x16x32_bf16 v[30:33], v[134:137], v[210:213], v[30:33]
	v_mfma_f32_16x16x32_bf16 v[22:25], v[170:173], v[210:213], v[22:25]
	v_mfma_f32_16x16x32_bf16 v[14:17], v[134:137], v[218:221], v[14:17]
	v_mfma_f32_16x16x32_bf16 v[6:9], v[170:173], v[218:221], v[6:9]
	v_mfma_f32_16x16x32_bf16 v[58:61], v[174:177], v[190:193], v[58:61]
	v_mfma_f32_16x16x32_bf16 v[50:53], v[182:185], v[190:193], v[50:53]
	v_mfma_f32_16x16x32_bf16 v[42:45], v[174:177], v[198:201], v[42:45]
	v_mfma_f32_16x16x32_bf16 v[34:37], v[182:185], v[198:201], v[34:37]
	v_mfma_f32_16x16x32_bf16 v[26:29], v[174:177], v[206:209], v[26:29]
	v_mfma_f32_16x16x32_bf16 v[18:21], v[182:185], v[206:209], v[18:21]
	v_mfma_f32_16x16x32_bf16 v[10:13], v[174:177], v[214:217], v[10:13]
	v_mfma_f32_16x16x32_bf16 v[2:5], v[182:185], v[214:217], v[2:5]
	v_mfma_f32_16x16x32_bf16 v[58:61], v[178:181], v[194:197], v[58:61]
	v_mfma_f32_16x16x32_bf16 v[50:53], v[186:189], v[194:197], v[50:53]
	v_mfma_f32_16x16x32_bf16 v[42:45], v[178:181], v[202:205], v[42:45]
	v_mfma_f32_16x16x32_bf16 v[34:37], v[186:189], v[202:205], v[34:37]
	v_mfma_f32_16x16x32_bf16 v[26:29], v[178:181], v[210:213], v[26:29]
	v_mfma_f32_16x16x32_bf16 v[18:21], v[186:189], v[210:213], v[18:21]
	v_mfma_f32_16x16x32_bf16 v[10:13], v[178:181], v[218:221], v[10:13]
	v_mfma_f32_16x16x32_bf16 v[2:5], v[186:189], v[218:221], v[2:5]
	s_barrier
	s_setprio 0
	s_add_i32 s67, s67, 2
	s_add_u32 s8, s8, 0x100
	s_addc_u32 s9, s9, 0
	s_add_u32 s46, s46, 0x100
	s_addc_u32 s66, s66, 0
	s_cmp_gt_u32 s67, 13
	s_cbranch_scc0 .LBB0_691
	s_branch .Lph691_x
.Lph691_y:
	ds_read_b128 v[130:133], v151
	ds_read_b128 v[134:137], v151 offset:1024
	ds_read_b128 v[166:169], v151 offset:2048
	ds_read_b128 v[170:173], v151 offset:3072
	ds_read_b128 v[174:177], v153
	ds_read_b128 v[178:181], v153 offset:1024
	ds_read_b128 v[182:185], v153 offset:2048
	ds_read_b128 v[186:189], v153 offset:3072
	s_add_u32 s4, s8, 0xfffc0080
	s_addc_u32 s10, s9, -1
	s_cmp_eq_u32 s67, 12
	s_cselect_b32 s87, s3, s10
	s_cselect_b32 s86, s7, s4
	s_cselect_b32 s11, s33, s66
	s_cselect_b32 s10, s35, s46
	v_lshl_add_u64 v[222:223], s[8:9], 0, v[160:161]
	s_add_i32 m0, s38, 0xc000
	ds_read_b128 v[190:193], v155
	ds_read_b128 v[194:197], v155 offset:1024
	ds_read_b128 v[198:201], v155 offset:2048
	ds_read_b128 v[202:205], v155 offset:3072
	ds_read_b128 v[206:209], v155 offset:4096
	ds_read_b128 v[210:213], v155 offset:5120
	ds_read_b128 v[214:217], v155 offset:6144
	ds_read_b128 v[218:221], v155 offset:7168
	global_load_lds_dwordx4 v[222:223], off
	v_lshl_add_u64 v[222:223], s[8:9], 0, v[162:163]
	s_add_i32 m0, s38, 0xe000
	s_nop 0
	global_load_lds_dwordx4 v[222:223], off
	s_waitcnt vmcnt(8)
	s_waitcnt lgkmcnt(0)
	s_setprio 2
	s_barrier
	v_mfma_f32_16x16x32_bf16 v[126:129], v[130:133], v[190:193], v[126:129]
	v_mfma_f32_16x16x32_bf16 v[118:121], v[166:169], v[190:193], v[118:121]
	v_mfma_f32_16x16x32_bf16 v[110:113], v[130:133], v[198:201], v[110:113]
	v_mfma_f32_16x16x32_bf16 v[102:105], v[166:169], v[198:201], v[102:105]
	v_mfma_f32_16x16x32_bf16 v[94:97], v[130:133], v[206:209], v[94:97]
	v_mfma_f32_16x16x32_bf16 v[86:89], v[166:169], v[206:209], v[86:89]
	v_mfma_f32_16x16x32_bf16 v[78:81], v[130:133], v[214:217], v[78:81]
	v_mfma_f32_16x16x32_bf16 v[70:73], v[166:169], v[214:217], v[70:73]
	v_mfma_f32_16x16x32_bf16 v[126:129], v[134:137], v[194:197], v[126:129]
	v_mfma_f32_16x16x32_bf16 v[118:121], v[170:173], v[194:197], v[118:121]
	v_mfma_f32_16x16x32_bf16 v[110:113], v[134:137], v[202:205], v[110:113]
	v_mfma_f32_16x16x32_bf16 v[102:105], v[170:173], v[202:205], v[102:105]
	v_mfma_f32_16x16x32_bf16 v[94:97], v[134:137], v[210:213], v[94:97]
	v_mfma_f32_16x16x32_bf16 v[86:89], v[170:173], v[210:213], v[86:89]
	v_mfma_f32_16x16x32_bf16 v[78:81], v[134:137], v[218:221], v[78:81]
	v_mfma_f32_16x16x32_bf16 v[70:73], v[170:173], v[218:221], v[70:73]
	v_mfma_f32_16x16x32_bf16 v[122:125], v[174:177], v[190:193], v[122:125]
	v_mfma_f32_16x16x32_bf16 v[114:117], v[182:185], v[190:193], v[114:117]
	v_mfma_f32_16x16x32_bf16 v[106:109], v[174:177], v[198:201], v[106:109]
	v_mfma_f32_16x16x32_bf16 v[98:101], v[182:185], v[198:201], v[98:101]
	v_mfma_f32_16x16x32_bf16 v[90:93], v[174:177], v[206:209], v[90:93]
	v_mfma_f32_16x16x32_bf16 v[82:85], v[182:185], v[206:209], v[82:85]
	v_mfma_f32_16x16x32_bf16 v[74:77], v[174:177], v[214:217], v[74:77]
	v_mfma_f32_16x16x32_bf16 v[66:69], v[182:185], v[214:217], v[66:69]
	v_mfma_f32_16x16x32_bf16 v[122:125], v[178:181], v[194:197], v[122:125]
	v_mfma_f32_16x16x32_bf16 v[114:117], v[186:189], v[194:197], v[114:117]
	v_mfma_f32_16x16x32_bf16 v[106:109], v[178:181], v[202:205], v[106:109]
	v_mfma_f32_16x16x32_bf16 v[98:101], v[186:189], v[202:205], v[98:101]
	v_mfma_f32_16x16x32_bf16 v[90:93], v[178:181], v[210:213], v[90:93]
	v_mfma_f32_16x16x32_bf16 v[82:85], v[186:189], v[210:213], v[82:85]
	v_mfma_f32_16x16x32_bf16 v[74:77], v[178:181], v[218:221], v[74:77]
	v_mfma_f32_16x16x32_bf16 v[66:69], v[186:189], v[218:221], v[66:69]
	s_barrier
; #define PG8_STAGE(bufoff, gbase, voff) do { _Pragma("unroll") for (int _i = 0; _i < 2; ++_i) \
;         __builtin_amdgcn_global_load_lds((const unsigned*)((const char*)(gbase) + (voff)[_i]), (PG8_LAS unsigned*)(lds + (bufoff) + ldsw + _i * 8192), 16, 0, 0); } while (0)
; #define PG8_LDA(dst, b, h) do { _Pragma("unroll") for (int m = 0; m < 4; ++m) _Pragma("unroll") for (int k = 0; k < 2; ++k) dst[m][k] = *(const PG8_LAS bf16x8*)(lds + PG8_SA(b, h) + aoff + m * 2048 + k * 1024); } while (0)
; #define PG8_LDB(dst, b, h) do { _Pragma("unroll") for (int n = 0; n < 2; ++n) _Pragma("unroll") for (int k = 0; k < 2; ++k) dst[n][k] = *(const PG8_LAS bf16x8*)(lds + PG8_SB(b, h) + boff + n * 2048 + k * 1024); } while (0)
; #define PG8_MMA(ai, bj, At, Bt) do { __builtin_amdgcn_s_setprio(1); _Pragma("unroll") for (int m = 0; m < 4; ++m) _Pragma("unroll") for (int n = 0; n < 2; ++n) _Pragma("unroll") for (int k = 0; k < 2; ++k) \
;         acc[ai][bj][m][n] = __builtin_amdgcn_mfma_f32_16x16x32_bf16(Bt[n][k], At[m][k], acc[ai][bj][m][n], 0, 0, 0); __builtin_amdgcn_s_setprio(0); } while (0)
; #define PG8_WAIT_V(n) asm volatile("s_waitcnt vmcnt(" #n ")" ::: "memory")
; #define PG8_WAIT_L(n) asm volatile("s_waitcnt lgkmcnt(" #n ")" ::: "memory")
; template <class Epi, class Sched, bool ALIGN_EPI = false, bool SP2 = false>
; __device__ __forceinline__ void gemm_phase(PG8_LAS unsigned char* lds, const Gemm g, const Sched& S, const Epi& E) {
;     ...
;             PG8_LDB(B0, 0, 0); PG8_LDB(B1, 0, 1); PG8_SCHED; PG8_LDA(At, 0, 0); PG8_STAGE(PG8_SA(1, 1), a1 + hstepA, voffA);
;             PG8_WAIT_V(8); PG8_WAIT_L(0); PG8_BAR; PG8_MMA(0, 0, At, B0); PG8_MMA(0, 1, At, B1); PG8_BAR; PG8_SCHED;
;             PG8_LDA(At, 0, 1); PG8_STAGE(PG8_SB(0, 0), b2, voffB); PG8_STAGE(PG8_SB(0, 1), b2 + hstepB, voffB); PG8_STAGE(PG8_SA(0, 0), a2, voffA);
;             PG8_WAIT_V(8); PG8_WAIT_L(0); PG8_BAR; PG8_MMA(1, 0, At, B0); PG8_MMA(1, 1, At, B1); PG8_BAR; PG8_SCHED;
;             PG8_LDB(B0, 1, 0); PG8_LDB(B1, 1, 1); PG8_SCHED; PG8_LDA(At, 1, 0); PG8_STAGE(PG8_SA(0, 1), a2 + hstepA, voffA);
;             PG8_WAIT_V(8); PG8_WAIT_L(0); PG8_BAR; PG8_MMA(0, 0, At, B0); PG8_MMA(0, 1, At, B1); PG8_BAR; PG8_SCHED;
;             PG8_LDA(At, 1, 1); PG8_STAGE(PG8_SB(1, 0), b3, voffB); PG8_STAGE(PG8_SB(1, 1), b3 + hstepB, voffB); PG8_STAGE(PG8_SA(1, 0), a3, voffA);
	s_setprio 1
	s_add_i32 s4, s47, s37
	v_lshl_add_u64 v[222:223], s[10:11], 0, v[140:141]
	s_mov_b32 m0, s4
	ds_read_b128 v[190:193], v155 offset:16384
	ds_read_b128 v[194:197], v155 offset:17408
	ds_read_b128 v[198:201], v155 offset:18432
	ds_read_b128 v[202:205], v155 offset:19456
	ds_read_b128 v[206:209], v155 offset:20480
	ds_read_b128 v[210:213], v155 offset:21504
	ds_read_b128 v[214:217], v155 offset:22528
	ds_read_b128 v[218:221], v155 offset:23552
	global_load_lds_dwordx4 v[222:223], off
	s_add_i32 m0, s4, 0x2000
	s_add_u32 s88, s10, 0x40000
	v_lshl_add_u64 v[224:225], s[10:11], 0, v[144:145]
	s_addc_u32 s89, s11, 0
	s_add_i32 s4, s48, s37
	global_load_lds_dwordx4 v[224:225], off
	v_lshl_add_u64 v[226:227], s[88:89], 0, v[140:141]
	s_mov_b32 m0, s4
	v_lshl_add_u64 v[228:229], s[86:87], 0, v[142:143]
	global_load_lds_dwordx4 v[226:227], off
	v_lshl_add_u64 v[226:227], s[88:89], 0, v[144:145]
	s_add_i32 m0, s4, 0x2000
	s_nop 0
	global_load_lds_dwordx4 v[226:227], off
	v_lshl_add_u64 v[226:227], s[86:87], 0, v[138:139]
	s_mov_b32 m0, s38
	s_nop 0
	global_load_lds_dwordx4 v[226:227], off
	s_mov_b32 m0, s39
	s_nop 0
	global_load_lds_dwordx4 v[228:229], off
	s_waitcnt vmcnt(8)
	s_waitcnt lgkmcnt(0)
	s_setprio 2
	s_barrier
	v_mfma_f32_16x16x32_bf16 v[62:65], v[130:133], v[190:193], v[62:65]
	v_mfma_f32_16x16x32_bf16 v[54:57], v[166:169], v[190:193], v[54:57]
	v_mfma_f32_16x16x32_bf16 v[46:49], v[130:133], v[198:201], v[46:49]
	v_mfma_f32_16x16x32_bf16 v[38:41], v[166:169], v[198:201], v[38:41]
	v_mfma_f32_16x16x32_bf16 v[30:33], v[130:133], v[206:209], v[30:33]
	v_mfma_f32_16x16x32_bf16 v[22:25], v[166:169], v[206:209], v[22:25]
	v_mfma_f32_16x16x32_bf16 v[14:17], v[130:133], v[214:217], v[14:17]
	v_mfma_f32_16x16x32_bf16 v[6:9], v[166:169], v[214:217], v[6:9]
	v_mfma_f32_16x16x32_bf16 v[62:65], v[134:137], v[194:197], v[62:65]
	v_mfma_f32_16x16x32_bf16 v[54:57], v[170:173], v[194:197], v[54:57]
	v_mfma_f32_16x16x32_bf16 v[46:49], v[134:137], v[202:205], v[46:49]
	v_mfma_f32_16x16x32_bf16 v[38:41], v[170:173], v[202:205], v[38:41]
	v_mfma_f32_16x16x32_bf16 v[30:33], v[134:137], v[210:213], v[30:33]
	v_mfma_f32_16x16x32_bf16 v[22:25], v[170:173], v[210:213], v[22:25]
	v_mfma_f32_16x16x32_bf16 v[14:17], v[134:137], v[218:221], v[14:17]
	v_mfma_f32_16x16x32_bf16 v[6:9], v[170:173], v[218:221], v[6:9]
	v_mfma_f32_16x16x32_bf16 v[58:61], v[174:177], v[190:193], v[58:61]
	v_mfma_f32_16x16x32_bf16 v[50:53], v[182:185], v[190:193], v[50:53]
	v_mfma_f32_16x16x32_bf16 v[42:45], v[174:177], v[198:201], v[42:45]
	v_mfma_f32_16x16x32_bf16 v[34:37], v[182:185], v[198:201], v[34:37]
	v_mfma_f32_16x16x32_bf16 v[26:29], v[174:177], v[206:209], v[26:29]
	v_mfma_f32_16x16x32_bf16 v[18:21], v[182:185], v[206:209], v[18:21]
	v_mfma_f32_16x16x32_bf16 v[10:13], v[174:177], v[214:217], v[10:13]
	v_mfma_f32_16x16x32_bf16 v[2:5], v[182:185], v[214:217], v[2:5]
	v_mfma_f32_16x16x32_bf16 v[58:61], v[178:181], v[194:197], v[58:61]
	v_mfma_f32_16x16x32_bf16 v[50:53], v[186:189], v[194:197], v[50:53]
	v_mfma_f32_16x16x32_bf16 v[42:45], v[178:181], v[202:205], v[42:45]
	v_mfma_f32_16x16x32_bf16 v[34:37], v[186:189], v[202:205], v[34:37]
	v_mfma_f32_16x16x32_bf16 v[26:29], v[178:181], v[210:213], v[26:29]
	v_mfma_f32_16x16x32_bf16 v[18:21], v[186:189], v[210:213], v[18:21]
	v_mfma_f32_16x16x32_bf16 v[10:13], v[178:181], v[218:221], v[10:13]
	v_mfma_f32_16x16x32_bf16 v[2:5], v[186:189], v[218:221], v[2:5]
	s_barrier
	s_setprio 1
	s_add_i32 s4, 0, 0x18000
	v_add_u32_e32 v146, s4, v149
	s_add_i32 s68, 0, 0x1c000
	ds_read_b128 v[130:133], v146
	ds_read_b128 v[134:137], v146 offset:1024
	ds_read_b128 v[166:169], v146 offset:2048
	ds_read_b128 v[170:173], v146 offset:3072
	v_add_u32_e32 v146, s68, v149
	ds_read_b128 v[174:177], v146
	ds_read_b128 v[178:181], v146 offset:1024
	ds_read_b128 v[182:185], v146 offset:2048
	ds_read_b128 v[186:189], v146 offset:3072
	s_add_u32 s86, s86, 0x40000
	s_addc_u32 s87, s87, 0
	s_mov_b32 m0, s40
	v_lshl_add_u64 v[230:231], s[86:87], 0, v[138:139]
	ds_read_b128 v[190:193], v155 offset:32768
	ds_read_b128 v[194:197], v155 offset:33792
	ds_read_b128 v[198:201], v155 offset:34816
	ds_read_b128 v[202:205], v155 offset:35840
	ds_read_b128 v[206:209], v155 offset:36864
	ds_read_b128 v[210:213], v155 offset:37888
	ds_read_b128 v[214:217], v155 offset:38912
	ds_read_b128 v[218:221], v155 offset:39936
	global_load_lds_dwordx4 v[230:231], off
	v_lshl_add_u64 v[230:231], s[86:87], 0, v[142:143]
	s_mov_b32 m0, s41
	s_nop 0
	global_load_lds_dwordx4 v[230:231], off
	s_waitcnt vmcnt(8)
	s_waitcnt lgkmcnt(0)
	s_setprio 2
	s_barrier
; #define PG8_STAGE(bufoff, gbase, voff) do { _Pragma("unroll") for (int _i = 0; _i < 2; ++_i) \
;         __builtin_amdgcn_global_load_lds((const unsigned*)((const char*)(gbase) + (voff)[_i]), (PG8_LAS unsigned*)(lds + (bufoff) + ldsw + _i * 8192), 16, 0, 0); } while (0)
; #define PG8_LDA(dst, b, h) do { _Pragma("unroll") for (int m = 0; m < 4; ++m) _Pragma("unroll") for (int k = 0; k < 2; ++k) dst[m][k] = *(const PG8_LAS bf16x8*)(lds + PG8_SA(b, h) + aoff + m * 2048 + k * 1024); } while (0)
; #define PG8_MMA(ai, bj, At, Bt) do { __builtin_amdgcn_s_setprio(1); _Pragma("unroll") for (int m = 0; m < 4; ++m) _Pragma("unroll") for (int n = 0; n < 2; ++n) _Pragma("unroll") for (int k = 0; k < 2; ++k) \
;         acc[ai][bj][m][n] = __builtin_amdgcn_mfma_f32_16x16x32_bf16(Bt[n][k], At[m][k], acc[ai][bj][m][n], 0, 0, 0); __builtin_amdgcn_s_setprio(0); } while (0)
; #define PG8_WAIT_V(n) asm volatile("s_waitcnt vmcnt(" #n ")" ::: "memory")
; #define PG8_WAIT_L(n) asm volatile("s_waitcnt lgkmcnt(" #n ")" ::: "memory")
; #define PG8_BAR __builtin_amdgcn_s_barrier()
; #define PG8_SCHED __builtin_amdgcn_sched_barrier(0)
; template <class Epi, class Sched, bool ALIGN_EPI = false, bool SP2 = false>
; __device__ __forceinline__ void gemm_phase(PG8_LAS unsigned char* lds, const Gemm g, const Sched& S, const Epi& E) {
;     ...
;             PG8_WAIT_V(8); PG8_WAIT_L(0); PG8_BAR; PG8_MMA(0, 0, At, B0); PG8_MMA(0, 1, At, B1); PG8_BAR; PG8_SCHED;
;             PG8_LDA(At, 1, 1); PG8_STAGE(PG8_SB(1, 0), b3, voffB); PG8_STAGE(PG8_SB(1, 1), b3 + hstepB, voffB); PG8_STAGE(PG8_SA(1, 0), a3, voffA);
;             PG8_WAIT_V(8); PG8_WAIT_L(0); PG8_BAR; PG8_MMA(1, 0, At, B0); PG8_MMA(1, 1, At, B1); PG8_BAR; PG8_SCHED;
;     ...
;         if constexpr (ALIGN_EPI) { if (wr == 0) PG8_BAR; }
	v_mfma_f32_16x16x32_bf16 v[126:129], v[130:133], v[190:193], v[126:129]
	v_mfma_f32_16x16x32_bf16 v[118:121], v[166:169], v[190:193], v[118:121]
	v_mfma_f32_16x16x32_bf16 v[110:113], v[130:133], v[198:201], v[110:113]
	v_mfma_f32_16x16x32_bf16 v[102:105], v[166:169], v[198:201], v[102:105]
	v_mfma_f32_16x16x32_bf16 v[94:97], v[130:133], v[206:209], v[94:97]
	v_mfma_f32_16x16x32_bf16 v[86:89], v[166:169], v[206:209], v[86:89]
	v_mfma_f32_16x16x32_bf16 v[78:81], v[130:133], v[214:217], v[78:81]
	v_mfma_f32_16x16x32_bf16 v[70:73], v[166:169], v[214:217], v[70:73]
	v_mfma_f32_16x16x32_bf16 v[126:129], v[134:137], v[194:197], v[126:129]
	v_mfma_f32_16x16x32_bf16 v[118:121], v[170:173], v[194:197], v[118:121]
	v_mfma_f32_16x16x32_bf16 v[110:113], v[134:137], v[202:205], v[110:113]
	v_mfma_f32_16x16x32_bf16 v[102:105], v[170:173], v[202:205], v[102:105]
	v_mfma_f32_16x16x32_bf16 v[94:97], v[134:137], v[210:213], v[94:97]
	v_mfma_f32_16x16x32_bf16 v[86:89], v[170:173], v[210:213], v[86:89]
	v_mfma_f32_16x16x32_bf16 v[78:81], v[134:137], v[218:221], v[78:81]
	v_mfma_f32_16x16x32_bf16 v[70:73], v[170:173], v[218:221], v[70:73]
	v_mfma_f32_16x16x32_bf16 v[122:125], v[174:177], v[190:193], v[122:125]
	v_mfma_f32_16x16x32_bf16 v[114:117], v[182:185], v[190:193], v[114:117]
	v_mfma_f32_16x16x32_bf16 v[106:109], v[174:177], v[198:201], v[106:109]
	v_mfma_f32_16x16x32_bf16 v[98:101], v[182:185], v[198:201], v[98:101]
	v_mfma_f32_16x16x32_bf16 v[90:93], v[174:177], v[206:209], v[90:93]
	v_mfma_f32_16x16x32_bf16 v[82:85], v[182:185], v[206:209], v[82:85]
	v_mfma_f32_16x16x32_bf16 v[74:77], v[174:177], v[214:217], v[74:77]
	v_mfma_f32_16x16x32_bf16 v[66:69], v[182:185], v[214:217], v[66:69]
	v_mfma_f32_16x16x32_bf16 v[122:125], v[178:181], v[194:197], v[122:125]
	v_mfma_f32_16x16x32_bf16 v[114:117], v[186:189], v[194:197], v[114:117]
	v_mfma_f32_16x16x32_bf16 v[106:109], v[178:181], v[202:205], v[106:109]
	v_mfma_f32_16x16x32_bf16 v[98:101], v[186:189], v[202:205], v[98:101]
	v_mfma_f32_16x16x32_bf16 v[90:93], v[178:181], v[210:213], v[90:93]
	v_mfma_f32_16x16x32_bf16 v[82:85], v[186:189], v[210:213], v[82:85]
	v_mfma_f32_16x16x32_bf16 v[74:77], v[178:181], v[218:221], v[74:77]
	v_mfma_f32_16x16x32_bf16 v[66:69], v[186:189], v[218:221], v[66:69]
	s_barrier
	s_setprio 1
	s_add_i32 s4, s4, s37
	v_lshl_add_u64 v[222:223], v[222:223], 0, s[72:73]
	s_mov_b32 m0, s4
	ds_read_b128 v[190:193], v155 offset:49152
	ds_read_b128 v[194:197], v155 offset:50176
	ds_read_b128 v[198:201], v155 offset:51200
	ds_read_b128 v[202:205], v155 offset:52224
	ds_read_b128 v[206:209], v155 offset:53248
	ds_read_b128 v[210:213], v155 offset:54272
	ds_read_b128 v[214:217], v155 offset:55296
	ds_read_b128 v[218:221], v155 offset:56320
	global_load_lds_dwordx4 v[222:223], off
	s_add_i32 m0, s4, 0x2000
	s_add_u32 s10, s10, 0x40080
	v_lshl_add_u64 v[222:223], v[224:225], 0, s[72:73]
	s_addc_u32 s11, s11, 0
	s_add_i32 s4, s68, s37
	global_load_lds_dwordx4 v[222:223], off
	v_lshl_add_u64 v[222:223], s[10:11], 0, v[140:141]
	s_mov_b32 m0, s4
	s_nop 0
	global_load_lds_dwordx4 v[222:223], off
	v_lshl_add_u64 v[222:223], s[10:11], 0, v[144:145]
	s_add_i32 m0, s4, 0x2000
	s_nop 0
	global_load_lds_dwordx4 v[222:223], off
	v_lshl_add_u64 v[222:223], v[226:227], 0, s[72:73]
	s_mov_b32 m0, s44
	s_nop 0
	global_load_lds_dwordx4 v[222:223], off
	v_lshl_add_u64 v[222:223], v[228:229], 0, s[72:73]
	s_mov_b32 m0, s45
	s_nop 0
	global_load_lds_dwordx4 v[222:223], off
	s_waitcnt vmcnt(8)
	s_waitcnt lgkmcnt(0)
	s_setprio 2
	s_barrier
	v_mfma_f32_16x16x32_bf16 v[62:65], v[130:133], v[190:193], v[62:65]
	v_mfma_f32_16x16x32_bf16 v[54:57], v[166:169], v[190:193], v[54:57]
	v_mfma_f32_16x16x32_bf16 v[46:49], v[130:133], v[198:201], v[46:49]
	v_mfma_f32_16x16x32_bf16 v[38:41], v[166:169], v[198:201], v[38:41]
	v_mfma_f32_16x16x32_bf16 v[30:33], v[130:133], v[206:209], v[30:33]
	v_mfma_f32_16x16x32_bf16 v[22:25], v[166:169], v[206:209], v[22:25]
	v_mfma_f32_16x16x32_bf16 v[14:17], v[130:133], v[214:217], v[14:17]
	v_mfma_f32_16x16x32_bf16 v[6:9], v[166:169], v[214:217], v[6:9]
	v_mfma_f32_16x16x32_bf16 v[62:65], v[134:137], v[194:197], v[62:65]
	v_mfma_f32_16x16x32_bf16 v[54:57], v[170:173], v[194:197], v[54:57]
	v_mfma_f32_16x16x32_bf16 v[46:49], v[134:137], v[202:205], v[46:49]
	v_mfma_f32_16x16x32_bf16 v[38:41], v[170:173], v[202:205], v[38:41]
	v_mfma_f32_16x16x32_bf16 v[30:33], v[134:137], v[210:213], v[30:33]
	v_mfma_f32_16x16x32_bf16 v[22:25], v[170:173], v[210:213], v[22:25]
	v_mfma_f32_16x16x32_bf16 v[14:17], v[134:137], v[218:221], v[14:17]
	v_mfma_f32_16x16x32_bf16 v[6:9], v[170:173], v[218:221], v[6:9]
	v_mfma_f32_16x16x32_bf16 v[58:61], v[174:177], v[190:193], v[58:61]
	v_mfma_f32_16x16x32_bf16 v[50:53], v[182:185], v[190:193], v[50:53]
	v_mfma_f32_16x16x32_bf16 v[42:45], v[174:177], v[198:201], v[42:45]
	v_mfma_f32_16x16x32_bf16 v[34:37], v[182:185], v[198:201], v[34:37]
	v_mfma_f32_16x16x32_bf16 v[26:29], v[174:177], v[206:209], v[26:29]
	v_mfma_f32_16x16x32_bf16 v[18:21], v[182:185], v[206:209], v[18:21]
	v_mfma_f32_16x16x32_bf16 v[10:13], v[174:177], v[214:217], v[10:13]
	v_mfma_f32_16x16x32_bf16 v[2:5], v[182:185], v[214:217], v[2:5]
	v_mfma_f32_16x16x32_bf16 v[58:61], v[178:181], v[194:197], v[58:61]
	v_mfma_f32_16x16x32_bf16 v[50:53], v[186:189], v[194:197], v[50:53]
	v_mfma_f32_16x16x32_bf16 v[42:45], v[178:181], v[202:205], v[42:45]
	v_mfma_f32_16x16x32_bf16 v[34:37], v[186:189], v[202:205], v[34:37]
	v_mfma_f32_16x16x32_bf16 v[26:29], v[178:181], v[210:213], v[26:29]
	v_mfma_f32_16x16x32_bf16 v[18:21], v[186:189], v[210:213], v[18:21]
	v_mfma_f32_16x16x32_bf16 v[10:13], v[178:181], v[218:221], v[10:13]
	v_mfma_f32_16x16x32_bf16 v[2:5], v[186:189], v[218:221], v[2:5]
	s_barrier
	s_setprio 1
	s_add_i32 s67, s67, 2
	s_add_u32 s8, s8, 0x100
	s_addc_u32 s9, s9, 0
	s_add_u32 s46, s46, 0x100
	s_addc_u32 s66, s66, 0
	s_cmp_gt_u32 s67, 13
	s_cbranch_scc0 .Lph691_y
	s_setprio 0
.Lph691_x:
	s_and_b64 vcc, exec, s[74:75]
	s_cbranch_vccz .LBB0_694
	s_barrier

;     __host__ __device__ bool next(int i, Unit& u) const { if (!so.next(i >> 1, u)) return false; u.k0 = (i & 1) * 512; return true; }
;     __host__ __device__ bool next(int i, Unit& u) const { if (!so.next(i, u)) return false; u.pe = main_tile(u.pn); return true; }
;     __host__ __device__ bool next(int i, Unit& u) const { if (start + i * stride >= limit) return false; if (!so.next(i, u)) return false; u.pe = late_tile(u.pn); return true; }
; #define PG8_STAGE(bufoff, gbase, voff) do { _Pragma("unroll") for (int _i = 0; _i < 2; ++_i) \
;         __builtin_amdgcn_global_load_lds((const unsigned*)((const char*)(gbase) + (voff)[_i]), (PG8_LAS unsigned*)(lds + (bufoff) + ldsw + _i * 8192), 16, 0, 0); } while (0)
; #define PG8_WAIT_V(n) asm volatile("s_waitcnt vmcnt(" #n ")" ::: "memory")
; #define PG8_BAR __builtin_amdgcn_s_barrier()
; template <class Epi, class Sched, bool ALIGN_EPI = false, bool SP2 = false>
; __device__ __forceinline__ void gemm_phase(PG8_LAS unsigned char* lds, const Gemm g, const Sched& S, const Epi& E) {
;     ...
;         const bool has_next = S.next(ui + 1, nxt);
;         const char* nA = has_next ? (const char*)g.A + (size_t)nxt.pm * tstepA + (size_t)nxt.k0 * 2 : cA; const char* nB = has_next ? (const char*)g.Bt + (size_t)nxt.pn * tstepB + (size_t)nxt.k0 * 2 : cB;
;         for (int t = 0; t < nt; t += 2) {
;             const bool last = (t == nt - 2);
;             const char* a1 = cA + (size_t)(t + 1) * kstepA;
;             const char* a2 = last ? nA : cA + (size_t)(t + 2) * kstepA; const char* b2 = last ? nB : cB + (size_t)(t + 2) * kstep;
;             const char* a3 = a2 + kstepA; const char* b3 = b2 + kstep;
;             if (last && has_next) S.a_ready(nxt);
;             if constexpr (SP2) {
;             PG8_LDB(B0, 0, 0); PG8_LDB(B1, 0, 1); PG8_SCHED; PG8_LDA(At, 0, 0); PG8_STAGE(PG8_SA(1, 1), a1 + hstepA, voffA);
;             PG8_WAIT_V(8); PG8_WAIT_L(0); PG8_BAR; PG8_MMA(0, 0, At, B0); PG8_MMA(0, 1, At, B1); PG8_BAR; PG8_SCHED;
;             PG8_LDA(At, 0, 1); PG8_STAGE(PG8_SB(0, 0), b2, voffB); PG8_STAGE(PG8_SB(0, 1), b2 + hstepB, voffB); PG8_STAGE(PG8_SA(0, 0), a2, voffA);
;             PG8_WAIT_V(8); PG8_WAIT_L(0); PG8_BAR; PG8_MMA(1, 0, At, B0); PG8_MMA(1, 1, At, B1); PG8_BAR; PG8_SCHED;
;             PG8_LDB(B0, 1, 0); PG8_LDB(B1, 1, 1); PG8_SCHED; PG8_LDA(At, 1, 0); PG8_STAGE(PG8_SA(0, 1), a2 + hstepA, voffA);
.LBB0_962:
	s_ashr_i32 s39, s38, 31
	s_lshl_b64 s[40:41], s[38:39], 20
	s_add_u32 s31, s10, s40
	s_addc_u32 s39, s11, s41
	s_ashr_i32 s37, s36, 31
	s_lshl_b64 s[46:47], s[36:37], 1
	s_add_u32 s40, s31, s46
	s_addc_u32 s41, s39, s47
	s_and_b64 s[68:69], s[0:1], exec
	s_cselect_b32 s37, s41, s65
	s_cselect_b32 s39, s40, s64
	s_ashr_i32 s31, s30, 31
	s_lshl_b64 s[68:69], s[30:31], 19
	s_add_u32 s31, s22, s68
	s_addc_u32 s49, s23, s69
	s_add_u32 s46, s31, s46
	s_addc_u32 s47, s49, s47
	s_and_b64 s[68:69], s[0:1], exec
	s_cselect_b32 s31, s47, s67
	s_cselect_b32 s49, s46, s66
	s_add_u32 s64, s64, 0x80080
	s_addc_u32 s65, s65, 0
	s_add_u32 s70, s66, 0x100
	s_addc_u32 s71, s67, 0
	s_mov_b32 s72, -2
	s_cmp_lg_u32 s101, 0
	s_cbranch_scc1 .Lph963_y
.LBB0_963:
	v_add_u32_e32 v3, s51, v235
	ds_read_b128 v[78:81], v3
	ds_read_b128 v[82:85], v3 offset:1024
	ds_read_b128 v[102:105], v3 offset:2048
	ds_read_b128 v[106:109], v3 offset:3072
	v_add_u32_e32 v3, s62, v235
	ds_read_b128 v[134:137], v3
	ds_read_b128 v[138:141], v3 offset:1024
	ds_read_b128 v[142:145], v3 offset:2048
	ds_read_b128 v[154:157], v3 offset:3072
	s_add_u32 s66, s64, 0xfff80080
	s_addc_u32 s67, s65, -1
	s_cmp_eq_u32 s72, 4
	s_cselect_b32 s69, s37, s67
	s_cselect_b32 s68, s39, s66
	s_cselect_b32 s67, s31, s71
	s_cselect_b32 s66, s49, s70
	v_lshl_add_u64 v[4:5], s[64:65], 0, v[210:211]
	s_add_i32 m0, s33, 0xc000
	ds_read_b128 v[158:161], v237
	ds_read_b128 v[162:165], v237 offset:1024
	ds_read_b128 v[166:169], v237 offset:2048
	ds_read_b128 v[178:181], v237 offset:3072
	ds_read_b128 v[182:185], v237 offset:4096
	ds_read_b128 v[186:189], v237 offset:5120
	ds_read_b128 v[190:193], v237 offset:6144
	ds_read_b128 v[194:197], v237 offset:7168
	global_load_lds_dwordx4 v[4:5], off
	v_lshl_add_u64 v[4:5], s[64:65], 0, v[212:213]
	s_add_i32 m0, s33, 0xe000
	s_nop 0
	global_load_lds_dwordx4 v[4:5], off
	s_waitcnt vmcnt(8)
	s_waitcnt lgkmcnt(0)
	s_setprio 1
	s_barrier
	v_mfma_f32_16x16x32_bf16 v[90:93], v[78:81], v[158:161], v[90:93]
	v_mfma_f32_16x16x32_bf16 v[86:89], v[102:105], v[158:161], v[86:89]
	v_mfma_f32_16x16x32_bf16 v[122:125], v[78:81], v[166:169], v[122:125]
	v_mfma_f32_16x16x32_bf16 v[118:121], v[102:105], v[166:169], v[118:121]
	v_mfma_f32_16x16x32_bf16 v[130:133], v[78:81], v[182:185], v[130:133]
	v_mfma_f32_16x16x32_bf16 v[126:129], v[102:105], v[182:185], v[126:129]
	v_mfma_f32_16x16x32_bf16 v[98:101], v[78:81], v[190:193], v[98:101]
	v_mfma_f32_16x16x32_bf16 v[94:97], v[102:105], v[190:193], v[94:97]
	v_mfma_f32_16x16x32_bf16 v[90:93], v[82:85], v[162:165], v[90:93]
	v_mfma_f32_16x16x32_bf16 v[86:89], v[106:109], v[162:165], v[86:89]
	v_mfma_f32_16x16x32_bf16 v[122:125], v[82:85], v[178:181], v[122:125]
	v_mfma_f32_16x16x32_bf16 v[118:121], v[106:109], v[178:181], v[118:121]
	v_mfma_f32_16x16x32_bf16 v[130:133], v[82:85], v[186:189], v[130:133]
	v_mfma_f32_16x16x32_bf16 v[126:129], v[106:109], v[186:189], v[126:129]
	v_mfma_f32_16x16x32_bf16 v[98:101], v[82:85], v[194:197], v[98:101]
	v_mfma_f32_16x16x32_bf16 v[94:97], v[106:109], v[194:197], v[94:97]
	v_mfma_f32_16x16x32_bf16 v[174:177], v[134:137], v[158:161], v[174:177]
	v_mfma_f32_16x16x32_bf16 v[150:153], v[134:137], v[166:169], v[150:153]
	v_mfma_f32_16x16x32_bf16 v[146:149], v[142:145], v[166:169], v[146:149]
	v_mfma_f32_16x16x32_bf16 v[114:117], v[134:137], v[182:185], v[114:117]
	v_mfma_f32_16x16x32_bf16 v[110:113], v[142:145], v[182:185], v[110:113]
	v_mfma_f32_16x16x32_bf16 v[74:77], v[134:137], v[190:193], v[74:77]
	v_mfma_f32_16x16x32_bf16 v[70:73], v[142:145], v[190:193], v[70:73]
	v_mfma_f32_16x16x32_bf16 v[174:177], v[138:141], v[162:165], v[174:177]
	v_mfma_f32_16x16x32_bf16 v[158:161], v[142:145], v[158:161], v[170:173]
	v_mfma_f32_16x16x32_bf16 v[150:153], v[138:141], v[178:181], v[150:153]
	v_mfma_f32_16x16x32_bf16 v[146:149], v[154:157], v[178:181], v[146:149]
	v_mfma_f32_16x16x32_bf16 v[114:117], v[138:141], v[186:189], v[114:117]
	v_mfma_f32_16x16x32_bf16 v[110:113], v[154:157], v[186:189], v[110:113]
	v_mfma_f32_16x16x32_bf16 v[74:77], v[138:141], v[194:197], v[74:77]
	v_mfma_f32_16x16x32_bf16 v[70:73], v[154:157], v[194:197], v[70:73]
	v_mfma_f32_16x16x32_bf16 v[158:161], v[154:157], v[162:165], v[158:161]
	s_barrier
	s_setprio 0
	s_add_i32 s73, s51, s5
	v_lshl_add_u64 v[218:219], s[66:67], 0, v[204:205]
	s_mov_b32 m0, s73
	ds_read_b128 v[162:165], v237 offset:16384
	ds_read_b128 v[166:169], v237 offset:17408
	ds_read_b128 v[170:173], v237 offset:18432
	ds_read_b128 v[178:181], v237 offset:19456
	ds_read_b128 v[182:185], v237 offset:20480
	ds_read_b128 v[186:189], v237 offset:21504
	ds_read_b128 v[190:193], v237 offset:22528
	ds_read_b128 v[194:197], v237 offset:23552
	global_load_lds_dwordx4 v[218:219], off
	s_add_i32 m0, s73, 0x2000
	s_add_u32 s74, s66, 0x40000
	v_lshl_add_u64 v[220:221], s[66:67], 0, v[208:209]
	s_addc_u32 s75, s67, 0
	s_add_i32 s73, s62, s5
	global_load_lds_dwordx4 v[220:221], off
	v_lshl_add_u64 v[4:5], s[74:75], 0, v[204:205]
	s_mov_b32 m0, s73
	v_lshl_add_u64 v[222:223], s[68:69], 0, v[202:203]
	global_load_lds_dwordx4 v[4:5], off
	v_lshl_add_u64 v[4:5], s[74:75], 0, v[208:209]
	s_add_i32 m0, s73, 0x2000
	v_lshl_add_u64 v[224:225], s[68:69], 0, v[206:207]
	global_load_lds_dwordx4 v[4:5], off
	s_mov_b32 m0, s33
	s_nop 0
	global_load_lds_dwordx4 v[222:223], off
	s_mov_b32 m0, s35
	s_nop 0
	global_load_lds_dwordx4 v[224:225], off
	s_waitcnt vmcnt(8)
	s_waitcnt lgkmcnt(0)
	s_setprio 1
	s_barrier
; #define PG8_STAGE(bufoff, gbase, voff) do { _Pragma("unroll") for (int _i = 0; _i < 2; ++_i) \
;         __builtin_amdgcn_global_load_lds((const unsigned*)((const char*)(gbase) + (voff)[_i]), (PG8_LAS unsigned*)(lds + (bufoff) + ldsw + _i * 8192), 16, 0, 0); } while (0)
; #define PG8_LDA(dst, b, h) do { _Pragma("unroll") for (int m = 0; m < 4; ++m) _Pragma("unroll") for (int k = 0; k < 2; ++k) dst[m][k] = *(const PG8_LAS bf16x8*)(lds + PG8_SA(b, h) + aoff + m * 2048 + k * 1024); } while (0)
; #define PG8_LDB(dst, b, h) do { _Pragma("unroll") for (int n = 0; n < 2; ++n) _Pragma("unroll") for (int k = 0; k < 2; ++k) dst[n][k] = *(const PG8_LAS bf16x8*)(lds + PG8_SB(b, h) + boff + n * 2048 + k * 1024); } while (0)
; #define PG8_MMA(ai, bj, At, Bt) do { __builtin_amdgcn_s_setprio(1); _Pragma("unroll") for (int m = 0; m < 4; ++m) _Pragma("unroll") for (int n = 0; n < 2; ++n) _Pragma("unroll") for (int k = 0; k < 2; ++k) \
;         acc[ai][bj][m][n] = __builtin_amdgcn_mfma_f32_16x16x32_bf16(Bt[n][k], At[m][k], acc[ai][bj][m][n], 0, 0, 0); __builtin_amdgcn_s_setprio(0); } while (0)
; #define PG8_WAIT_V(n) asm volatile("s_waitcnt vmcnt(" #n ")" ::: "memory")
; #define PG8_WAIT_L(n) asm volatile("s_waitcnt lgkmcnt(" #n ")" ::: "memory")
; #define PG8_BAR __builtin_amdgcn_s_barrier()
; #define PG8_SCHED __builtin_amdgcn_sched_barrier(0)
; template <class Epi, class Sched, bool ALIGN_EPI = false, bool SP2 = false>
; __device__ __forceinline__ void gemm_phase(PG8_LAS unsigned char* lds, const Gemm g, const Sched& S, const Epi& E) {
;     ...
;             PG8_WAIT_V(8); PG8_WAIT_L(0); PG8_BAR; PG8_MMA(1, 0, At, B0); PG8_MMA(1, 1, At, B1); PG8_BAR; PG8_SCHED;
;             PG8_LDB(B0, 1, 0); PG8_LDB(B1, 1, 1); PG8_SCHED; PG8_LDA(At, 1, 0); PG8_STAGE(PG8_SA(0, 1), a2 + hstepA, voffA);
;             PG8_WAIT_V(8); PG8_WAIT_L(0); PG8_BAR; PG8_MMA(0, 0, At, B0); PG8_MMA(0, 1, At, B1); PG8_BAR; PG8_SCHED;
;             PG8_LDA(At, 1, 1); PG8_STAGE(PG8_SB(1, 0), b3, voffB); PG8_STAGE(PG8_SB(1, 1), b3 + hstepB, voffB); PG8_STAGE(PG8_SA(1, 0), a3, voffA);
	v_mfma_f32_16x16x32_bf16 v[66:69], v[78:81], v[162:165], v[66:69]
	v_mfma_f32_16x16x32_bf16 v[62:65], v[102:105], v[162:165], v[62:65]
	v_mfma_f32_16x16x32_bf16 v[50:53], v[78:81], v[170:173], v[50:53]
	v_mfma_f32_16x16x32_bf16 v[46:49], v[102:105], v[170:173], v[46:49]
	v_mfma_f32_16x16x32_bf16 v[34:37], v[78:81], v[182:185], v[34:37]
	v_mfma_f32_16x16x32_bf16 v[30:33], v[102:105], v[182:185], v[30:33]
	v_mfma_f32_16x16x32_bf16 v[18:21], v[78:81], v[190:193], v[18:21]
	v_mfma_f32_16x16x32_bf16 v[14:17], v[102:105], v[190:193], v[14:17]
	v_mfma_f32_16x16x32_bf16 v[66:69], v[82:85], v[166:169], v[66:69]
	v_mfma_f32_16x16x32_bf16 v[62:65], v[106:109], v[166:169], v[62:65]
	v_mfma_f32_16x16x32_bf16 v[50:53], v[82:85], v[178:181], v[50:53]
	v_mfma_f32_16x16x32_bf16 v[46:49], v[106:109], v[178:181], v[46:49]
	v_mfma_f32_16x16x32_bf16 v[34:37], v[82:85], v[186:189], v[34:37]
	v_mfma_f32_16x16x32_bf16 v[30:33], v[106:109], v[186:189], v[30:33]
	v_mfma_f32_16x16x32_bf16 v[18:21], v[82:85], v[194:197], v[18:21]
	v_mfma_f32_16x16x32_bf16 v[14:17], v[106:109], v[194:197], v[14:17]
	v_mfma_f32_16x16x32_bf16 v[58:61], v[134:137], v[162:165], v[58:61]
	v_mfma_f32_16x16x32_bf16 v[54:57], v[142:145], v[162:165], v[54:57]
	v_mfma_f32_16x16x32_bf16 v[42:45], v[134:137], v[170:173], v[42:45]
	v_mfma_f32_16x16x32_bf16 v[38:41], v[142:145], v[170:173], v[38:41]
	v_mfma_f32_16x16x32_bf16 v[26:29], v[134:137], v[182:185], v[26:29]
	v_mfma_f32_16x16x32_bf16 v[22:25], v[142:145], v[182:185], v[22:25]
	v_mfma_f32_16x16x32_bf16 v[10:13], v[134:137], v[190:193], v[10:13]
	v_mfma_f32_16x16x32_bf16 v[4:7], v[142:145], v[190:193], v[6:9]
	v_mfma_f32_16x16x32_bf16 v[58:61], v[138:141], v[166:169], v[58:61]
	v_mfma_f32_16x16x32_bf16 v[54:57], v[154:157], v[166:169], v[54:57]
	v_mfma_f32_16x16x32_bf16 v[42:45], v[138:141], v[178:181], v[42:45]
	v_mfma_f32_16x16x32_bf16 v[38:41], v[154:157], v[178:181], v[38:41]
	v_mfma_f32_16x16x32_bf16 v[26:29], v[138:141], v[186:189], v[26:29]
	v_mfma_f32_16x16x32_bf16 v[22:25], v[154:157], v[186:189], v[22:25]
	v_mfma_f32_16x16x32_bf16 v[10:13], v[138:141], v[194:197], v[10:13]
	v_mfma_f32_16x16x32_bf16 v[4:7], v[154:157], v[194:197], v[4:7]
	s_barrier
	s_setprio 0
	s_add_i32 s73, 0, 0x18000
	v_add_u32_e32 v3, s73, v235
	s_add_i32 s74, 0, 0x1c000
	ds_read_b128 v[78:81], v3
	ds_read_b128 v[82:85], v3 offset:1024
	ds_read_b128 v[102:105], v3 offset:2048
	ds_read_b128 v[106:109], v3 offset:3072
	v_add_u32_e32 v3, s74, v235
	ds_read_b128 v[134:137], v3
	ds_read_b128 v[138:141], v3 offset:1024
	ds_read_b128 v[142:145], v3 offset:2048
	ds_read_b128 v[154:157], v3 offset:3072
	s_add_u32 s68, s68, 0x80000
	s_addc_u32 s69, s69, 0
	s_mov_b32 m0, s42
	v_lshl_add_u64 v[8:9], s[68:69], 0, v[202:203]
	ds_read_b128 v[162:165], v237 offset:32768
	ds_read_b128 v[166:169], v237 offset:33792
	ds_read_b128 v[178:181], v237 offset:34816
	ds_read_b128 v[182:185], v237 offset:35840
	ds_read_b128 v[186:189], v237 offset:36864
	ds_read_b128 v[190:193], v237 offset:37888
	ds_read_b128 v[194:197], v237 offset:38912
	ds_read_b128 v[198:201], v237 offset:39936
	global_load_lds_dwordx4 v[8:9], off
	v_lshl_add_u64 v[8:9], s[68:69], 0, v[206:207]
	s_mov_b32 m0, s43
	s_nop 0
	global_load_lds_dwordx4 v[8:9], off
	s_waitcnt vmcnt(8)
	s_waitcnt lgkmcnt(0)
	s_setprio 1
	s_barrier
	v_mfma_f32_16x16x32_bf16 v[90:93], v[78:81], v[162:165], v[90:93]
	v_mfma_f32_16x16x32_bf16 v[86:89], v[102:105], v[162:165], v[86:89]
	v_mfma_f32_16x16x32_bf16 v[122:125], v[78:81], v[178:181], v[122:125]
	v_mfma_f32_16x16x32_bf16 v[118:121], v[102:105], v[178:181], v[118:121]
	v_mfma_f32_16x16x32_bf16 v[130:133], v[78:81], v[186:189], v[130:133]
	v_mfma_f32_16x16x32_bf16 v[126:129], v[102:105], v[186:189], v[126:129]
	v_mfma_f32_16x16x32_bf16 v[98:101], v[78:81], v[194:197], v[98:101]
	v_mfma_f32_16x16x32_bf16 v[94:97], v[102:105], v[194:197], v[94:97]
	v_mfma_f32_16x16x32_bf16 v[90:93], v[82:85], v[166:169], v[90:93]
	v_mfma_f32_16x16x32_bf16 v[86:89], v[106:109], v[166:169], v[86:89]
	v_mfma_f32_16x16x32_bf16 v[122:125], v[82:85], v[182:185], v[122:125]
	v_mfma_f32_16x16x32_bf16 v[118:121], v[106:109], v[182:185], v[118:121]
	v_mfma_f32_16x16x32_bf16 v[130:133], v[82:85], v[190:193], v[130:133]
	v_mfma_f32_16x16x32_bf16 v[126:129], v[106:109], v[190:193], v[126:129]
	v_mfma_f32_16x16x32_bf16 v[98:101], v[82:85], v[198:201], v[98:101]
	v_mfma_f32_16x16x32_bf16 v[94:97], v[106:109], v[198:201], v[94:97]
	v_mfma_f32_16x16x32_bf16 v[170:173], v[134:137], v[162:165], v[174:177]
	v_mfma_f32_16x16x32_bf16 v[158:161], v[142:145], v[162:165], v[158:161]
	v_mfma_f32_16x16x32_bf16 v[150:153], v[134:137], v[178:181], v[150:153]
	v_mfma_f32_16x16x32_bf16 v[146:149], v[142:145], v[178:181], v[146:149]
	v_mfma_f32_16x16x32_bf16 v[114:117], v[134:137], v[186:189], v[114:117]
	v_mfma_f32_16x16x32_bf16 v[110:113], v[142:145], v[186:189], v[110:113]
	v_mfma_f32_16x16x32_bf16 v[74:77], v[134:137], v[194:197], v[74:77]
	v_mfma_f32_16x16x32_bf16 v[70:73], v[142:145], v[194:197], v[70:73]
	v_mfma_f32_16x16x32_bf16 v[174:177], v[138:141], v[166:169], v[170:173]
	v_mfma_f32_16x16x32_bf16 v[170:173], v[154:157], v[166:169], v[158:161]
	v_mfma_f32_16x16x32_bf16 v[150:153], v[138:141], v[182:185], v[150:153]
	v_mfma_f32_16x16x32_bf16 v[146:149], v[154:157], v[182:185], v[146:149]
	v_mfma_f32_16x16x32_bf16 v[114:117], v[138:141], v[190:193], v[114:117]
	v_mfma_f32_16x16x32_bf16 v[110:113], v[154:157], v[190:193], v[110:113]
	v_mfma_f32_16x16x32_bf16 v[74:77], v[138:141], v[198:201], v[74:77]
	v_mfma_f32_16x16x32_bf16 v[70:73], v[154:157], v[198:201], v[70:73]
	s_barrier
; #define PG8_STAGE(bufoff, gbase, voff) do { _Pragma("unroll") for (int _i = 0; _i < 2; ++_i) \
;         __builtin_amdgcn_global_load_lds((const unsigned*)((const char*)(gbase) + (voff)[_i]), (PG8_LAS unsigned*)(lds + (bufoff) + ldsw + _i * 8192), 16, 0, 0); } while (0)
; #define PG8_LDA(dst, b, h) do { _Pragma("unroll") for (int m = 0; m < 4; ++m) _Pragma("unroll") for (int k = 0; k < 2; ++k) dst[m][k] = *(const PG8_LAS bf16x8*)(lds + PG8_SA(b, h) + aoff + m * 2048 + k * 1024); } while (0)
; #define PG8_LDB(dst, b, h) do { _Pragma("unroll") for (int n = 0; n < 2; ++n) _Pragma("unroll") for (int k = 0; k < 2; ++k) dst[n][k] = *(const PG8_LAS bf16x8*)(lds + PG8_SB(b, h) + boff + n * 2048 + k * 1024); } while (0)
; #define PG8_MMA(ai, bj, At, Bt) do { __builtin_amdgcn_s_setprio(1); _Pragma("unroll") for (int m = 0; m < 4; ++m) _Pragma("unroll") for (int n = 0; n < 2; ++n) _Pragma("unroll") for (int k = 0; k < 2; ++k) \
;         acc[ai][bj][m][n] = __builtin_amdgcn_mfma_f32_16x16x32_bf16(Bt[n][k], At[m][k], acc[ai][bj][m][n], 0, 0, 0); __builtin_amdgcn_s_setprio(0); } while (0)
; #define PG8_WAIT_V(n) asm volatile("s_waitcnt vmcnt(" #n ")" ::: "memory")
; #define PG8_WAIT_L(n) asm volatile("s_waitcnt lgkmcnt(" #n ")" ::: "memory")
; #define PG8_BAR __builtin_amdgcn_s_barrier()
; #define PG8_SCHED __builtin_amdgcn_sched_barrier(0)
; template <class Epi, class Sched, bool ALIGN_EPI = false, bool SP2 = false>
; __device__ __forceinline__ void gemm_phase(PG8_LAS unsigned char* lds, const Gemm g, const Sched& S, const Epi& E) {
;     ...
;             PG8_LDB(B0, 0, 0); PG8_LDB(B1, 0, 1); PG8_SCHED; PG8_LDA(At, 0, 0); PG8_STAGE(PG8_SA(1, 1), a1 + hstepA, voffA);
;             PG8_WAIT_V(8); PG8_WAIT_L(0); PG8_BAR; PG8_MMA(0, 0, At, B0); PG8_MMA(0, 1, At, B1); PG8_BAR; PG8_SCHED;
;     ...
;             PG8_LDA(At, 1, 1); PG8_STAGE(PG8_SB(1, 0), b3, voffB); PG8_STAGE(PG8_SB(1, 1), b3 + hstepB, voffB); PG8_STAGE(PG8_SA(1, 0), a3, voffA);
;             PG8_WAIT_V(8); PG8_WAIT_L(0); PG8_BAR; PG8_MMA(1, 0, At, B0); PG8_MMA(1, 1, At, B1); PG8_BAR; PG8_SCHED;
	s_setprio 0
	s_add_i32 s68, s73, s5
	v_lshl_add_u64 v[8:9], v[218:219], 0, s[24:25]
	s_mov_b32 m0, s68
	ds_read_b128 v[158:161], v237 offset:49152
	ds_read_b128 v[162:165], v237 offset:50176
	ds_read_b128 v[166:169], v237 offset:51200
	ds_read_b128 v[178:181], v237 offset:52224
	ds_read_b128 v[182:185], v237 offset:53248
	ds_read_b128 v[186:189], v237 offset:54272
	ds_read_b128 v[190:193], v237 offset:55296
	ds_read_b128 v[194:197], v237 offset:56320
	global_load_lds_dwordx4 v[8:9], off
	s_add_i32 m0, s68, 0x2000
	s_add_u32 s66, s66, 0x40080
	v_lshl_add_u64 v[8:9], v[220:221], 0, s[24:25]
	s_addc_u32 s67, s67, 0
	s_add_i32 s68, s74, s5
	global_load_lds_dwordx4 v[8:9], off
	v_lshl_add_u64 v[8:9], s[66:67], 0, v[204:205]
	s_mov_b32 m0, s68
	s_nop 0
	global_load_lds_dwordx4 v[8:9], off
	v_lshl_add_u64 v[8:9], s[66:67], 0, v[208:209]
	s_add_i32 m0, s68, 0x2000
	s_nop 0
	global_load_lds_dwordx4 v[8:9], off
	v_lshl_add_u64 v[8:9], v[222:223], 0, s[24:25]
	s_mov_b32 m0, s45
	s_nop 0
	global_load_lds_dwordx4 v[8:9], off
	v_lshl_add_u64 v[8:9], v[224:225], 0, s[24:25]
	s_mov_b32 m0, s50
	s_nop 0
	global_load_lds_dwordx4 v[8:9], off
	s_waitcnt vmcnt(8)
	s_waitcnt lgkmcnt(0)
	s_setprio 1
	s_barrier
	v_mfma_f32_16x16x32_bf16 v[66:69], v[78:81], v[158:161], v[66:69]
	v_mfma_f32_16x16x32_bf16 v[62:65], v[102:105], v[158:161], v[62:65]
	v_mfma_f32_16x16x32_bf16 v[50:53], v[78:81], v[166:169], v[50:53]
	v_mfma_f32_16x16x32_bf16 v[46:49], v[102:105], v[166:169], v[46:49]
	v_mfma_f32_16x16x32_bf16 v[34:37], v[78:81], v[182:185], v[34:37]
	v_mfma_f32_16x16x32_bf16 v[30:33], v[102:105], v[182:185], v[30:33]
	v_mfma_f32_16x16x32_bf16 v[18:21], v[78:81], v[190:193], v[18:21]
	v_mfma_f32_16x16x32_bf16 v[14:17], v[102:105], v[190:193], v[14:17]
	v_mfma_f32_16x16x32_bf16 v[66:69], v[82:85], v[162:165], v[66:69]
	v_mfma_f32_16x16x32_bf16 v[62:65], v[106:109], v[162:165], v[62:65]
	v_mfma_f32_16x16x32_bf16 v[50:53], v[82:85], v[178:181], v[50:53]
	v_mfma_f32_16x16x32_bf16 v[46:49], v[106:109], v[178:181], v[46:49]
	v_mfma_f32_16x16x32_bf16 v[34:37], v[82:85], v[186:189], v[34:37]
	v_mfma_f32_16x16x32_bf16 v[30:33], v[106:109], v[186:189], v[30:33]
	v_mfma_f32_16x16x32_bf16 v[18:21], v[82:85], v[194:197], v[18:21]
	v_mfma_f32_16x16x32_bf16 v[14:17], v[106:109], v[194:197], v[14:17]
	v_mfma_f32_16x16x32_bf16 v[58:61], v[134:137], v[158:161], v[58:61]
	v_mfma_f32_16x16x32_bf16 v[54:57], v[142:145], v[158:161], v[54:57]
	v_mfma_f32_16x16x32_bf16 v[42:45], v[134:137], v[166:169], v[42:45]
	v_mfma_f32_16x16x32_bf16 v[38:41], v[142:145], v[166:169], v[38:41]
	v_mfma_f32_16x16x32_bf16 v[26:29], v[134:137], v[182:185], v[26:29]
	v_mfma_f32_16x16x32_bf16 v[22:25], v[142:145], v[182:185], v[22:25]
	v_mfma_f32_16x16x32_bf16 v[8:11], v[134:137], v[190:193], v[10:13]
	v_mfma_f32_16x16x32_bf16 v[4:7], v[142:145], v[190:193], v[4:7]
	v_mfma_f32_16x16x32_bf16 v[58:61], v[138:141], v[162:165], v[58:61]
	v_mfma_f32_16x16x32_bf16 v[54:57], v[154:157], v[162:165], v[54:57]
	v_mfma_f32_16x16x32_bf16 v[42:45], v[138:141], v[178:181], v[42:45]
	v_mfma_f32_16x16x32_bf16 v[38:41], v[154:157], v[178:181], v[38:41]
	v_mfma_f32_16x16x32_bf16 v[26:29], v[138:141], v[186:189], v[26:29]
	v_mfma_f32_16x16x32_bf16 v[22:25], v[154:157], v[186:189], v[22:25]
	v_mfma_f32_16x16x32_bf16 v[10:13], v[138:141], v[194:197], v[8:11]
	v_mfma_f32_16x16x32_bf16 v[6:9], v[154:157], v[194:197], v[4:7]
	s_barrier
	s_setprio 0
	s_add_i32 s72, s72, 2
	s_add_u32 s64, s64, 0x100
	s_addc_u32 s65, s65, 0
	s_add_u32 s70, s70, 0x100
	s_addc_u32 s71, s71, 0
	s_cmp_gt_u32 s72, 5
	s_cbranch_scc0 .LBB0_963
	s_branch .Lph963_x
.Lph963_y:
	v_add_u32_e32 v3, s51, v235
	ds_read_b128 v[78:81], v3
	ds_read_b128 v[82:85], v3 offset:1024
	ds_read_b128 v[102:105], v3 offset:2048
	ds_read_b128 v[106:109], v3 offset:3072
	v_add_u32_e32 v3, s62, v235
	ds_read_b128 v[134:137], v3
	ds_read_b128 v[138:141], v3 offset:1024
	ds_read_b128 v[142:145], v3 offset:2048
	ds_read_b128 v[154:157], v3 offset:3072
	s_add_u32 s66, s64, 0xfff80080
	s_addc_u32 s67, s65, -1
	s_cmp_eq_u32 s72, 4
	s_cselect_b32 s69, s37, s67
	s_cselect_b32 s68, s39, s66
	s_cselect_b32 s67, s31, s71
	s_cselect_b32 s66, s49, s70
	v_lshl_add_u64 v[4:5], s[64:65], 0, v[210:211]
	s_add_i32 m0, s33, 0xc000
	ds_read_b128 v[158:161], v237
	ds_read_b128 v[162:165], v237 offset:1024
	ds_read_b128 v[166:169], v237 offset:2048
	ds_read_b128 v[178:181], v237 offset:3072
	ds_read_b128 v[182:185], v237 offset:4096
	ds_read_b128 v[186:189], v237 offset:5120
	ds_read_b128 v[190:193], v237 offset:6144
	ds_read_b128 v[194:197], v237 offset:7168
	global_load_lds_dwordx4 v[4:5], off
	v_lshl_add_u64 v[4:5], s[64:65], 0, v[212:213]
	s_add_i32 m0, s33, 0xe000
	s_nop 0
	global_load_lds_dwordx4 v[4:5], off
	s_waitcnt vmcnt(8)
	s_waitcnt lgkmcnt(0)
	s_setprio 2
	s_barrier
; #define PG8_STAGE(bufoff, gbase, voff) do { _Pragma("unroll") for (int _i = 0; _i < 2; ++_i) \
;         __builtin_amdgcn_global_load_lds((const unsigned*)((const char*)(gbase) + (voff)[_i]), (PG8_LAS unsigned*)(lds + (bufoff) + ldsw + _i * 8192), 16, 0, 0); } while (0)
; #define PG8_LDA(dst, b, h) do { _Pragma("unroll") for (int m = 0; m < 4; ++m) _Pragma("unroll") for (int k = 0; k < 2; ++k) dst[m][k] = *(const PG8_LAS bf16x8*)(lds + PG8_SA(b, h) + aoff + m * 2048 + k * 1024); } while (0)
; #define PG8_MMA(ai, bj, At, Bt) do { __builtin_amdgcn_s_setprio(1); _Pragma("unroll") for (int m = 0; m < 4; ++m) _Pragma("unroll") for (int n = 0; n < 2; ++n) _Pragma("unroll") for (int k = 0; k < 2; ++k) \
;         acc[ai][bj][m][n] = __builtin_amdgcn_mfma_f32_16x16x32_bf16(Bt[n][k], At[m][k], acc[ai][bj][m][n], 0, 0, 0); __builtin_amdgcn_s_setprio(0); } while (0)
; #define PG8_WAIT_V(n) asm volatile("s_waitcnt vmcnt(" #n ")" ::: "memory")
; #define PG8_WAIT_L(n) asm volatile("s_waitcnt lgkmcnt(" #n ")" ::: "memory")
; #define PG8_BAR __builtin_amdgcn_s_barrier()
; #define PG8_SCHED __builtin_amdgcn_sched_barrier(0)
; template <class Epi, class Sched, bool ALIGN_EPI = false, bool SP2 = false>
; __device__ __forceinline__ void gemm_phase(PG8_LAS unsigned char* lds, const Gemm g, const Sched& S, const Epi& E) {
;     ...
;             PG8_WAIT_V(8); PG8_WAIT_L(0); PG8_BAR; PG8_MMA(0, 0, At, B0); PG8_MMA(0, 1, At, B1); PG8_BAR; PG8_SCHED;
;             PG8_LDA(At, 0, 1); PG8_STAGE(PG8_SB(0, 0), b2, voffB); PG8_STAGE(PG8_SB(0, 1), b2 + hstepB, voffB); PG8_STAGE(PG8_SA(0, 0), a2, voffA);
;             PG8_WAIT_V(8); PG8_WAIT_L(0); PG8_BAR; PG8_MMA(1, 0, At, B0); PG8_MMA(1, 1, At, B1); PG8_BAR; PG8_SCHED;
	v_mfma_f32_16x16x32_bf16 v[90:93], v[78:81], v[158:161], v[90:93]
	v_mfma_f32_16x16x32_bf16 v[86:89], v[102:105], v[158:161], v[86:89]
	v_mfma_f32_16x16x32_bf16 v[122:125], v[78:81], v[166:169], v[122:125]
	v_mfma_f32_16x16x32_bf16 v[118:121], v[102:105], v[166:169], v[118:121]
	v_mfma_f32_16x16x32_bf16 v[130:133], v[78:81], v[182:185], v[130:133]
	v_mfma_f32_16x16x32_bf16 v[126:129], v[102:105], v[182:185], v[126:129]
	v_mfma_f32_16x16x32_bf16 v[98:101], v[78:81], v[190:193], v[98:101]
	v_mfma_f32_16x16x32_bf16 v[94:97], v[102:105], v[190:193], v[94:97]
	v_mfma_f32_16x16x32_bf16 v[90:93], v[82:85], v[162:165], v[90:93]
	v_mfma_f32_16x16x32_bf16 v[86:89], v[106:109], v[162:165], v[86:89]
	v_mfma_f32_16x16x32_bf16 v[122:125], v[82:85], v[178:181], v[122:125]
	v_mfma_f32_16x16x32_bf16 v[118:121], v[106:109], v[178:181], v[118:121]
	v_mfma_f32_16x16x32_bf16 v[130:133], v[82:85], v[186:189], v[130:133]
	v_mfma_f32_16x16x32_bf16 v[126:129], v[106:109], v[186:189], v[126:129]
	v_mfma_f32_16x16x32_bf16 v[98:101], v[82:85], v[194:197], v[98:101]
	v_mfma_f32_16x16x32_bf16 v[94:97], v[106:109], v[194:197], v[94:97]
	v_mfma_f32_16x16x32_bf16 v[174:177], v[134:137], v[158:161], v[174:177]
	v_mfma_f32_16x16x32_bf16 v[150:153], v[134:137], v[166:169], v[150:153]
	v_mfma_f32_16x16x32_bf16 v[146:149], v[142:145], v[166:169], v[146:149]
	v_mfma_f32_16x16x32_bf16 v[114:117], v[134:137], v[182:185], v[114:117]
	v_mfma_f32_16x16x32_bf16 v[110:113], v[142:145], v[182:185], v[110:113]
	v_mfma_f32_16x16x32_bf16 v[74:77], v[134:137], v[190:193], v[74:77]
	v_mfma_f32_16x16x32_bf16 v[70:73], v[142:145], v[190:193], v[70:73]
	v_mfma_f32_16x16x32_bf16 v[174:177], v[138:141], v[162:165], v[174:177]
	v_mfma_f32_16x16x32_bf16 v[158:161], v[142:145], v[158:161], v[170:173]
	v_mfma_f32_16x16x32_bf16 v[150:153], v[138:141], v[178:181], v[150:153]
	v_mfma_f32_16x16x32_bf16 v[146:149], v[154:157], v[178:181], v[146:149]
	v_mfma_f32_16x16x32_bf16 v[114:117], v[138:141], v[186:189], v[114:117]
	v_mfma_f32_16x16x32_bf16 v[110:113], v[154:157], v[186:189], v[110:113]
	v_mfma_f32_16x16x32_bf16 v[74:77], v[138:141], v[194:197], v[74:77]
	v_mfma_f32_16x16x32_bf16 v[70:73], v[154:157], v[194:197], v[70:73]
	v_mfma_f32_16x16x32_bf16 v[158:161], v[154:157], v[162:165], v[158:161]
	s_barrier
	s_setprio 1
	s_add_i32 s73, s51, s5
	v_lshl_add_u64 v[218:219], s[66:67], 0, v[204:205]
	s_mov_b32 m0, s73
	ds_read_b128 v[162:165], v237 offset:16384
	ds_read_b128 v[166:169], v237 offset:17408
	ds_read_b128 v[170:173], v237 offset:18432
	ds_read_b128 v[178:181], v237 offset:19456
	ds_read_b128 v[182:185], v237 offset:20480
	ds_read_b128 v[186:189], v237 offset:21504
	ds_read_b128 v[190:193], v237 offset:22528
	ds_read_b128 v[194:197], v237 offset:23552
	global_load_lds_dwordx4 v[218:219], off
	s_add_i32 m0, s73, 0x2000
	s_add_u32 s74, s66, 0x40000
	v_lshl_add_u64 v[220:221], s[66:67], 0, v[208:209]
	s_addc_u32 s75, s67, 0
	s_add_i32 s73, s62, s5
	global_load_lds_dwordx4 v[220:221], off
	v_lshl_add_u64 v[4:5], s[74:75], 0, v[204:205]
	s_mov_b32 m0, s73
	v_lshl_add_u64 v[222:223], s[68:69], 0, v[202:203]
	global_load_lds_dwordx4 v[4:5], off
	v_lshl_add_u64 v[4:5], s[74:75], 0, v[208:209]
	s_add_i32 m0, s73, 0x2000
	v_lshl_add_u64 v[224:225], s[68:69], 0, v[206:207]
	global_load_lds_dwordx4 v[4:5], off
	s_mov_b32 m0, s33
	s_nop 0
	global_load_lds_dwordx4 v[222:223], off
	s_mov_b32 m0, s35
	s_nop 0
	global_load_lds_dwordx4 v[224:225], off
	s_waitcnt vmcnt(8)
	s_waitcnt lgkmcnt(0)
	s_setprio 2
	s_barrier
	v_mfma_f32_16x16x32_bf16 v[66:69], v[78:81], v[162:165], v[66:69]
	v_mfma_f32_16x16x32_bf16 v[62:65], v[102:105], v[162:165], v[62:65]
	v_mfma_f32_16x16x32_bf16 v[50:53], v[78:81], v[170:173], v[50:53]
	v_mfma_f32_16x16x32_bf16 v[46:49], v[102:105], v[170:173], v[46:49]
	v_mfma_f32_16x16x32_bf16 v[34:37], v[78:81], v[182:185], v[34:37]
	v_mfma_f32_16x16x32_bf16 v[30:33], v[102:105], v[182:185], v[30:33]
	v_mfma_f32_16x16x32_bf16 v[18:21], v[78:81], v[190:193], v[18:21]
	v_mfma_f32_16x16x32_bf16 v[14:17], v[102:105], v[190:193], v[14:17]
	v_mfma_f32_16x16x32_bf16 v[66:69], v[82:85], v[166:169], v[66:69]
	v_mfma_f32_16x16x32_bf16 v[62:65], v[106:109], v[166:169], v[62:65]
	v_mfma_f32_16x16x32_bf16 v[50:53], v[82:85], v[178:181], v[50:53]
	v_mfma_f32_16x16x32_bf16 v[46:49], v[106:109], v[178:181], v[46:49]
	v_mfma_f32_16x16x32_bf16 v[34:37], v[82:85], v[186:189], v[34:37]
	v_mfma_f32_16x16x32_bf16 v[30:33], v[106:109], v[186:189], v[30:33]
	v_mfma_f32_16x16x32_bf16 v[18:21], v[82:85], v[194:197], v[18:21]
	v_mfma_f32_16x16x32_bf16 v[14:17], v[106:109], v[194:197], v[14:17]
	v_mfma_f32_16x16x32_bf16 v[58:61], v[134:137], v[162:165], v[58:61]
	v_mfma_f32_16x16x32_bf16 v[54:57], v[142:145], v[162:165], v[54:57]
	v_mfma_f32_16x16x32_bf16 v[42:45], v[134:137], v[170:173], v[42:45]
	v_mfma_f32_16x16x32_bf16 v[38:41], v[142:145], v[170:173], v[38:41]
	v_mfma_f32_16x16x32_bf16 v[26:29], v[134:137], v[182:185], v[26:29]
	v_mfma_f32_16x16x32_bf16 v[22:25], v[142:145], v[182:185], v[22:25]
	v_mfma_f32_16x16x32_bf16 v[10:13], v[134:137], v[190:193], v[10:13]
	v_mfma_f32_16x16x32_bf16 v[4:7], v[142:145], v[190:193], v[6:9]
	v_mfma_f32_16x16x32_bf16 v[58:61], v[138:141], v[166:169], v[58:61]
	v_mfma_f32_16x16x32_bf16 v[54:57], v[154:157], v[166:169], v[54:57]
	v_mfma_f32_16x16x32_bf16 v[42:45], v[138:141], v[178:181], v[42:45]
	v_mfma_f32_16x16x32_bf16 v[38:41], v[154:157], v[178:181], v[38:41]
	v_mfma_f32_16x16x32_bf16 v[26:29], v[138:141], v[186:189], v[26:29]
	v_mfma_f32_16x16x32_bf16 v[22:25], v[154:157], v[186:189], v[22:25]
	v_mfma_f32_16x16x32_bf16 v[10:13], v[138:141], v[194:197], v[10:13]
	v_mfma_f32_16x16x32_bf16 v[4:7], v[154:157], v[194:197], v[4:7]
	s_barrier
; #define PG8_STAGE(bufoff, gbase, voff) do { _Pragma("unroll") for (int _i = 0; _i < 2; ++_i) \
;         __builtin_amdgcn_global_load_lds((const unsigned*)((const char*)(gbase) + (voff)[_i]), (PG8_LAS unsigned*)(lds + (bufoff) + ldsw + _i * 8192), 16, 0, 0); } while (0)
; #define PG8_LDA(dst, b, h) do { _Pragma("unroll") for (int m = 0; m < 4; ++m) _Pragma("unroll") for (int k = 0; k < 2; ++k) dst[m][k] = *(const PG8_LAS bf16x8*)(lds + PG8_SA(b, h) + aoff + m * 2048 + k * 1024); } while (0)
; #define PG8_LDB(dst, b, h) do { _Pragma("unroll") for (int n = 0; n < 2; ++n) _Pragma("unroll") for (int k = 0; k < 2; ++k) dst[n][k] = *(const PG8_LAS bf16x8*)(lds + PG8_SB(b, h) + boff + n * 2048 + k * 1024); } while (0)
; #define PG8_MMA(ai, bj, At, Bt) do { __builtin_amdgcn_s_setprio(1); _Pragma("unroll") for (int m = 0; m < 4; ++m) _Pragma("unroll") for (int n = 0; n < 2; ++n) _Pragma("unroll") for (int k = 0; k < 2; ++k) \
;         acc[ai][bj][m][n] = __builtin_amdgcn_mfma_f32_16x16x32_bf16(Bt[n][k], At[m][k], acc[ai][bj][m][n], 0, 0, 0); __builtin_amdgcn_s_setprio(0); } while (0)
; #define PG8_WAIT_V(n) asm volatile("s_waitcnt vmcnt(" #n ")" ::: "memory")
; #define PG8_WAIT_L(n) asm volatile("s_waitcnt lgkmcnt(" #n ")" ::: "memory")
; #define PG8_BAR __builtin_amdgcn_s_barrier()
; #define PG8_SCHED __builtin_amdgcn_sched_barrier(0)
; template <class Epi, class Sched, bool ALIGN_EPI = false, bool SP2 = false>
; __device__ __forceinline__ void gemm_phase(PG8_LAS unsigned char* lds, const Gemm g, const Sched& S, const Epi& E) {
;     ...
;             PG8_LDB(B0, 1, 0); PG8_LDB(B1, 1, 1); PG8_SCHED; PG8_LDA(At, 1, 0); PG8_STAGE(PG8_SA(0, 1), a2 + hstepA, voffA);
;             PG8_WAIT_V(8); PG8_WAIT_L(0); PG8_BAR; PG8_MMA(0, 0, At, B0); PG8_MMA(0, 1, At, B1); PG8_BAR; PG8_SCHED;
;             PG8_LDA(At, 1, 1); PG8_STAGE(PG8_SB(1, 0), b3, voffB); PG8_STAGE(PG8_SB(1, 1), b3 + hstepB, voffB); PG8_STAGE(PG8_SA(1, 0), a3, voffA);
;             PG8_WAIT_V(8); PG8_WAIT_L(0); PG8_BAR; PG8_MMA(1, 0, At, B0); PG8_MMA(1, 1, At, B1); PG8_BAR; PG8_SCHED;
	s_setprio 1
	s_add_i32 s73, 0, 0x18000
	v_add_u32_e32 v3, s73, v235
	s_add_i32 s74, 0, 0x1c000
	ds_read_b128 v[78:81], v3
	ds_read_b128 v[82:85], v3 offset:1024
	ds_read_b128 v[102:105], v3 offset:2048
	ds_read_b128 v[106:109], v3 offset:3072
	v_add_u32_e32 v3, s74, v235
	ds_read_b128 v[134:137], v3
	ds_read_b128 v[138:141], v3 offset:1024
	ds_read_b128 v[142:145], v3 offset:2048
	ds_read_b128 v[154:157], v3 offset:3072
	s_add_u32 s68, s68, 0x80000
	s_addc_u32 s69, s69, 0
	s_mov_b32 m0, s42
	v_lshl_add_u64 v[8:9], s[68:69], 0, v[202:203]
	ds_read_b128 v[162:165], v237 offset:32768
	ds_read_b128 v[166:169], v237 offset:33792
	ds_read_b128 v[178:181], v237 offset:34816
	ds_read_b128 v[182:185], v237 offset:35840
	ds_read_b128 v[186:189], v237 offset:36864
	ds_read_b128 v[190:193], v237 offset:37888
	ds_read_b128 v[194:197], v237 offset:38912
	ds_read_b128 v[198:201], v237 offset:39936
	global_load_lds_dwordx4 v[8:9], off
	v_lshl_add_u64 v[8:9], s[68:69], 0, v[206:207]
	s_mov_b32 m0, s43
	s_nop 0
	global_load_lds_dwordx4 v[8:9], off
	s_waitcnt vmcnt(8)
	s_waitcnt lgkmcnt(0)
	s_setprio 2
	s_barrier
	v_mfma_f32_16x16x32_bf16 v[90:93], v[78:81], v[162:165], v[90:93]
	v_mfma_f32_16x16x32_bf16 v[86:89], v[102:105], v[162:165], v[86:89]
	v_mfma_f32_16x16x32_bf16 v[122:125], v[78:81], v[178:181], v[122:125]
	v_mfma_f32_16x16x32_bf16 v[118:121], v[102:105], v[178:181], v[118:121]
	v_mfma_f32_16x16x32_bf16 v[130:133], v[78:81], v[186:189], v[130:133]
	v_mfma_f32_16x16x32_bf16 v[126:129], v[102:105], v[186:189], v[126:129]
	v_mfma_f32_16x16x32_bf16 v[98:101], v[78:81], v[194:197], v[98:101]
	v_mfma_f32_16x16x32_bf16 v[94:97], v[102:105], v[194:197], v[94:97]
	v_mfma_f32_16x16x32_bf16 v[90:93], v[82:85], v[166:169], v[90:93]
	v_mfma_f32_16x16x32_bf16 v[86:89], v[106:109], v[166:169], v[86:89]
	v_mfma_f32_16x16x32_bf16 v[122:125], v[82:85], v[182:185], v[122:125]
	v_mfma_f32_16x16x32_bf16 v[118:121], v[106:109], v[182:185], v[118:121]
	v_mfma_f32_16x16x32_bf16 v[130:133], v[82:85], v[190:193], v[130:133]
	v_mfma_f32_16x16x32_bf16 v[126:129], v[106:109], v[190:193], v[126:129]
	v_mfma_f32_16x16x32_bf16 v[98:101], v[82:85], v[198:201], v[98:101]
	v_mfma_f32_16x16x32_bf16 v[94:97], v[106:109], v[198:201], v[94:97]
	v_mfma_f32_16x16x32_bf16 v[170:173], v[134:137], v[162:165], v[174:177]
	v_mfma_f32_16x16x32_bf16 v[158:161], v[142:145], v[162:165], v[158:161]
	v_mfma_f32_16x16x32_bf16 v[150:153], v[134:137], v[178:181], v[150:153]
	v_mfma_f32_16x16x32_bf16 v[146:149], v[142:145], v[178:181], v[146:149]
	v_mfma_f32_16x16x32_bf16 v[114:117], v[134:137], v[186:189], v[114:117]
	v_mfma_f32_16x16x32_bf16 v[110:113], v[142:145], v[186:189], v[110:113]
	v_mfma_f32_16x16x32_bf16 v[74:77], v[134:137], v[194:197], v[74:77]
	v_mfma_f32_16x16x32_bf16 v[70:73], v[142:145], v[194:197], v[70:73]
	v_mfma_f32_16x16x32_bf16 v[174:177], v[138:141], v[166:169], v[170:173]
	v_mfma_f32_16x16x32_bf16 v[170:173], v[154:157], v[166:169], v[158:161]
	v_mfma_f32_16x16x32_bf16 v[150:153], v[138:141], v[182:185], v[150:153]
	v_mfma_f32_16x16x32_bf16 v[146:149], v[154:157], v[182:185], v[146:149]
	v_mfma_f32_16x16x32_bf16 v[114:117], v[138:141], v[190:193], v[114:117]
	v_mfma_f32_16x16x32_bf16 v[110:113], v[154:157], v[190:193], v[110:113]
	v_mfma_f32_16x16x32_bf16 v[74:77], v[138:141], v[198:201], v[74:77]
	v_mfma_f32_16x16x32_bf16 v[70:73], v[154:157], v[198:201], v[70:73]
	s_barrier
	s_setprio 1
	s_add_i32 s68, s73, s5
	v_lshl_add_u64 v[8:9], v[218:219], 0, s[24:25]
	s_mov_b32 m0, s68
	ds_read_b128 v[158:161], v237 offset:49152
	ds_read_b128 v[162:165], v237 offset:50176
	ds_read_b128 v[166:169], v237 offset:51200
	ds_read_b128 v[178:181], v237 offset:52224
	ds_read_b128 v[182:185], v237 offset:53248
	ds_read_b128 v[186:189], v237 offset:54272
	ds_read_b128 v[190:193], v237 offset:55296
	ds_read_b128 v[194:197], v237 offset:56320
	global_load_lds_dwordx4 v[8:9], off
	s_add_i32 m0, s68, 0x2000
	s_add_u32 s66, s66, 0x40080
	v_lshl_add_u64 v[8:9], v[220:221], 0, s[24:25]
	s_addc_u32 s67, s67, 0
	s_add_i32 s68, s74, s5
	global_load_lds_dwordx4 v[8:9], off
	v_lshl_add_u64 v[8:9], s[66:67], 0, v[204:205]
	s_mov_b32 m0, s68
	s_nop 0
	global_load_lds_dwordx4 v[8:9], off
	v_lshl_add_u64 v[8:9], s[66:67], 0, v[208:209]
	s_add_i32 m0, s68, 0x2000
	s_nop 0
	global_load_lds_dwordx4 v[8:9], off
	v_lshl_add_u64 v[8:9], v[222:223], 0, s[24:25]
	s_mov_b32 m0, s45
	s_nop 0
	global_load_lds_dwordx4 v[8:9], off
	v_lshl_add_u64 v[8:9], v[224:225], 0, s[24:25]
	s_mov_b32 m0, s50
	s_nop 0
	global_load_lds_dwordx4 v[8:9], off
	s_waitcnt vmcnt(8)
	s_waitcnt lgkmcnt(0)
	s_setprio 2
	s_barrier
	v_mfma_f32_16x16x32_bf16 v[66:69], v[78:81], v[158:161], v[66:69]
	v_mfma_f32_16x16x32_bf16 v[62:65], v[102:105], v[158:161], v[62:65]
	v_mfma_f32_16x16x32_bf16 v[50:53], v[78:81], v[166:169], v[50:53]
	v_mfma_f32_16x16x32_bf16 v[46:49], v[102:105], v[166:169], v[46:49]
	v_mfma_f32_16x16x32_bf16 v[34:37], v[78:81], v[182:185], v[34:37]
	v_mfma_f32_16x16x32_bf16 v[30:33], v[102:105], v[182:185], v[30:33]
	v_mfma_f32_16x16x32_bf16 v[18:21], v[78:81], v[190:193], v[18:21]
	v_mfma_f32_16x16x32_bf16 v[14:17], v[102:105], v[190:193], v[14:17]
	v_mfma_f32_16x16x32_bf16 v[66:69], v[82:85], v[162:165], v[66:69]
	v_mfma_f32_16x16x32_bf16 v[62:65], v[106:109], v[162:165], v[62:65]
	v_mfma_f32_16x16x32_bf16 v[50:53], v[82:85], v[178:181], v[50:53]
	v_mfma_f32_16x16x32_bf16 v[46:49], v[106:109], v[178:181], v[46:49]
	v_mfma_f32_16x16x32_bf16 v[34:37], v[82:85], v[186:189], v[34:37]
	v_mfma_f32_16x16x32_bf16 v[30:33], v[106:109], v[186:189], v[30:33]
	v_mfma_f32_16x16x32_bf16 v[18:21], v[82:85], v[194:197], v[18:21]
	v_mfma_f32_16x16x32_bf16 v[14:17], v[106:109], v[194:197], v[14:17]
	v_mfma_f32_16x16x32_bf16 v[58:61], v[134:137], v[158:161], v[58:61]
	v_mfma_f32_16x16x32_bf16 v[54:57], v[142:145], v[158:161], v[54:57]
	v_mfma_f32_16x16x32_bf16 v[42:45], v[134:137], v[166:169], v[42:45]
	v_mfma_f32_16x16x32_bf16 v[38:41], v[142:145], v[166:169], v[38:41]
	v_mfma_f32_16x16x32_bf16 v[26:29], v[134:137], v[182:185], v[26:29]
	v_mfma_f32_16x16x32_bf16 v[22:25], v[142:145], v[182:185], v[22:25]
	v_mfma_f32_16x16x32_bf16 v[8:11], v[134:137], v[190:193], v[10:13]
	v_mfma_f32_16x16x32_bf16 v[4:7], v[142:145], v[190:193], v[4:7]
	v_mfma_f32_16x16x32_bf16 v[58:61], v[138:141], v[162:165], v[58:61]
	v_mfma_f32_16x16x32_bf16 v[54:57], v[154:157], v[162:165], v[54:57]
	v_mfma_f32_16x16x32_bf16 v[42:45], v[138:141], v[178:181], v[42:45]
	v_mfma_f32_16x16x32_bf16 v[38:41], v[154:157], v[178:181], v[38:41]
	v_mfma_f32_16x16x32_bf16 v[26:29], v[138:141], v[186:189], v[26:29]
	v_mfma_f32_16x16x32_bf16 v[22:25], v[154:157], v[186:189], v[22:25]
	v_mfma_f32_16x16x32_bf16 v[10:13], v[138:141], v[194:197], v[8:11]
	v_mfma_f32_16x16x32_bf16 v[6:9], v[154:157], v[194:197], v[4:7]
	s_barrier
	s_setprio 1
	s_add_i32 s72, s72, 2
	s_add_u32 s64, s64, 0x100
	s_addc_u32 s65, s65, 0
	s_add_u32 s70, s70, 0x100
	s_addc_u32 s71, s71, 0
	s_cmp_gt_u32 s72, 5
	s_cbranch_scc0 .Lph963_y
	s_setprio 0
; #define PG8_BAR __builtin_amdgcn_s_barrier()
; template <class Epi, class Sched, bool ALIGN_EPI = false, bool SP2 = false>
; __device__ __forceinline__ void gemm_phase(PG8_LAS unsigned char* lds, const Gemm g, const Sched& S, const Epi& E) {
;     ...
;         if constexpr (ALIGN_EPI) { if (wr == 0) PG8_BAR; }
.Lph963_x:
	s_and_b64 vcc, exec, s[28:29]
	s_cbranch_vccz .LBB0_966
	s_barrier

;     __host__ __device__ bool next(int i, Unit& u) const { if (!so.next(i >> 1, u)) return false; u.k0 = (i & 1) * 512; return true; }
;     __host__ __device__ bool next(int i, Unit& u) const { if (!so.next(i, u)) return false; u.pe = main_tile(u.pn); return true; }
;     __host__ __device__ bool next(int i, Unit& u) const { if (start + i * stride >= limit) return false; if (!so.next(i, u)) return false; u.pe = late_tile(u.pn); return true; }
; #define PG8_STAGE(bufoff, gbase, voff) do { _Pragma("unroll") for (int _i = 0; _i < 2; ++_i) \
;         __builtin_amdgcn_global_load_lds((const unsigned*)((const char*)(gbase) + (voff)[_i]), (PG8_LAS unsigned*)(lds + (bufoff) + ldsw + _i * 8192), 16, 0, 0); } while (0)
; #define PG8_LDA(dst, b, h) do { _Pragma("unroll") for (int m = 0; m < 4; ++m) _Pragma("unroll") for (int k = 0; k < 2; ++k) dst[m][k] = *(const PG8_LAS bf16x8*)(lds + PG8_SA(b, h) + aoff + m * 2048 + k * 1024); } while (0)
; template <class Epi, class Sched, bool ALIGN_EPI = false, bool SP2 = false>
; __device__ __forceinline__ void gemm_phase(PG8_LAS unsigned char* lds, const Gemm g, const Sched& S, const Epi& E) {
;     ...
;         const bool has_next = S.next(ui + 1, nxt);
;         const char* nA = has_next ? (const char*)g.A + (size_t)nxt.pm * tstepA + (size_t)nxt.k0 * 2 : cA; const char* nB = has_next ? (const char*)g.Bt + (size_t)nxt.pn * tstepB + (size_t)nxt.k0 * 2 : cB;
;         for (int t = 0; t < nt; t += 2) {
;             const bool last = (t == nt - 2);
;             const char* a1 = cA + (size_t)(t + 1) * kstepA;
;             const char* a2 = last ? nA : cA + (size_t)(t + 2) * kstepA; const char* b2 = last ? nB : cB + (size_t)(t + 2) * kstep;
;             const char* a3 = a2 + kstepA; const char* b3 = b2 + kstep;
;             if (last && has_next) S.a_ready(nxt);
;             if constexpr (SP2) {
;             PG8_LDB(B0, 0, 0); PG8_LDB(B1, 0, 1); PG8_SCHED; PG8_LDA(At, 0, 0); PG8_STAGE(PG8_SA(1, 1), a1 + hstepA, voffA);
;             PG8_WAIT_V(8); PG8_WAIT_L(0); PG8_BAR; PG8_MMA(0, 0, At, B0); PG8_MMA(0, 1, At, B1); PG8_BAR; PG8_SCHED;
;             PG8_LDA(At, 0, 1); PG8_STAGE(PG8_SB(0, 0), b2, voffB); PG8_STAGE(PG8_SB(0, 1), b2 + hstepB, voffB); PG8_STAGE(PG8_SA(0, 0), a2, voffA);
;             PG8_WAIT_V(8); PG8_WAIT_L(0); PG8_BAR; PG8_MMA(1, 0, At, B0); PG8_MMA(1, 1, At, B1); PG8_BAR; PG8_SCHED;
.LBB0_1087:
	s_add_u32 s67, s40, 0x100
	s_addc_u32 s68, s41, 0
	s_ashr_i32 s31, s30, 31
	s_lshl_b64 s[36:37], s[30:31], 19
	s_add_u32 s38, s8, s36
	s_addc_u32 s39, s9, s37
	s_and_b64 s[36:37], s[6:7], exec
	s_cselect_b32 s31, s39, s23
	s_cselect_b32 s69, s38, s22
	s_ashr_i32 s29, s28, 31
	s_lshl_b64 s[36:37], s[28:29], 19
	s_add_u32 s36, s16, s36
	s_addc_u32 s37, s17, s37
	s_and_b64 s[46:47], s[6:7], exec
	s_cselect_b32 s29, s37, s41
	s_cselect_b32 s70, s36, s40
	v_lshl_add_u64 v[146:147], s[22:23], 0, v[138:139]
	v_lshl_add_u64 v[148:149], s[22:23], 0, v[140:141]
	s_mov_b32 s71, -2
	s_mov_b64 s[40:41], 0
	s_cmp_lg_u32 s101, 0
	s_cbranch_scc1 .Lph1088_y
.LBB0_1088:
	v_add_u32_e32 v166, s64, v152
	v_add_u32_e32 v171, s65, v152
	s_add_u32 s46, s22, s40
	ds_read_b128 v[154:157], v166
	ds_read_b128 v[158:161], v166 offset:1024
	ds_read_b128 v[162:165], v166 offset:2048
	ds_read_b128 v[166:169], v166 offset:3072
	ds_read_b128 v[172:175], v171
	ds_read_b128 v[176:179], v171 offset:1024
	ds_read_b128 v[180:183], v171 offset:2048
	ds_read_b128 v[184:187], v171 offset:3072
	s_addc_u32 s47, s23, s41
	s_add_u32 s46, s46, 0x100
	s_addc_u32 s47, s47, 0
	s_add_u32 s72, s67, s40
	s_addc_u32 s73, s68, s41
	s_cmpk_eq_i32 s40, 0x700
	s_cselect_b32 s49, s31, s47
	s_cselect_b32 s48, s69, s46
	s_cselect_b32 s47, s29, s73
	s_cselect_b32 s46, s70, s72
	v_lshl_add_u64 v[220:221], v[146:147], 0, s[40:41]
	s_add_i32 m0, s43, 0xc000
	ds_read_b128 v[188:191], v153
	ds_read_b128 v[192:195], v153 offset:1024
	ds_read_b128 v[196:199], v153 offset:2048
	ds_read_b128 v[200:203], v153 offset:3072
	ds_read_b128 v[204:207], v153 offset:4096
	ds_read_b128 v[208:211], v153 offset:5120
	ds_read_b128 v[212:215], v153 offset:6144
	ds_read_b128 v[216:219], v153 offset:7168
	global_load_lds_dwordx4 v[220:221], off
	v_lshl_add_u64 v[220:221], v[148:149], 0, s[40:41]
	s_add_i32 m0, s43, 0xe000
	s_nop 0
	global_load_lds_dwordx4 v[220:221], off
	s_waitcnt vmcnt(8)
	s_waitcnt lgkmcnt(0)
	s_setprio 1
	s_barrier
	v_mfma_f32_16x16x32_bf16 v[122:125], v[154:157], v[188:191], v[122:125]
	v_mfma_f32_16x16x32_bf16 v[118:121], v[162:165], v[188:191], v[118:121]
	v_mfma_f32_16x16x32_bf16 v[114:117], v[154:157], v[196:199], v[114:117]
	v_mfma_f32_16x16x32_bf16 v[98:101], v[162:165], v[196:199], v[98:101]
	v_mfma_f32_16x16x32_bf16 v[134:137], v[154:157], v[204:207], v[134:137]
	v_mfma_f32_16x16x32_bf16 v[102:105], v[162:165], v[204:207], v[102:105]
	v_mfma_f32_16x16x32_bf16 v[110:113], v[154:157], v[212:215], v[110:113]
	v_mfma_f32_16x16x32_bf16 v[86:89], v[162:165], v[212:215], v[86:89]
	v_mfma_f32_16x16x32_bf16 v[122:125], v[158:161], v[192:195], v[122:125]
	v_mfma_f32_16x16x32_bf16 v[118:121], v[166:169], v[192:195], v[118:121]
	v_mfma_f32_16x16x32_bf16 v[114:117], v[158:161], v[200:203], v[114:117]
	v_mfma_f32_16x16x32_bf16 v[98:101], v[166:169], v[200:203], v[98:101]
	v_mfma_f32_16x16x32_bf16 v[134:137], v[158:161], v[208:211], v[134:137]
	v_mfma_f32_16x16x32_bf16 v[102:105], v[166:169], v[208:211], v[102:105]
	v_mfma_f32_16x16x32_bf16 v[110:113], v[158:161], v[216:219], v[110:113]
	v_mfma_f32_16x16x32_bf16 v[86:89], v[166:169], v[216:219], v[86:89]
	v_mfma_f32_16x16x32_bf16 v[106:109], v[172:175], v[188:191], v[106:109]
	v_mfma_f32_16x16x32_bf16 v[94:97], v[180:183], v[188:191], v[94:97]
	v_mfma_f32_16x16x32_bf16 v[90:93], v[172:175], v[196:199], v[90:93]
	v_mfma_f32_16x16x32_bf16 v[82:85], v[180:183], v[196:199], v[82:85]
	v_mfma_f32_16x16x32_bf16 v[78:81], v[172:175], v[204:207], v[78:81]
	v_mfma_f32_16x16x32_bf16 v[74:77], v[180:183], v[204:207], v[74:77]
	v_mfma_f32_16x16x32_bf16 v[70:73], v[172:175], v[212:215], v[70:73]
	v_mfma_f32_16x16x32_bf16 v[66:69], v[180:183], v[212:215], v[66:69]
	v_mfma_f32_16x16x32_bf16 v[106:109], v[176:179], v[192:195], v[106:109]
	v_mfma_f32_16x16x32_bf16 v[94:97], v[184:187], v[192:195], v[94:97]
	v_mfma_f32_16x16x32_bf16 v[90:93], v[176:179], v[200:203], v[90:93]
	v_mfma_f32_16x16x32_bf16 v[82:85], v[184:187], v[200:203], v[82:85]
	v_mfma_f32_16x16x32_bf16 v[78:81], v[176:179], v[208:211], v[78:81]
	v_mfma_f32_16x16x32_bf16 v[74:77], v[184:187], v[208:211], v[74:77]
	v_mfma_f32_16x16x32_bf16 v[70:73], v[176:179], v[216:219], v[70:73]
	v_mfma_f32_16x16x32_bf16 v[66:69], v[184:187], v[216:219], v[66:69]
	s_barrier
	s_setprio 0
	s_add_i32 s72, s64, s33
	v_lshl_add_u64 v[220:221], s[46:47], 0, v[126:127]
	s_mov_b32 m0, s72
	ds_read_b128 v[188:191], v153 offset:16384
	ds_read_b128 v[192:195], v153 offset:17408
	ds_read_b128 v[196:199], v153 offset:18432
	ds_read_b128 v[200:203], v153 offset:19456
	ds_read_b128 v[204:207], v153 offset:20480
	ds_read_b128 v[208:211], v153 offset:21504
	ds_read_b128 v[212:215], v153 offset:22528
	ds_read_b128 v[216:219], v153 offset:23552
	global_load_lds_dwordx4 v[220:221], off
	s_add_i32 m0, s72, 0x2000
	s_add_u32 s72, s46, 0x40000
	v_lshl_add_u64 v[222:223], s[46:47], 0, v[132:133]
	s_addc_u32 s73, s47, 0
	s_add_i32 s74, s65, s33
	global_load_lds_dwordx4 v[222:223], off
	v_lshl_add_u64 v[224:225], s[72:73], 0, v[126:127]
	s_mov_b32 m0, s74
	v_lshl_add_u64 v[226:227], s[48:49], 0, v[130:131]
	global_load_lds_dwordx4 v[224:225], off
	v_lshl_add_u64 v[224:225], s[72:73], 0, v[132:133]
	s_add_i32 m0, s74, 0x2000
	s_nop 0
	global_load_lds_dwordx4 v[224:225], off
	v_lshl_add_u64 v[224:225], s[48:49], 0, v[128:129]
	s_mov_b32 m0, s43
	s_nop 0
	global_load_lds_dwordx4 v[224:225], off
	s_mov_b32 m0, s44
	s_nop 0
	global_load_lds_dwordx4 v[226:227], off
	s_waitcnt vmcnt(8)
	s_waitcnt lgkmcnt(0)
	s_setprio 1
	s_barrier
; #define PG8_STAGE(bufoff, gbase, voff) do { _Pragma("unroll") for (int _i = 0; _i < 2; ++_i) \
;         __builtin_amdgcn_global_load_lds((const unsigned*)((const char*)(gbase) + (voff)[_i]), (PG8_LAS unsigned*)(lds + (bufoff) + ldsw + _i * 8192), 16, 0, 0); } while (0)
; #define PG8_LDA(dst, b, h) do { _Pragma("unroll") for (int m = 0; m < 4; ++m) _Pragma("unroll") for (int k = 0; k < 2; ++k) dst[m][k] = *(const PG8_LAS bf16x8*)(lds + PG8_SA(b, h) + aoff + m * 2048 + k * 1024); } while (0)
; #define PG8_LDB(dst, b, h) do { _Pragma("unroll") for (int n = 0; n < 2; ++n) _Pragma("unroll") for (int k = 0; k < 2; ++k) dst[n][k] = *(const PG8_LAS bf16x8*)(lds + PG8_SB(b, h) + boff + n * 2048 + k * 1024); } while (0)
; #define PG8_MMA(ai, bj, At, Bt) do { __builtin_amdgcn_s_setprio(1); _Pragma("unroll") for (int m = 0; m < 4; ++m) _Pragma("unroll") for (int n = 0; n < 2; ++n) _Pragma("unroll") for (int k = 0; k < 2; ++k) \
;         acc[ai][bj][m][n] = __builtin_amdgcn_mfma_f32_16x16x32_bf16(Bt[n][k], At[m][k], acc[ai][bj][m][n], 0, 0, 0); __builtin_amdgcn_s_setprio(0); } while (0)
; #define PG8_WAIT_V(n) asm volatile("s_waitcnt vmcnt(" #n ")" ::: "memory")
; #define PG8_WAIT_L(n) asm volatile("s_waitcnt lgkmcnt(" #n ")" ::: "memory")
; #define PG8_BAR __builtin_amdgcn_s_barrier()
; #define PG8_SCHED __builtin_amdgcn_sched_barrier(0)
; template <class Epi, class Sched, bool ALIGN_EPI = false, bool SP2 = false>
; __device__ __forceinline__ void gemm_phase(PG8_LAS unsigned char* lds, const Gemm g, const Sched& S, const Epi& E) {
;     ...
;             PG8_WAIT_V(8); PG8_WAIT_L(0); PG8_BAR; PG8_MMA(1, 0, At, B0); PG8_MMA(1, 1, At, B1); PG8_BAR; PG8_SCHED;
;             PG8_LDB(B0, 1, 0); PG8_LDB(B1, 1, 1); PG8_SCHED; PG8_LDA(At, 1, 0); PG8_STAGE(PG8_SA(0, 1), a2 + hstepA, voffA);
;             PG8_WAIT_V(8); PG8_WAIT_L(0); PG8_BAR; PG8_MMA(0, 0, At, B0); PG8_MMA(0, 1, At, B1); PG8_BAR; PG8_SCHED;
;             PG8_LDA(At, 1, 1); PG8_STAGE(PG8_SB(1, 0), b3, voffB); PG8_STAGE(PG8_SB(1, 1), b3 + hstepB, voffB); PG8_STAGE(PG8_SA(1, 0), a3, voffA);
	v_mfma_f32_16x16x32_bf16 v[62:65], v[154:157], v[188:191], v[62:65]
	v_mfma_f32_16x16x32_bf16 v[58:61], v[162:165], v[188:191], v[58:61]
	v_mfma_f32_16x16x32_bf16 v[54:57], v[154:157], v[196:199], v[54:57]
	v_mfma_f32_16x16x32_bf16 v[46:49], v[162:165], v[196:199], v[46:49]
	v_mfma_f32_16x16x32_bf16 v[38:41], v[154:157], v[204:207], v[38:41]
	v_mfma_f32_16x16x32_bf16 v[30:33], v[162:165], v[204:207], v[30:33]
	v_mfma_f32_16x16x32_bf16 v[14:17], v[154:157], v[212:215], v[14:17]
	v_mfma_f32_16x16x32_bf16 v[10:13], v[162:165], v[212:215], v[10:13]
	v_mfma_f32_16x16x32_bf16 v[62:65], v[158:161], v[192:195], v[62:65]
	v_mfma_f32_16x16x32_bf16 v[58:61], v[166:169], v[192:195], v[58:61]
	v_mfma_f32_16x16x32_bf16 v[54:57], v[158:161], v[200:203], v[54:57]
	v_mfma_f32_16x16x32_bf16 v[46:49], v[166:169], v[200:203], v[46:49]
	v_mfma_f32_16x16x32_bf16 v[38:41], v[158:161], v[208:211], v[38:41]
	v_mfma_f32_16x16x32_bf16 v[30:33], v[166:169], v[208:211], v[30:33]
	v_mfma_f32_16x16x32_bf16 v[14:17], v[158:161], v[216:219], v[14:17]
	v_mfma_f32_16x16x32_bf16 v[10:13], v[166:169], v[216:219], v[10:13]
	v_mfma_f32_16x16x32_bf16 v[50:53], v[172:175], v[188:191], v[50:53]
	v_mfma_f32_16x16x32_bf16 v[42:45], v[180:183], v[188:191], v[42:45]
	v_mfma_f32_16x16x32_bf16 v[34:37], v[172:175], v[196:199], v[34:37]
	v_mfma_f32_16x16x32_bf16 v[26:29], v[180:183], v[196:199], v[26:29]
	v_mfma_f32_16x16x32_bf16 v[22:25], v[172:175], v[204:207], v[22:25]
	v_mfma_f32_16x16x32_bf16 v[18:21], v[180:183], v[204:207], v[18:21]
	v_mfma_f32_16x16x32_bf16 v[6:9], v[172:175], v[212:215], v[6:9]
	v_mfma_f32_16x16x32_bf16 v[2:5], v[180:183], v[212:215], v[2:5]
	v_mfma_f32_16x16x32_bf16 v[50:53], v[176:179], v[192:195], v[50:53]
	v_mfma_f32_16x16x32_bf16 v[42:45], v[184:187], v[192:195], v[42:45]
	v_mfma_f32_16x16x32_bf16 v[34:37], v[176:179], v[200:203], v[34:37]
	v_mfma_f32_16x16x32_bf16 v[26:29], v[184:187], v[200:203], v[26:29]
	v_mfma_f32_16x16x32_bf16 v[22:25], v[176:179], v[208:211], v[22:25]
	v_mfma_f32_16x16x32_bf16 v[18:21], v[184:187], v[208:211], v[18:21]
	v_mfma_f32_16x16x32_bf16 v[6:9], v[176:179], v[216:219], v[6:9]
	v_mfma_f32_16x16x32_bf16 v[2:5], v[184:187], v[216:219], v[2:5]
	s_barrier
	s_setprio 0
	s_add_i32 s72, 0, 0x18000
	s_add_i32 s73, 0, 0x1c000
	v_add_u32_e32 v166, s72, v152
	v_add_u32_e32 v171, s73, v152
	ds_read_b128 v[154:157], v166
	ds_read_b128 v[158:161], v166 offset:1024
	ds_read_b128 v[162:165], v166 offset:2048
	ds_read_b128 v[166:169], v166 offset:3072
	ds_read_b128 v[172:175], v171
	ds_read_b128 v[176:179], v171 offset:1024
	ds_read_b128 v[180:183], v171 offset:2048
	ds_read_b128 v[184:187], v171 offset:3072
	s_add_u32 s48, s48, 0x40000
	s_addc_u32 s49, s49, 0
	s_mov_b32 m0, s45
	v_lshl_add_u64 v[228:229], s[48:49], 0, v[128:129]
	ds_read_b128 v[188:191], v153 offset:32768
	ds_read_b128 v[192:195], v153 offset:33792
	ds_read_b128 v[196:199], v153 offset:34816
	ds_read_b128 v[200:203], v153 offset:35840
	ds_read_b128 v[204:207], v153 offset:36864
	ds_read_b128 v[208:211], v153 offset:37888
	ds_read_b128 v[212:215], v153 offset:38912
	ds_read_b128 v[216:219], v153 offset:39936
	global_load_lds_dwordx4 v[228:229], off
	v_lshl_add_u64 v[228:229], s[48:49], 0, v[130:131]
	s_mov_b32 m0, s50
	s_nop 0
	global_load_lds_dwordx4 v[228:229], off
	s_waitcnt vmcnt(8)
	s_waitcnt lgkmcnt(0)
	s_setprio 1
	s_barrier
	v_mfma_f32_16x16x32_bf16 v[122:125], v[154:157], v[188:191], v[122:125]
	v_mfma_f32_16x16x32_bf16 v[118:121], v[162:165], v[188:191], v[118:121]
	v_mfma_f32_16x16x32_bf16 v[114:117], v[154:157], v[196:199], v[114:117]
	v_mfma_f32_16x16x32_bf16 v[98:101], v[162:165], v[196:199], v[98:101]
	v_mfma_f32_16x16x32_bf16 v[134:137], v[154:157], v[204:207], v[134:137]
	v_mfma_f32_16x16x32_bf16 v[102:105], v[162:165], v[204:207], v[102:105]
	v_mfma_f32_16x16x32_bf16 v[110:113], v[154:157], v[212:215], v[110:113]
	v_mfma_f32_16x16x32_bf16 v[86:89], v[162:165], v[212:215], v[86:89]
	v_mfma_f32_16x16x32_bf16 v[122:125], v[158:161], v[192:195], v[122:125]
	v_mfma_f32_16x16x32_bf16 v[118:121], v[166:169], v[192:195], v[118:121]
	v_mfma_f32_16x16x32_bf16 v[114:117], v[158:161], v[200:203], v[114:117]
	v_mfma_f32_16x16x32_bf16 v[98:101], v[166:169], v[200:203], v[98:101]
	v_mfma_f32_16x16x32_bf16 v[134:137], v[158:161], v[208:211], v[134:137]
	v_mfma_f32_16x16x32_bf16 v[102:105], v[166:169], v[208:211], v[102:105]
	v_mfma_f32_16x16x32_bf16 v[110:113], v[158:161], v[216:219], v[110:113]
	v_mfma_f32_16x16x32_bf16 v[86:89], v[166:169], v[216:219], v[86:89]
	v_mfma_f32_16x16x32_bf16 v[106:109], v[172:175], v[188:191], v[106:109]
	v_mfma_f32_16x16x32_bf16 v[94:97], v[180:183], v[188:191], v[94:97]
	v_mfma_f32_16x16x32_bf16 v[90:93], v[172:175], v[196:199], v[90:93]
	v_mfma_f32_16x16x32_bf16 v[82:85], v[180:183], v[196:199], v[82:85]
	v_mfma_f32_16x16x32_bf16 v[78:81], v[172:175], v[204:207], v[78:81]
	v_mfma_f32_16x16x32_bf16 v[74:77], v[180:183], v[204:207], v[74:77]
	v_mfma_f32_16x16x32_bf16 v[70:73], v[172:175], v[212:215], v[70:73]
	v_mfma_f32_16x16x32_bf16 v[66:69], v[180:183], v[212:215], v[66:69]
	v_mfma_f32_16x16x32_bf16 v[106:109], v[176:179], v[192:195], v[106:109]
	v_mfma_f32_16x16x32_bf16 v[94:97], v[184:187], v[192:195], v[94:97]
	v_mfma_f32_16x16x32_bf16 v[90:93], v[176:179], v[200:203], v[90:93]
	v_mfma_f32_16x16x32_bf16 v[82:85], v[184:187], v[200:203], v[82:85]
	v_mfma_f32_16x16x32_bf16 v[78:81], v[176:179], v[208:211], v[78:81]
	v_mfma_f32_16x16x32_bf16 v[74:77], v[184:187], v[208:211], v[74:77]
	v_mfma_f32_16x16x32_bf16 v[70:73], v[176:179], v[216:219], v[70:73]
	v_mfma_f32_16x16x32_bf16 v[66:69], v[184:187], v[216:219], v[66:69]
	s_barrier
; #define PG8_STAGE(bufoff, gbase, voff) do { _Pragma("unroll") for (int _i = 0; _i < 2; ++_i) \
;         __builtin_amdgcn_global_load_lds((const unsigned*)((const char*)(gbase) + (voff)[_i]), (PG8_LAS unsigned*)(lds + (bufoff) + ldsw + _i * 8192), 16, 0, 0); } while (0)
; #define PG8_LDA(dst, b, h) do { _Pragma("unroll") for (int m = 0; m < 4; ++m) _Pragma("unroll") for (int k = 0; k < 2; ++k) dst[m][k] = *(const PG8_LAS bf16x8*)(lds + PG8_SA(b, h) + aoff + m * 2048 + k * 1024); } while (0)
; #define PG8_LDB(dst, b, h) do { _Pragma("unroll") for (int n = 0; n < 2; ++n) _Pragma("unroll") for (int k = 0; k < 2; ++k) dst[n][k] = *(const PG8_LAS bf16x8*)(lds + PG8_SB(b, h) + boff + n * 2048 + k * 1024); } while (0)
; #define PG8_MMA(ai, bj, At, Bt) do { __builtin_amdgcn_s_setprio(1); _Pragma("unroll") for (int m = 0; m < 4; ++m) _Pragma("unroll") for (int n = 0; n < 2; ++n) _Pragma("unroll") for (int k = 0; k < 2; ++k) \
;         acc[ai][bj][m][n] = __builtin_amdgcn_mfma_f32_16x16x32_bf16(Bt[n][k], At[m][k], acc[ai][bj][m][n], 0, 0, 0); __builtin_amdgcn_s_setprio(0); } while (0)
; #define PG8_WAIT_V(n) asm volatile("s_waitcnt vmcnt(" #n ")" ::: "memory")
; #define PG8_WAIT_L(n) asm volatile("s_waitcnt lgkmcnt(" #n ")" ::: "memory")
; #define PG8_BAR __builtin_amdgcn_s_barrier()
; #define PG8_SCHED __builtin_amdgcn_sched_barrier(0)
; template <class Epi, class Sched, bool ALIGN_EPI = false, bool SP2 = false>
; __device__ __forceinline__ void gemm_phase(PG8_LAS unsigned char* lds, const Gemm g, const Sched& S, const Epi& E) {
;     ...
;             PG8_LDB(B0, 0, 0); PG8_LDB(B1, 0, 1); PG8_SCHED; PG8_LDA(At, 0, 0); PG8_STAGE(PG8_SA(1, 1), a1 + hstepA, voffA);
;             PG8_WAIT_V(8); PG8_WAIT_L(0); PG8_BAR; PG8_MMA(0, 0, At, B0); PG8_MMA(0, 1, At, B1); PG8_BAR; PG8_SCHED;
;     ...
;             PG8_LDA(At, 1, 1); PG8_STAGE(PG8_SB(1, 0), b3, voffB); PG8_STAGE(PG8_SB(1, 1), b3 + hstepB, voffB); PG8_STAGE(PG8_SA(1, 0), a3, voffA);
;             PG8_WAIT_V(8); PG8_WAIT_L(0); PG8_BAR; PG8_MMA(1, 0, At, B0); PG8_MMA(1, 1, At, B1); PG8_BAR; PG8_SCHED;
	s_setprio 0
	s_add_i32 s48, s72, s33
	v_lshl_add_u64 v[220:221], v[220:221], 0, s[24:25]
	s_mov_b32 m0, s48
	ds_read_b128 v[188:191], v153 offset:49152
	ds_read_b128 v[192:195], v153 offset:50176
	ds_read_b128 v[196:199], v153 offset:51200
	ds_read_b128 v[200:203], v153 offset:52224
	ds_read_b128 v[204:207], v153 offset:53248
	ds_read_b128 v[208:211], v153 offset:54272
	ds_read_b128 v[212:215], v153 offset:55296
	ds_read_b128 v[216:219], v153 offset:56320
	global_load_lds_dwordx4 v[220:221], off
	s_add_i32 m0, s48, 0x2000
	s_add_u32 s46, s46, 0x40080
	v_lshl_add_u64 v[220:221], v[222:223], 0, s[24:25]
	s_addc_u32 s47, s47, 0
	s_add_i32 s48, s73, s33
	global_load_lds_dwordx4 v[220:221], off
	v_lshl_add_u64 v[220:221], s[46:47], 0, v[126:127]
	s_mov_b32 m0, s48
	s_nop 0
	global_load_lds_dwordx4 v[220:221], off
	v_lshl_add_u64 v[220:221], s[46:47], 0, v[132:133]
	s_add_i32 m0, s48, 0x2000
	s_nop 0
	global_load_lds_dwordx4 v[220:221], off
	v_lshl_add_u64 v[220:221], v[224:225], 0, s[24:25]
	s_mov_b32 m0, s62
	s_nop 0
	global_load_lds_dwordx4 v[220:221], off
	v_lshl_add_u64 v[220:221], v[226:227], 0, s[24:25]
	s_mov_b32 m0, s63
	s_nop 0
	global_load_lds_dwordx4 v[220:221], off
	s_waitcnt vmcnt(8)
	s_waitcnt lgkmcnt(0)
	s_setprio 1
	s_barrier
	v_mfma_f32_16x16x32_bf16 v[62:65], v[154:157], v[188:191], v[62:65]
	v_mfma_f32_16x16x32_bf16 v[58:61], v[162:165], v[188:191], v[58:61]
	v_mfma_f32_16x16x32_bf16 v[54:57], v[154:157], v[196:199], v[54:57]
	v_mfma_f32_16x16x32_bf16 v[46:49], v[162:165], v[196:199], v[46:49]
	v_mfma_f32_16x16x32_bf16 v[38:41], v[154:157], v[204:207], v[38:41]
	v_mfma_f32_16x16x32_bf16 v[30:33], v[162:165], v[204:207], v[30:33]
	v_mfma_f32_16x16x32_bf16 v[14:17], v[154:157], v[212:215], v[14:17]
	v_mfma_f32_16x16x32_bf16 v[10:13], v[162:165], v[212:215], v[10:13]
	v_mfma_f32_16x16x32_bf16 v[62:65], v[158:161], v[192:195], v[62:65]
	v_mfma_f32_16x16x32_bf16 v[58:61], v[166:169], v[192:195], v[58:61]
	v_mfma_f32_16x16x32_bf16 v[54:57], v[158:161], v[200:203], v[54:57]
	v_mfma_f32_16x16x32_bf16 v[46:49], v[166:169], v[200:203], v[46:49]
	v_mfma_f32_16x16x32_bf16 v[38:41], v[158:161], v[208:211], v[38:41]
	v_mfma_f32_16x16x32_bf16 v[30:33], v[166:169], v[208:211], v[30:33]
	v_mfma_f32_16x16x32_bf16 v[14:17], v[158:161], v[216:219], v[14:17]
	v_mfma_f32_16x16x32_bf16 v[10:13], v[166:169], v[216:219], v[10:13]
	v_mfma_f32_16x16x32_bf16 v[50:53], v[172:175], v[188:191], v[50:53]
	v_mfma_f32_16x16x32_bf16 v[42:45], v[180:183], v[188:191], v[42:45]
	v_mfma_f32_16x16x32_bf16 v[34:37], v[172:175], v[196:199], v[34:37]
	v_mfma_f32_16x16x32_bf16 v[26:29], v[180:183], v[196:199], v[26:29]
	v_mfma_f32_16x16x32_bf16 v[22:25], v[172:175], v[204:207], v[22:25]
	v_mfma_f32_16x16x32_bf16 v[18:21], v[180:183], v[204:207], v[18:21]
	v_mfma_f32_16x16x32_bf16 v[6:9], v[172:175], v[212:215], v[6:9]
	v_mfma_f32_16x16x32_bf16 v[2:5], v[180:183], v[212:215], v[2:5]
	v_mfma_f32_16x16x32_bf16 v[50:53], v[176:179], v[192:195], v[50:53]
	v_mfma_f32_16x16x32_bf16 v[42:45], v[184:187], v[192:195], v[42:45]
	v_mfma_f32_16x16x32_bf16 v[34:37], v[176:179], v[200:203], v[34:37]
	v_mfma_f32_16x16x32_bf16 v[26:29], v[184:187], v[200:203], v[26:29]
	v_mfma_f32_16x16x32_bf16 v[22:25], v[176:179], v[208:211], v[22:25]
	v_mfma_f32_16x16x32_bf16 v[18:21], v[184:187], v[208:211], v[18:21]
	v_mfma_f32_16x16x32_bf16 v[6:9], v[176:179], v[216:219], v[6:9]
	v_mfma_f32_16x16x32_bf16 v[2:5], v[184:187], v[216:219], v[2:5]
	s_barrier
	s_setprio 0
	s_add_i32 s71, s71, 2
	s_add_u32 s40, s40, 0x100
	s_addc_u32 s41, s41, 0
	s_cmp_gt_u32 s71, 13
	s_cbranch_scc0 .LBB0_1088
	s_branch .Lph1088_x
.Lph1088_y:
	v_add_u32_e32 v166, s64, v152
	v_add_u32_e32 v171, s65, v152
	s_add_u32 s46, s22, s40
	ds_read_b128 v[154:157], v166
	ds_read_b128 v[158:161], v166 offset:1024
	ds_read_b128 v[162:165], v166 offset:2048
	ds_read_b128 v[166:169], v166 offset:3072
	ds_read_b128 v[172:175], v171
	ds_read_b128 v[176:179], v171 offset:1024
	ds_read_b128 v[180:183], v171 offset:2048
	ds_read_b128 v[184:187], v171 offset:3072
	s_addc_u32 s47, s23, s41
	s_add_u32 s46, s46, 0x100
	s_addc_u32 s47, s47, 0
	s_add_u32 s72, s67, s40
	s_addc_u32 s73, s68, s41
	s_cmpk_eq_i32 s40, 0x700
	s_cselect_b32 s49, s31, s47
	s_cselect_b32 s48, s69, s46
	s_cselect_b32 s47, s29, s73
	s_cselect_b32 s46, s70, s72
	v_lshl_add_u64 v[220:221], v[146:147], 0, s[40:41]
	s_add_i32 m0, s43, 0xc000
	ds_read_b128 v[188:191], v153
	ds_read_b128 v[192:195], v153 offset:1024
	ds_read_b128 v[196:199], v153 offset:2048
	ds_read_b128 v[200:203], v153 offset:3072
	ds_read_b128 v[204:207], v153 offset:4096
	ds_read_b128 v[208:211], v153 offset:5120
	ds_read_b128 v[212:215], v153 offset:6144
	ds_read_b128 v[216:219], v153 offset:7168
	global_load_lds_dwordx4 v[220:221], off
	v_lshl_add_u64 v[220:221], v[148:149], 0, s[40:41]
	s_add_i32 m0, s43, 0xe000
	s_nop 0
	global_load_lds_dwordx4 v[220:221], off
	s_waitcnt vmcnt(8)
	s_waitcnt lgkmcnt(0)
	s_setprio 2
	s_barrier
; #define PG8_STAGE(bufoff, gbase, voff) do { _Pragma("unroll") for (int _i = 0; _i < 2; ++_i) \
;         __builtin_amdgcn_global_load_lds((const unsigned*)((const char*)(gbase) + (voff)[_i]), (PG8_LAS unsigned*)(lds + (bufoff) + ldsw + _i * 8192), 16, 0, 0); } while (0)
; #define PG8_LDA(dst, b, h) do { _Pragma("unroll") for (int m = 0; m < 4; ++m) _Pragma("unroll") for (int k = 0; k < 2; ++k) dst[m][k] = *(const PG8_LAS bf16x8*)(lds + PG8_SA(b, h) + aoff + m * 2048 + k * 1024); } while (0)
; #define PG8_MMA(ai, bj, At, Bt) do { __builtin_amdgcn_s_setprio(1); _Pragma("unroll") for (int m = 0; m < 4; ++m) _Pragma("unroll") for (int n = 0; n < 2; ++n) _Pragma("unroll") for (int k = 0; k < 2; ++k) \
;         acc[ai][bj][m][n] = __builtin_amdgcn_mfma_f32_16x16x32_bf16(Bt[n][k], At[m][k], acc[ai][bj][m][n], 0, 0, 0); __builtin_amdgcn_s_setprio(0); } while (0)
; #define PG8_WAIT_V(n) asm volatile("s_waitcnt vmcnt(" #n ")" ::: "memory")
; #define PG8_WAIT_L(n) asm volatile("s_waitcnt lgkmcnt(" #n ")" ::: "memory")
; #define PG8_BAR __builtin_amdgcn_s_barrier()
; #define PG8_SCHED __builtin_amdgcn_sched_barrier(0)
; template <class Epi, class Sched, bool ALIGN_EPI = false, bool SP2 = false>
; __device__ __forceinline__ void gemm_phase(PG8_LAS unsigned char* lds, const Gemm g, const Sched& S, const Epi& E) {
;     ...
;             PG8_WAIT_V(8); PG8_WAIT_L(0); PG8_BAR; PG8_MMA(0, 0, At, B0); PG8_MMA(0, 1, At, B1); PG8_BAR; PG8_SCHED;
;             PG8_LDA(At, 0, 1); PG8_STAGE(PG8_SB(0, 0), b2, voffB); PG8_STAGE(PG8_SB(0, 1), b2 + hstepB, voffB); PG8_STAGE(PG8_SA(0, 0), a2, voffA);
;             PG8_WAIT_V(8); PG8_WAIT_L(0); PG8_BAR; PG8_MMA(1, 0, At, B0); PG8_MMA(1, 1, At, B1); PG8_BAR; PG8_SCHED;
	v_mfma_f32_16x16x32_bf16 v[122:125], v[154:157], v[188:191], v[122:125]
	v_mfma_f32_16x16x32_bf16 v[118:121], v[162:165], v[188:191], v[118:121]
	v_mfma_f32_16x16x32_bf16 v[114:117], v[154:157], v[196:199], v[114:117]
	v_mfma_f32_16x16x32_bf16 v[98:101], v[162:165], v[196:199], v[98:101]
	v_mfma_f32_16x16x32_bf16 v[134:137], v[154:157], v[204:207], v[134:137]
	v_mfma_f32_16x16x32_bf16 v[102:105], v[162:165], v[204:207], v[102:105]
	v_mfma_f32_16x16x32_bf16 v[110:113], v[154:157], v[212:215], v[110:113]
	v_mfma_f32_16x16x32_bf16 v[86:89], v[162:165], v[212:215], v[86:89]
	v_mfma_f32_16x16x32_bf16 v[122:125], v[158:161], v[192:195], v[122:125]
	v_mfma_f32_16x16x32_bf16 v[118:121], v[166:169], v[192:195], v[118:121]
	v_mfma_f32_16x16x32_bf16 v[114:117], v[158:161], v[200:203], v[114:117]
	v_mfma_f32_16x16x32_bf16 v[98:101], v[166:169], v[200:203], v[98:101]
	v_mfma_f32_16x16x32_bf16 v[134:137], v[158:161], v[208:211], v[134:137]
	v_mfma_f32_16x16x32_bf16 v[102:105], v[166:169], v[208:211], v[102:105]
	v_mfma_f32_16x16x32_bf16 v[110:113], v[158:161], v[216:219], v[110:113]
	v_mfma_f32_16x16x32_bf16 v[86:89], v[166:169], v[216:219], v[86:89]
	v_mfma_f32_16x16x32_bf16 v[106:109], v[172:175], v[188:191], v[106:109]
	v_mfma_f32_16x16x32_bf16 v[94:97], v[180:183], v[188:191], v[94:97]
	v_mfma_f32_16x16x32_bf16 v[90:93], v[172:175], v[196:199], v[90:93]
	v_mfma_f32_16x16x32_bf16 v[82:85], v[180:183], v[196:199], v[82:85]
	v_mfma_f32_16x16x32_bf16 v[78:81], v[172:175], v[204:207], v[78:81]
	v_mfma_f32_16x16x32_bf16 v[74:77], v[180:183], v[204:207], v[74:77]
	v_mfma_f32_16x16x32_bf16 v[70:73], v[172:175], v[212:215], v[70:73]
	v_mfma_f32_16x16x32_bf16 v[66:69], v[180:183], v[212:215], v[66:69]
	v_mfma_f32_16x16x32_bf16 v[106:109], v[176:179], v[192:195], v[106:109]
	v_mfma_f32_16x16x32_bf16 v[94:97], v[184:187], v[192:195], v[94:97]
	v_mfma_f32_16x16x32_bf16 v[90:93], v[176:179], v[200:203], v[90:93]
	v_mfma_f32_16x16x32_bf16 v[82:85], v[184:187], v[200:203], v[82:85]
	v_mfma_f32_16x16x32_bf16 v[78:81], v[176:179], v[208:211], v[78:81]
	v_mfma_f32_16x16x32_bf16 v[74:77], v[184:187], v[208:211], v[74:77]
	v_mfma_f32_16x16x32_bf16 v[70:73], v[176:179], v[216:219], v[70:73]
	v_mfma_f32_16x16x32_bf16 v[66:69], v[184:187], v[216:219], v[66:69]
	s_barrier
	s_setprio 1
	s_add_i32 s72, s64, s33
	v_lshl_add_u64 v[220:221], s[46:47], 0, v[126:127]
	s_mov_b32 m0, s72
	ds_read_b128 v[188:191], v153 offset:16384
	ds_read_b128 v[192:195], v153 offset:17408
	ds_read_b128 v[196:199], v153 offset:18432
	ds_read_b128 v[200:203], v153 offset:19456
	ds_read_b128 v[204:207], v153 offset:20480
	ds_read_b128 v[208:211], v153 offset:21504
	ds_read_b128 v[212:215], v153 offset:22528
	ds_read_b128 v[216:219], v153 offset:23552
	global_load_lds_dwordx4 v[220:221], off
	s_add_i32 m0, s72, 0x2000
	s_add_u32 s72, s46, 0x40000
	v_lshl_add_u64 v[222:223], s[46:47], 0, v[132:133]
	s_addc_u32 s73, s47, 0
	s_add_i32 s74, s65, s33
	global_load_lds_dwordx4 v[222:223], off
	v_lshl_add_u64 v[224:225], s[72:73], 0, v[126:127]
	s_mov_b32 m0, s74
	v_lshl_add_u64 v[226:227], s[48:49], 0, v[130:131]
	global_load_lds_dwordx4 v[224:225], off
	v_lshl_add_u64 v[224:225], s[72:73], 0, v[132:133]
	s_add_i32 m0, s74, 0x2000
	s_nop 0
	global_load_lds_dwordx4 v[224:225], off
	v_lshl_add_u64 v[224:225], s[48:49], 0, v[128:129]
	s_mov_b32 m0, s43
	s_nop 0
	global_load_lds_dwordx4 v[224:225], off
	s_mov_b32 m0, s44
	s_nop 0
	global_load_lds_dwordx4 v[226:227], off
	s_waitcnt vmcnt(8)
	s_waitcnt lgkmcnt(0)
	s_setprio 2
	s_barrier
	v_mfma_f32_16x16x32_bf16 v[62:65], v[154:157], v[188:191], v[62:65]
	v_mfma_f32_16x16x32_bf16 v[58:61], v[162:165], v[188:191], v[58:61]
	v_mfma_f32_16x16x32_bf16 v[54:57], v[154:157], v[196:199], v[54:57]
	v_mfma_f32_16x16x32_bf16 v[46:49], v[162:165], v[196:199], v[46:49]
	v_mfma_f32_16x16x32_bf16 v[38:41], v[154:157], v[204:207], v[38:41]
	v_mfma_f32_16x16x32_bf16 v[30:33], v[162:165], v[204:207], v[30:33]
	v_mfma_f32_16x16x32_bf16 v[14:17], v[154:157], v[212:215], v[14:17]
	v_mfma_f32_16x16x32_bf16 v[10:13], v[162:165], v[212:215], v[10:13]
	v_mfma_f32_16x16x32_bf16 v[62:65], v[158:161], v[192:195], v[62:65]
	v_mfma_f32_16x16x32_bf16 v[58:61], v[166:169], v[192:195], v[58:61]
	v_mfma_f32_16x16x32_bf16 v[54:57], v[158:161], v[200:203], v[54:57]
	v_mfma_f32_16x16x32_bf16 v[46:49], v[166:169], v[200:203], v[46:49]
	v_mfma_f32_16x16x32_bf16 v[38:41], v[158:161], v[208:211], v[38:41]
	v_mfma_f32_16x16x32_bf16 v[30:33], v[166:169], v[208:211], v[30:33]
	v_mfma_f32_16x16x32_bf16 v[14:17], v[158:161], v[216:219], v[14:17]
	v_mfma_f32_16x16x32_bf16 v[10:13], v[166:169], v[216:219], v[10:13]
	v_mfma_f32_16x16x32_bf16 v[50:53], v[172:175], v[188:191], v[50:53]
	v_mfma_f32_16x16x32_bf16 v[42:45], v[180:183], v[188:191], v[42:45]
	v_mfma_f32_16x16x32_bf16 v[34:37], v[172:175], v[196:199], v[34:37]
	v_mfma_f32_16x16x32_bf16 v[26:29], v[180:183], v[196:199], v[26:29]
	v_mfma_f32_16x16x32_bf16 v[22:25], v[172:175], v[204:207], v[22:25]
	v_mfma_f32_16x16x32_bf16 v[18:21], v[180:183], v[204:207], v[18:21]
	v_mfma_f32_16x16x32_bf16 v[6:9], v[172:175], v[212:215], v[6:9]
	v_mfma_f32_16x16x32_bf16 v[2:5], v[180:183], v[212:215], v[2:5]
	v_mfma_f32_16x16x32_bf16 v[50:53], v[176:179], v[192:195], v[50:53]
	v_mfma_f32_16x16x32_bf16 v[42:45], v[184:187], v[192:195], v[42:45]
	v_mfma_f32_16x16x32_bf16 v[34:37], v[176:179], v[200:203], v[34:37]
	v_mfma_f32_16x16x32_bf16 v[26:29], v[184:187], v[200:203], v[26:29]
	v_mfma_f32_16x16x32_bf16 v[22:25], v[176:179], v[208:211], v[22:25]
	v_mfma_f32_16x16x32_bf16 v[18:21], v[184:187], v[208:211], v[18:21]
	v_mfma_f32_16x16x32_bf16 v[6:9], v[176:179], v[216:219], v[6:9]
	v_mfma_f32_16x16x32_bf16 v[2:5], v[184:187], v[216:219], v[2:5]
	s_barrier
; #define PG8_STAGE(bufoff, gbase, voff) do { _Pragma("unroll") for (int _i = 0; _i < 2; ++_i) \
;         __builtin_amdgcn_global_load_lds((const unsigned*)((const char*)(gbase) + (voff)[_i]), (PG8_LAS unsigned*)(lds + (bufoff) + ldsw + _i * 8192), 16, 0, 0); } while (0)
; #define PG8_LDA(dst, b, h) do { _Pragma("unroll") for (int m = 0; m < 4; ++m) _Pragma("unroll") for (int k = 0; k < 2; ++k) dst[m][k] = *(const PG8_LAS bf16x8*)(lds + PG8_SA(b, h) + aoff + m * 2048 + k * 1024); } while (0)
; #define PG8_LDB(dst, b, h) do { _Pragma("unroll") for (int n = 0; n < 2; ++n) _Pragma("unroll") for (int k = 0; k < 2; ++k) dst[n][k] = *(const PG8_LAS bf16x8*)(lds + PG8_SB(b, h) + boff + n * 2048 + k * 1024); } while (0)
; #define PG8_MMA(ai, bj, At, Bt) do { __builtin_amdgcn_s_setprio(1); _Pragma("unroll") for (int m = 0; m < 4; ++m) _Pragma("unroll") for (int n = 0; n < 2; ++n) _Pragma("unroll") for (int k = 0; k < 2; ++k) \
;         acc[ai][bj][m][n] = __builtin_amdgcn_mfma_f32_16x16x32_bf16(Bt[n][k], At[m][k], acc[ai][bj][m][n], 0, 0, 0); __builtin_amdgcn_s_setprio(0); } while (0)
; #define PG8_WAIT_V(n) asm volatile("s_waitcnt vmcnt(" #n ")" ::: "memory")
; #define PG8_WAIT_L(n) asm volatile("s_waitcnt lgkmcnt(" #n ")" ::: "memory")
; #define PG8_BAR __builtin_amdgcn_s_barrier()
; #define PG8_SCHED __builtin_amdgcn_sched_barrier(0)
; template <class Epi, class Sched, bool ALIGN_EPI = false, bool SP2 = false>
; __device__ __forceinline__ void gemm_phase(PG8_LAS unsigned char* lds, const Gemm g, const Sched& S, const Epi& E) {
;     ...
;             PG8_LDB(B0, 1, 0); PG8_LDB(B1, 1, 1); PG8_SCHED; PG8_LDA(At, 1, 0); PG8_STAGE(PG8_SA(0, 1), a2 + hstepA, voffA);
;             PG8_WAIT_V(8); PG8_WAIT_L(0); PG8_BAR; PG8_MMA(0, 0, At, B0); PG8_MMA(0, 1, At, B1); PG8_BAR; PG8_SCHED;
;             PG8_LDA(At, 1, 1); PG8_STAGE(PG8_SB(1, 0), b3, voffB); PG8_STAGE(PG8_SB(1, 1), b3 + hstepB, voffB); PG8_STAGE(PG8_SA(1, 0), a3, voffA);
;             PG8_WAIT_V(8); PG8_WAIT_L(0); PG8_BAR; PG8_MMA(1, 0, At, B0); PG8_MMA(1, 1, At, B1); PG8_BAR; PG8_SCHED;
	s_setprio 1
	s_add_i32 s72, 0, 0x18000
	s_add_i32 s73, 0, 0x1c000
	v_add_u32_e32 v166, s72, v152
	v_add_u32_e32 v171, s73, v152
	ds_read_b128 v[154:157], v166
	ds_read_b128 v[158:161], v166 offset:1024
	ds_read_b128 v[162:165], v166 offset:2048
	ds_read_b128 v[166:169], v166 offset:3072
	ds_read_b128 v[172:175], v171
	ds_read_b128 v[176:179], v171 offset:1024
	ds_read_b128 v[180:183], v171 offset:2048
	ds_read_b128 v[184:187], v171 offset:3072
	s_add_u32 s48, s48, 0x40000
	s_addc_u32 s49, s49, 0
	s_mov_b32 m0, s45
	v_lshl_add_u64 v[228:229], s[48:49], 0, v[128:129]
	ds_read_b128 v[188:191], v153 offset:32768
	ds_read_b128 v[192:195], v153 offset:33792
	ds_read_b128 v[196:199], v153 offset:34816
	ds_read_b128 v[200:203], v153 offset:35840
	ds_read_b128 v[204:207], v153 offset:36864
	ds_read_b128 v[208:211], v153 offset:37888
	ds_read_b128 v[212:215], v153 offset:38912
	ds_read_b128 v[216:219], v153 offset:39936
	global_load_lds_dwordx4 v[228:229], off
	v_lshl_add_u64 v[228:229], s[48:49], 0, v[130:131]
	s_mov_b32 m0, s50
	s_nop 0
	global_load_lds_dwordx4 v[228:229], off
	s_waitcnt vmcnt(8)
	s_waitcnt lgkmcnt(0)
	s_setprio 2
	s_barrier
	v_mfma_f32_16x16x32_bf16 v[122:125], v[154:157], v[188:191], v[122:125]
	v_mfma_f32_16x16x32_bf16 v[118:121], v[162:165], v[188:191], v[118:121]
	v_mfma_f32_16x16x32_bf16 v[114:117], v[154:157], v[196:199], v[114:117]
	v_mfma_f32_16x16x32_bf16 v[98:101], v[162:165], v[196:199], v[98:101]
	v_mfma_f32_16x16x32_bf16 v[134:137], v[154:157], v[204:207], v[134:137]
	v_mfma_f32_16x16x32_bf16 v[102:105], v[162:165], v[204:207], v[102:105]
	v_mfma_f32_16x16x32_bf16 v[110:113], v[154:157], v[212:215], v[110:113]
	v_mfma_f32_16x16x32_bf16 v[86:89], v[162:165], v[212:215], v[86:89]
	v_mfma_f32_16x16x32_bf16 v[122:125], v[158:161], v[192:195], v[122:125]
	v_mfma_f32_16x16x32_bf16 v[118:121], v[166:169], v[192:195], v[118:121]
	v_mfma_f32_16x16x32_bf16 v[114:117], v[158:161], v[200:203], v[114:117]
	v_mfma_f32_16x16x32_bf16 v[98:101], v[166:169], v[200:203], v[98:101]
	v_mfma_f32_16x16x32_bf16 v[134:137], v[158:161], v[208:211], v[134:137]
	v_mfma_f32_16x16x32_bf16 v[102:105], v[166:169], v[208:211], v[102:105]
	v_mfma_f32_16x16x32_bf16 v[110:113], v[158:161], v[216:219], v[110:113]
	v_mfma_f32_16x16x32_bf16 v[86:89], v[166:169], v[216:219], v[86:89]
	v_mfma_f32_16x16x32_bf16 v[106:109], v[172:175], v[188:191], v[106:109]
	v_mfma_f32_16x16x32_bf16 v[94:97], v[180:183], v[188:191], v[94:97]
	v_mfma_f32_16x16x32_bf16 v[90:93], v[172:175], v[196:199], v[90:93]
	v_mfma_f32_16x16x32_bf16 v[82:85], v[180:183], v[196:199], v[82:85]
	v_mfma_f32_16x16x32_bf16 v[78:81], v[172:175], v[204:207], v[78:81]
	v_mfma_f32_16x16x32_bf16 v[74:77], v[180:183], v[204:207], v[74:77]
	v_mfma_f32_16x16x32_bf16 v[70:73], v[172:175], v[212:215], v[70:73]
	v_mfma_f32_16x16x32_bf16 v[66:69], v[180:183], v[212:215], v[66:69]
	v_mfma_f32_16x16x32_bf16 v[106:109], v[176:179], v[192:195], v[106:109]
	v_mfma_f32_16x16x32_bf16 v[94:97], v[184:187], v[192:195], v[94:97]
	v_mfma_f32_16x16x32_bf16 v[90:93], v[176:179], v[200:203], v[90:93]
	v_mfma_f32_16x16x32_bf16 v[82:85], v[184:187], v[200:203], v[82:85]
	v_mfma_f32_16x16x32_bf16 v[78:81], v[176:179], v[208:211], v[78:81]
	v_mfma_f32_16x16x32_bf16 v[74:77], v[184:187], v[208:211], v[74:77]
	v_mfma_f32_16x16x32_bf16 v[70:73], v[176:179], v[216:219], v[70:73]
	v_mfma_f32_16x16x32_bf16 v[66:69], v[184:187], v[216:219], v[66:69]
	s_barrier
	s_setprio 1
	s_add_i32 s48, s72, s33
	v_lshl_add_u64 v[220:221], v[220:221], 0, s[24:25]
	s_mov_b32 m0, s48
	ds_read_b128 v[188:191], v153 offset:49152
	ds_read_b128 v[192:195], v153 offset:50176
	ds_read_b128 v[196:199], v153 offset:51200
	ds_read_b128 v[200:203], v153 offset:52224
	ds_read_b128 v[204:207], v153 offset:53248
	ds_read_b128 v[208:211], v153 offset:54272
	ds_read_b128 v[212:215], v153 offset:55296
	ds_read_b128 v[216:219], v153 offset:56320
	global_load_lds_dwordx4 v[220:221], off
	s_add_i32 m0, s48, 0x2000
	s_add_u32 s46, s46, 0x40080
	v_lshl_add_u64 v[220:221], v[222:223], 0, s[24:25]
	s_addc_u32 s47, s47, 0
	s_add_i32 s48, s73, s33
	global_load_lds_dwordx4 v[220:221], off
	v_lshl_add_u64 v[220:221], s[46:47], 0, v[126:127]
	s_mov_b32 m0, s48
	s_nop 0
	global_load_lds_dwordx4 v[220:221], off
	v_lshl_add_u64 v[220:221], s[46:47], 0, v[132:133]
	s_add_i32 m0, s48, 0x2000
	s_nop 0
	global_load_lds_dwordx4 v[220:221], off
	v_lshl_add_u64 v[220:221], v[224:225], 0, s[24:25]
	s_mov_b32 m0, s62
	s_nop 0
	global_load_lds_dwordx4 v[220:221], off
	v_lshl_add_u64 v[220:221], v[226:227], 0, s[24:25]
	s_mov_b32 m0, s63
	s_nop 0
	global_load_lds_dwordx4 v[220:221], off
	s_waitcnt vmcnt(8)
	s_waitcnt lgkmcnt(0)
	s_setprio 2
	s_barrier
	v_mfma_f32_16x16x32_bf16 v[62:65], v[154:157], v[188:191], v[62:65]
	v_mfma_f32_16x16x32_bf16 v[58:61], v[162:165], v[188:191], v[58:61]
	v_mfma_f32_16x16x32_bf16 v[54:57], v[154:157], v[196:199], v[54:57]
	v_mfma_f32_16x16x32_bf16 v[46:49], v[162:165], v[196:199], v[46:49]
	v_mfma_f32_16x16x32_bf16 v[38:41], v[154:157], v[204:207], v[38:41]
	v_mfma_f32_16x16x32_bf16 v[30:33], v[162:165], v[204:207], v[30:33]
	v_mfma_f32_16x16x32_bf16 v[14:17], v[154:157], v[212:215], v[14:17]
	v_mfma_f32_16x16x32_bf16 v[10:13], v[162:165], v[212:215], v[10:13]
	v_mfma_f32_16x16x32_bf16 v[62:65], v[158:161], v[192:195], v[62:65]
	v_mfma_f32_16x16x32_bf16 v[58:61], v[166:169], v[192:195], v[58:61]
	v_mfma_f32_16x16x32_bf16 v[54:57], v[158:161], v[200:203], v[54:57]
	v_mfma_f32_16x16x32_bf16 v[46:49], v[166:169], v[200:203], v[46:49]
	v_mfma_f32_16x16x32_bf16 v[38:41], v[158:161], v[208:211], v[38:41]
	v_mfma_f32_16x16x32_bf16 v[30:33], v[166:169], v[208:211], v[30:33]
	v_mfma_f32_16x16x32_bf16 v[14:17], v[158:161], v[216:219], v[14:17]
	v_mfma_f32_16x16x32_bf16 v[10:13], v[166:169], v[216:219], v[10:13]
	v_mfma_f32_16x16x32_bf16 v[50:53], v[172:175], v[188:191], v[50:53]
	v_mfma_f32_16x16x32_bf16 v[42:45], v[180:183], v[188:191], v[42:45]
	v_mfma_f32_16x16x32_bf16 v[34:37], v[172:175], v[196:199], v[34:37]
	v_mfma_f32_16x16x32_bf16 v[26:29], v[180:183], v[196:199], v[26:29]
	v_mfma_f32_16x16x32_bf16 v[22:25], v[172:175], v[204:207], v[22:25]
	v_mfma_f32_16x16x32_bf16 v[18:21], v[180:183], v[204:207], v[18:21]
	v_mfma_f32_16x16x32_bf16 v[6:9], v[172:175], v[212:215], v[6:9]
	v_mfma_f32_16x16x32_bf16 v[2:5], v[180:183], v[212:215], v[2:5]
	v_mfma_f32_16x16x32_bf16 v[50:53], v[176:179], v[192:195], v[50:53]
	v_mfma_f32_16x16x32_bf16 v[42:45], v[184:187], v[192:195], v[42:45]
	v_mfma_f32_16x16x32_bf16 v[34:37], v[176:179], v[200:203], v[34:37]
	v_mfma_f32_16x16x32_bf16 v[26:29], v[184:187], v[200:203], v[26:29]
	v_mfma_f32_16x16x32_bf16 v[22:25], v[176:179], v[208:211], v[22:25]
	v_mfma_f32_16x16x32_bf16 v[18:21], v[184:187], v[208:211], v[18:21]
	v_mfma_f32_16x16x32_bf16 v[6:9], v[176:179], v[216:219], v[6:9]
	v_mfma_f32_16x16x32_bf16 v[2:5], v[184:187], v[216:219], v[2:5]
	s_barrier
	s_setprio 1
	s_add_i32 s71, s71, 2
	s_add_u32 s40, s40, 0x100
	s_addc_u32 s41, s41, 0
	s_cmp_gt_u32 s71, 13
	s_cbranch_scc0 .Lph1088_y
	s_setprio 0

;     __host__ __device__ bool next(int i, Unit& u) const { if (!so.next(i >> 1, u)) return false; u.k0 = (i & 1) * 512; return true; }
;     __host__ __device__ bool next(int i, Unit& u) const { if (!so.next(i, u)) return false; u.pe = main_tile(u.pn); return true; }
;     __host__ __device__ bool next(int i, Unit& u) const { if (start + i * stride >= limit) return false; if (!so.next(i, u)) return false; u.pe = late_tile(u.pn); return true; }
; template <class Epi, class Sched, bool ALIGN_EPI = false, bool SP2 = false>
; __device__ __forceinline__ void gemm_phase(PG8_LAS unsigned char* lds, const Gemm g, const Sched& S, const Epi& E) {
;     ...
;         const bool has_next = S.next(ui + 1, nxt);
;         const char* nA = has_next ? (const char*)g.A + (size_t)nxt.pm * tstepA + (size_t)nxt.k0 * 2 : cA; const char* nB = has_next ? (const char*)g.Bt + (size_t)nxt.pn * tstepB + (size_t)nxt.k0 * 2 : cB;
;     ...
;         if (!keep_) {
; #pragma unroll
;         for (int a = 0; a < 2; ++a)
; #pragma unroll
;             for (int b = 0; b < 2; ++b)
; #pragma unroll
;                 for (int m = 0; m < 4; ++m)
; #pragma unroll
;                     for (int n = 0; n < 2; ++n) acc[a][b][m][n] = (f32x4){0.f, 0.f, 0.f, 0.f};
.LBB0_1243:
	s_ashr_i32 s19, s18, 31
	s_lshl_b64 s[22:23], s[18:19], 19
	s_add_u32 s22, s20, s22
	s_addc_u32 s23, s21, s23
	s_and_b64 s[24:25], s[0:1], exec
	s_cselect_b32 s19, s23, s31
	s_cselect_b32 s51, s22, s30
	s_ashr_i32 s17, s16, 31
	s_lshl_b64 s[24:25], s[16:17], 19
	s_add_u32 s24, s14, s24
	s_addc_u32 s25, s15, s25
	s_and_b64 s[38:39], s[0:1], exec
	s_cselect_b32 s17, s25, s37
	s_cselect_b32 s62, s24, s36
	s_add_u32 s30, s30, 0x40080
	s_addc_u32 s31, s31, 0
	s_add_u32 s63, s36, 0x100
	v_mov_b32_e32 v2, 0
	s_addc_u32 s64, s37, 0
	s_mov_b32 s65, -2
	v_mov_b32_e32 v3, v2
	v_mov_b32_e32 v4, v2
	v_mov_b32_e32 v5, v2
	v_mov_b32_e32 v6, v2
	v_mov_b32_e32 v7, v2
	v_mov_b32_e32 v8, v2
	v_mov_b32_e32 v9, v2
	v_mov_b32_e32 v18, v2
	v_mov_b32_e32 v19, v2
	v_mov_b32_e32 v20, v2
	v_mov_b32_e32 v21, v2
	v_mov_b32_e32 v22, v2
	v_mov_b32_e32 v23, v2
	v_mov_b32_e32 v24, v2
	v_mov_b32_e32 v25, v2
	v_mov_b32_e32 v34, v2
	v_mov_b32_e32 v35, v2
	v_mov_b32_e32 v36, v2
	v_mov_b32_e32 v37, v2
	v_mov_b32_e32 v38, v2
	v_mov_b32_e32 v39, v2
	v_mov_b32_e32 v40, v2
	v_mov_b32_e32 v41, v2
	v_mov_b32_e32 v50, v2
	v_mov_b32_e32 v51, v2
	v_mov_b32_e32 v52, v2
	v_mov_b32_e32 v53, v2
	v_mov_b32_e32 v54, v2
	v_mov_b32_e32 v55, v2
	v_mov_b32_e32 v56, v2
	v_mov_b32_e32 v57, v2
	v_mov_b32_e32 v10, v2
	v_mov_b32_e32 v11, v2
	v_mov_b32_e32 v12, v2
	v_mov_b32_e32 v13, v2
	v_mov_b32_e32 v14, v2
	v_mov_b32_e32 v15, v2
	v_mov_b32_e32 v16, v2
	v_mov_b32_e32 v17, v2
	v_mov_b32_e32 v26, v2
	v_mov_b32_e32 v27, v2
	v_mov_b32_e32 v28, v2
	v_mov_b32_e32 v29, v2
	v_mov_b32_e32 v30, v2
	v_mov_b32_e32 v31, v2
	v_mov_b32_e32 v32, v2
	v_mov_b32_e32 v33, v2
	v_mov_b32_e32 v42, v2
	v_mov_b32_e32 v43, v2
	v_mov_b32_e32 v44, v2
	v_mov_b32_e32 v45, v2
	v_mov_b32_e32 v46, v2
	v_mov_b32_e32 v47, v2
	v_mov_b32_e32 v48, v2
	v_mov_b32_e32 v49, v2
	v_mov_b32_e32 v58, v2
	v_mov_b32_e32 v59, v2
	v_mov_b32_e32 v60, v2
	v_mov_b32_e32 v61, v2
	v_mov_b32_e32 v62, v2
	v_mov_b32_e32 v63, v2
	v_mov_b32_e32 v64, v2
	v_mov_b32_e32 v65, v2
	v_mov_b32_e32 v66, v2
	v_mov_b32_e32 v67, v2
	v_mov_b32_e32 v68, v2
	v_mov_b32_e32 v69, v2
	v_mov_b32_e32 v70, v2
	v_mov_b32_e32 v71, v2
	v_mov_b32_e32 v72, v2
	v_mov_b32_e32 v73, v2
	v_mov_b32_e32 v82, v2
	v_mov_b32_e32 v83, v2
	v_mov_b32_e32 v84, v2
	v_mov_b32_e32 v85, v2
	v_mov_b32_e32 v86, v2
	v_mov_b32_e32 v87, v2
	v_mov_b32_e32 v88, v2
	v_mov_b32_e32 v89, v2
	v_mov_b32_e32 v98, v2
	v_mov_b32_e32 v99, v2
	v_mov_b32_e32 v100, v2
	v_mov_b32_e32 v101, v2
	v_mov_b32_e32 v102, v2
	v_mov_b32_e32 v103, v2
	v_mov_b32_e32 v104, v2
	v_mov_b32_e32 v105, v2
	v_mov_b32_e32 v114, v2
	v_mov_b32_e32 v115, v2
	v_mov_b32_e32 v116, v2
	v_mov_b32_e32 v117, v2
	v_mov_b32_e32 v118, v2
	v_mov_b32_e32 v119, v2
	v_mov_b32_e32 v120, v2
	v_mov_b32_e32 v121, v2
	v_mov_b32_e32 v74, v2
	v_mov_b32_e32 v75, v2
	v_mov_b32_e32 v76, v2
	v_mov_b32_e32 v77, v2
	v_mov_b32_e32 v78, v2
	v_mov_b32_e32 v79, v2
	v_mov_b32_e32 v80, v2
	v_mov_b32_e32 v81, v2
	v_mov_b32_e32 v90, v2
	v_mov_b32_e32 v91, v2
	v_mov_b32_e32 v92, v2
	v_mov_b32_e32 v93, v2
	v_mov_b32_e32 v94, v2
	v_mov_b32_e32 v95, v2
	v_mov_b32_e32 v96, v2
	v_mov_b32_e32 v97, v2
	v_mov_b32_e32 v106, v2
	v_mov_b32_e32 v107, v2
	v_mov_b32_e32 v108, v2
	v_mov_b32_e32 v109, v2
	v_mov_b32_e32 v110, v2
	v_mov_b32_e32 v111, v2
	v_mov_b32_e32 v112, v2
	v_mov_b32_e32 v113, v2
	v_mov_b32_e32 v122, v2
	v_mov_b32_e32 v123, v2
	v_mov_b32_e32 v124, v2
	v_mov_b32_e32 v125, v2
	v_mov_b32_e32 v126, v2
	v_mov_b32_e32 v127, v2
	v_mov_b32_e32 v128, v2
	v_mov_b32_e32 v129, v2
	s_cmp_lg_u32 s101, 0
	s_cbranch_scc1 .Lph1244_y

; #define PG8_STAGE(bufoff, gbase, voff) do { _Pragma("unroll") for (int _i = 0; _i < 2; ++_i) \
;         __builtin_amdgcn_global_load_lds((const unsigned*)((const char*)(gbase) + (voff)[_i]), (PG8_LAS unsigned*)(lds + (bufoff) + ldsw + _i * 8192), 16, 0, 0); } while (0)
; #define PG8_LDA(dst, b, h) do { _Pragma("unroll") for (int m = 0; m < 4; ++m) _Pragma("unroll") for (int k = 0; k < 2; ++k) dst[m][k] = *(const PG8_LAS bf16x8*)(lds + PG8_SA(b, h) + aoff + m * 2048 + k * 1024); } while (0)
; #define PG8_LDB(dst, b, h) do { _Pragma("unroll") for (int n = 0; n < 2; ++n) _Pragma("unroll") for (int k = 0; k < 2; ++k) dst[n][k] = *(const PG8_LAS bf16x8*)(lds + PG8_SB(b, h) + boff + n * 2048 + k * 1024); } while (0)
; #define PG8_MMA(ai, bj, At, Bt) do { __builtin_amdgcn_s_setprio(1); _Pragma("unroll") for (int m = 0; m < 4; ++m) _Pragma("unroll") for (int n = 0; n < 2; ++n) _Pragma("unroll") for (int k = 0; k < 2; ++k) \
;         acc[ai][bj][m][n] = __builtin_amdgcn_mfma_f32_16x16x32_bf16(Bt[n][k], At[m][k], acc[ai][bj][m][n], 0, 0, 0); __builtin_amdgcn_s_setprio(0); } while (0)
; #define PG8_WAIT_V(n) asm volatile("s_waitcnt vmcnt(" #n ")" ::: "memory")
; #define PG8_WAIT_L(n) asm volatile("s_waitcnt lgkmcnt(" #n ")" ::: "memory")
; #define PG8_BAR __builtin_amdgcn_s_barrier()
; #define PG8_SCHED __builtin_amdgcn_sched_barrier(0)
; template <class Epi, class Sched, bool ALIGN_EPI = false, bool SP2 = false>
; __device__ __forceinline__ void gemm_phase(PG8_LAS unsigned char* lds, const Gemm g, const Sched& S, const Epi& E) {
;     ...
;             PG8_LDB(B0, 0, 0); PG8_LDB(B1, 0, 1); PG8_SCHED; PG8_LDA(At, 0, 0); PG8_STAGE(PG8_SA(1, 1), a1 + hstepA, voffA);
;             PG8_WAIT_V(8); PG8_WAIT_L(0); PG8_BAR; PG8_MMA(0, 0, At, B0); PG8_MMA(0, 1, At, B1); PG8_BAR; PG8_SCHED;
;             PG8_LDA(At, 0, 1); PG8_STAGE(PG8_SB(0, 0), b2, voffB); PG8_STAGE(PG8_SB(0, 1), b2 + hstepB, voffB); PG8_STAGE(PG8_SA(0, 0), a2, voffA);
;             PG8_WAIT_V(8); PG8_WAIT_L(0); PG8_BAR; PG8_MMA(1, 0, At, B0); PG8_MMA(1, 1, At, B1); PG8_BAR; PG8_SCHED;
.Lph1244_y:
	ds_read_b128 v[158:161], v154
	ds_read_b128 v[162:165], v154 offset:1024
	ds_read_b128 v[166:169], v154 offset:2048
	ds_read_b128 v[170:173], v154 offset:3072
	ds_read_b128 v[174:177], v155
	ds_read_b128 v[178:181], v155 offset:1024
	ds_read_b128 v[182:185], v155 offset:2048
	ds_read_b128 v[186:189], v155 offset:3072
	s_add_u32 s36, s30, 0xfffc0080
	s_addc_u32 s37, s31, -1
	s_cmp_eq_u32 s65, 12
	s_cselect_b32 s39, s19, s37
	s_cselect_b32 s38, s51, s36
	s_cselect_b32 s37, s17, s64
	s_cselect_b32 s36, s62, s63
	v_lshl_add_u64 v[222:223], s[30:31], 0, v[146:147]
	s_add_i32 m0, s33, 0xc000
	ds_read_b128 v[190:193], v156
	ds_read_b128 v[194:197], v156 offset:1024
	ds_read_b128 v[198:201], v156 offset:2048
	ds_read_b128 v[202:205], v156 offset:3072
	ds_read_b128 v[206:209], v156 offset:4096
	ds_read_b128 v[210:213], v156 offset:5120
	ds_read_b128 v[214:217], v156 offset:6144
	ds_read_b128 v[218:221], v156 offset:7168
	global_load_lds_dwordx4 v[222:223], off
	v_lshl_add_u64 v[222:223], s[30:31], 0, v[148:149]
	s_add_i32 m0, s33, 0xe000
	s_nop 0
	global_load_lds_dwordx4 v[222:223], off
	s_waitcnt vmcnt(8)
	s_waitcnt lgkmcnt(0)
	s_setprio 2
	s_barrier
	v_mfma_f32_16x16x32_bf16 v[126:129], v[158:161], v[190:193], v[126:129]
	v_mfma_f32_16x16x32_bf16 v[122:125], v[166:169], v[190:193], v[122:125]
	v_mfma_f32_16x16x32_bf16 v[110:113], v[158:161], v[198:201], v[110:113]
	v_mfma_f32_16x16x32_bf16 v[106:109], v[166:169], v[198:201], v[106:109]
	v_mfma_f32_16x16x32_bf16 v[94:97], v[158:161], v[206:209], v[94:97]
	v_mfma_f32_16x16x32_bf16 v[90:93], v[166:169], v[206:209], v[90:93]
	v_mfma_f32_16x16x32_bf16 v[78:81], v[158:161], v[214:217], v[78:81]
	v_mfma_f32_16x16x32_bf16 v[74:77], v[166:169], v[214:217], v[74:77]
	v_mfma_f32_16x16x32_bf16 v[126:129], v[162:165], v[194:197], v[126:129]
	v_mfma_f32_16x16x32_bf16 v[122:125], v[170:173], v[194:197], v[122:125]
	v_mfma_f32_16x16x32_bf16 v[110:113], v[162:165], v[202:205], v[110:113]
	v_mfma_f32_16x16x32_bf16 v[106:109], v[170:173], v[202:205], v[106:109]
	v_mfma_f32_16x16x32_bf16 v[94:97], v[162:165], v[210:213], v[94:97]
	v_mfma_f32_16x16x32_bf16 v[90:93], v[170:173], v[210:213], v[90:93]
	v_mfma_f32_16x16x32_bf16 v[78:81], v[162:165], v[218:221], v[78:81]
	v_mfma_f32_16x16x32_bf16 v[74:77], v[170:173], v[218:221], v[74:77]
	v_mfma_f32_16x16x32_bf16 v[118:121], v[174:177], v[190:193], v[118:121]
	v_mfma_f32_16x16x32_bf16 v[114:117], v[182:185], v[190:193], v[114:117]
	v_mfma_f32_16x16x32_bf16 v[102:105], v[174:177], v[198:201], v[102:105]
	v_mfma_f32_16x16x32_bf16 v[98:101], v[182:185], v[198:201], v[98:101]
	v_mfma_f32_16x16x32_bf16 v[86:89], v[174:177], v[206:209], v[86:89]
	v_mfma_f32_16x16x32_bf16 v[82:85], v[182:185], v[206:209], v[82:85]
	v_mfma_f32_16x16x32_bf16 v[70:73], v[174:177], v[214:217], v[70:73]
	v_mfma_f32_16x16x32_bf16 v[66:69], v[182:185], v[214:217], v[66:69]
	v_mfma_f32_16x16x32_bf16 v[118:121], v[178:181], v[194:197], v[118:121]
	v_mfma_f32_16x16x32_bf16 v[114:117], v[186:189], v[194:197], v[114:117]
	v_mfma_f32_16x16x32_bf16 v[102:105], v[178:181], v[202:205], v[102:105]
	v_mfma_f32_16x16x32_bf16 v[98:101], v[186:189], v[202:205], v[98:101]
	v_mfma_f32_16x16x32_bf16 v[86:89], v[178:181], v[210:213], v[86:89]
	v_mfma_f32_16x16x32_bf16 v[82:85], v[186:189], v[210:213], v[82:85]
	v_mfma_f32_16x16x32_bf16 v[70:73], v[178:181], v[218:221], v[70:73]
	v_mfma_f32_16x16x32_bf16 v[66:69], v[186:189], v[218:221], v[66:69]
	s_barrier
	s_setprio 1
	s_add_i32 s66, s48, s4
	v_lshl_add_u64 v[222:223], s[36:37], 0, v[132:133]
	s_mov_b32 m0, s66
	ds_read_b128 v[190:193], v156 offset:16384
	ds_read_b128 v[194:197], v156 offset:17408
	ds_read_b128 v[198:201], v156 offset:18432
	ds_read_b128 v[202:205], v156 offset:19456
	ds_read_b128 v[206:209], v156 offset:20480
	ds_read_b128 v[210:213], v156 offset:21504
	ds_read_b128 v[214:217], v156 offset:22528
	ds_read_b128 v[218:221], v156 offset:23552
	global_load_lds_dwordx4 v[222:223], off
	s_add_i32 m0, s66, 0x2000
	s_add_u32 s66, s36, 0x40000
	v_lshl_add_u64 v[224:225], s[36:37], 0, v[136:137]
	s_addc_u32 s67, s37, 0
	s_add_i32 s68, s49, s4
	global_load_lds_dwordx4 v[224:225], off
	v_lshl_add_u64 v[226:227], s[66:67], 0, v[132:133]
	s_mov_b32 m0, s68
	v_lshl_add_u64 v[228:229], s[38:39], 0, v[134:135]
	global_load_lds_dwordx4 v[226:227], off
	v_lshl_add_u64 v[226:227], s[66:67], 0, v[136:137]
	s_add_i32 m0, s68, 0x2000
	s_nop 0
	global_load_lds_dwordx4 v[226:227], off
	v_lshl_add_u64 v[226:227], s[38:39], 0, v[130:131]
	s_mov_b32 m0, s33
	s_nop 0
	global_load_lds_dwordx4 v[226:227], off
	s_mov_b32 m0, s35
	s_nop 0
	global_load_lds_dwordx4 v[228:229], off
	s_waitcnt vmcnt(8)
	s_waitcnt lgkmcnt(0)
	s_setprio 2
	s_barrier
; #define PG8_STAGE(bufoff, gbase, voff) do { _Pragma("unroll") for (int _i = 0; _i < 2; ++_i) \
;         __builtin_amdgcn_global_load_lds((const unsigned*)((const char*)(gbase) + (voff)[_i]), (PG8_LAS unsigned*)(lds + (bufoff) + ldsw + _i * 8192), 16, 0, 0); } while (0)
; #define PG8_LDA(dst, b, h) do { _Pragma("unroll") for (int m = 0; m < 4; ++m) _Pragma("unroll") for (int k = 0; k < 2; ++k) dst[m][k] = *(const PG8_LAS bf16x8*)(lds + PG8_SA(b, h) + aoff + m * 2048 + k * 1024); } while (0)
; #define PG8_LDB(dst, b, h) do { _Pragma("unroll") for (int n = 0; n < 2; ++n) _Pragma("unroll") for (int k = 0; k < 2; ++k) dst[n][k] = *(const PG8_LAS bf16x8*)(lds + PG8_SB(b, h) + boff + n * 2048 + k * 1024); } while (0)
; #define PG8_MMA(ai, bj, At, Bt) do { __builtin_amdgcn_s_setprio(1); _Pragma("unroll") for (int m = 0; m < 4; ++m) _Pragma("unroll") for (int n = 0; n < 2; ++n) _Pragma("unroll") for (int k = 0; k < 2; ++k) \
;         acc[ai][bj][m][n] = __builtin_amdgcn_mfma_f32_16x16x32_bf16(Bt[n][k], At[m][k], acc[ai][bj][m][n], 0, 0, 0); __builtin_amdgcn_s_setprio(0); } while (0)
; #define PG8_WAIT_V(n) asm volatile("s_waitcnt vmcnt(" #n ")" ::: "memory")
; #define PG8_WAIT_L(n) asm volatile("s_waitcnt lgkmcnt(" #n ")" ::: "memory")
; #define PG8_BAR __builtin_amdgcn_s_barrier()
; #define PG8_SCHED __builtin_amdgcn_sched_barrier(0)
; template <class Epi, class Sched, bool ALIGN_EPI = false, bool SP2 = false>
; __device__ __forceinline__ void gemm_phase(PG8_LAS unsigned char* lds, const Gemm g, const Sched& S, const Epi& E) {
;     ...
;             PG8_WAIT_V(8); PG8_WAIT_L(0); PG8_BAR; PG8_MMA(1, 0, At, B0); PG8_MMA(1, 1, At, B1); PG8_BAR; PG8_SCHED;
;             PG8_LDB(B0, 1, 0); PG8_LDB(B1, 1, 1); PG8_SCHED; PG8_LDA(At, 1, 0); PG8_STAGE(PG8_SA(0, 1), a2 + hstepA, voffA);
;             PG8_WAIT_V(8); PG8_WAIT_L(0); PG8_BAR; PG8_MMA(0, 0, At, B0); PG8_MMA(0, 1, At, B1); PG8_BAR; PG8_SCHED;
	v_mfma_f32_16x16x32_bf16 v[62:65], v[158:161], v[190:193], v[62:65]
	v_mfma_f32_16x16x32_bf16 v[58:61], v[166:169], v[190:193], v[58:61]
	v_mfma_f32_16x16x32_bf16 v[46:49], v[158:161], v[198:201], v[46:49]
	v_mfma_f32_16x16x32_bf16 v[42:45], v[166:169], v[198:201], v[42:45]
	v_mfma_f32_16x16x32_bf16 v[30:33], v[158:161], v[206:209], v[30:33]
	v_mfma_f32_16x16x32_bf16 v[26:29], v[166:169], v[206:209], v[26:29]
	v_mfma_f32_16x16x32_bf16 v[14:17], v[158:161], v[214:217], v[14:17]
	v_mfma_f32_16x16x32_bf16 v[10:13], v[166:169], v[214:217], v[10:13]
	v_mfma_f32_16x16x32_bf16 v[62:65], v[162:165], v[194:197], v[62:65]
	v_mfma_f32_16x16x32_bf16 v[58:61], v[170:173], v[194:197], v[58:61]
	v_mfma_f32_16x16x32_bf16 v[46:49], v[162:165], v[202:205], v[46:49]
	v_mfma_f32_16x16x32_bf16 v[42:45], v[170:173], v[202:205], v[42:45]
	v_mfma_f32_16x16x32_bf16 v[30:33], v[162:165], v[210:213], v[30:33]
	v_mfma_f32_16x16x32_bf16 v[26:29], v[170:173], v[210:213], v[26:29]
	v_mfma_f32_16x16x32_bf16 v[14:17], v[162:165], v[218:221], v[14:17]
	v_mfma_f32_16x16x32_bf16 v[10:13], v[170:173], v[218:221], v[10:13]
	v_mfma_f32_16x16x32_bf16 v[54:57], v[174:177], v[190:193], v[54:57]
	v_mfma_f32_16x16x32_bf16 v[50:53], v[182:185], v[190:193], v[50:53]
	v_mfma_f32_16x16x32_bf16 v[38:41], v[174:177], v[198:201], v[38:41]
	v_mfma_f32_16x16x32_bf16 v[34:37], v[182:185], v[198:201], v[34:37]
	v_mfma_f32_16x16x32_bf16 v[22:25], v[174:177], v[206:209], v[22:25]
	v_mfma_f32_16x16x32_bf16 v[18:21], v[182:185], v[206:209], v[18:21]
	v_mfma_f32_16x16x32_bf16 v[6:9], v[174:177], v[214:217], v[6:9]
	v_mfma_f32_16x16x32_bf16 v[2:5], v[182:185], v[214:217], v[2:5]
	v_mfma_f32_16x16x32_bf16 v[54:57], v[178:181], v[194:197], v[54:57]
	v_mfma_f32_16x16x32_bf16 v[50:53], v[186:189], v[194:197], v[50:53]
	v_mfma_f32_16x16x32_bf16 v[38:41], v[178:181], v[202:205], v[38:41]
	v_mfma_f32_16x16x32_bf16 v[34:37], v[186:189], v[202:205], v[34:37]
	v_mfma_f32_16x16x32_bf16 v[22:25], v[178:181], v[210:213], v[22:25]
	v_mfma_f32_16x16x32_bf16 v[18:21], v[186:189], v[210:213], v[18:21]
	v_mfma_f32_16x16x32_bf16 v[6:9], v[178:181], v[218:221], v[6:9]
	v_mfma_f32_16x16x32_bf16 v[2:5], v[186:189], v[218:221], v[2:5]
	s_barrier
	s_setprio 1
	s_add_i32 s66, 0, 0x18000
	v_add_u32_e32 v157, s66, v1
	s_add_i32 s67, 0, 0x1c000
	ds_read_b128 v[158:161], v157
	ds_read_b128 v[162:165], v157 offset:1024
	ds_read_b128 v[166:169], v157 offset:2048
	ds_read_b128 v[170:173], v157 offset:3072
	v_add_u32_e32 v157, s67, v1
	ds_read_b128 v[174:177], v157
	ds_read_b128 v[178:181], v157 offset:1024
	ds_read_b128 v[182:185], v157 offset:2048
	ds_read_b128 v[186:189], v157 offset:3072
	s_add_u32 s38, s38, 0x40000
	s_addc_u32 s39, s39, 0
	s_mov_b32 m0, s40
	v_lshl_add_u64 v[230:231], s[38:39], 0, v[130:131]
	ds_read_b128 v[190:193], v156 offset:32768
	ds_read_b128 v[194:197], v156 offset:33792
	ds_read_b128 v[198:201], v156 offset:34816
	ds_read_b128 v[202:205], v156 offset:35840
	ds_read_b128 v[206:209], v156 offset:36864
	ds_read_b128 v[210:213], v156 offset:37888
	ds_read_b128 v[214:217], v156 offset:38912
	ds_read_b128 v[218:221], v156 offset:39936
	global_load_lds_dwordx4 v[230:231], off
	v_lshl_add_u64 v[230:231], s[38:39], 0, v[134:135]
	s_mov_b32 m0, s41
	s_nop 0
	global_load_lds_dwordx4 v[230:231], off
	s_waitcnt vmcnt(8)
	s_waitcnt lgkmcnt(0)
	s_setprio 2
	s_barrier
	v_mfma_f32_16x16x32_bf16 v[126:129], v[158:161], v[190:193], v[126:129]
	v_mfma_f32_16x16x32_bf16 v[122:125], v[166:169], v[190:193], v[122:125]
	v_mfma_f32_16x16x32_bf16 v[110:113], v[158:161], v[198:201], v[110:113]
	v_mfma_f32_16x16x32_bf16 v[106:109], v[166:169], v[198:201], v[106:109]
	v_mfma_f32_16x16x32_bf16 v[94:97], v[158:161], v[206:209], v[94:97]
	v_mfma_f32_16x16x32_bf16 v[90:93], v[166:169], v[206:209], v[90:93]
	v_mfma_f32_16x16x32_bf16 v[78:81], v[158:161], v[214:217], v[78:81]
	v_mfma_f32_16x16x32_bf16 v[74:77], v[166:169], v[214:217], v[74:77]
	v_mfma_f32_16x16x32_bf16 v[126:129], v[162:165], v[194:197], v[126:129]
	v_mfma_f32_16x16x32_bf16 v[122:125], v[170:173], v[194:197], v[122:125]
	v_mfma_f32_16x16x32_bf16 v[110:113], v[162:165], v[202:205], v[110:113]
	v_mfma_f32_16x16x32_bf16 v[106:109], v[170:173], v[202:205], v[106:109]
	v_mfma_f32_16x16x32_bf16 v[94:97], v[162:165], v[210:213], v[94:97]
	v_mfma_f32_16x16x32_bf16 v[90:93], v[170:173], v[210:213], v[90:93]
	v_mfma_f32_16x16x32_bf16 v[78:81], v[162:165], v[218:221], v[78:81]
	v_mfma_f32_16x16x32_bf16 v[74:77], v[170:173], v[218:221], v[74:77]
	v_mfma_f32_16x16x32_bf16 v[118:121], v[174:177], v[190:193], v[118:121]
	v_mfma_f32_16x16x32_bf16 v[114:117], v[182:185], v[190:193], v[114:117]
	v_mfma_f32_16x16x32_bf16 v[102:105], v[174:177], v[198:201], v[102:105]
	v_mfma_f32_16x16x32_bf16 v[98:101], v[182:185], v[198:201], v[98:101]
	v_mfma_f32_16x16x32_bf16 v[86:89], v[174:177], v[206:209], v[86:89]
	v_mfma_f32_16x16x32_bf16 v[82:85], v[182:185], v[206:209], v[82:85]
	v_mfma_f32_16x16x32_bf16 v[70:73], v[174:177], v[214:217], v[70:73]
	v_mfma_f32_16x16x32_bf16 v[66:69], v[182:185], v[214:217], v[66:69]
	v_mfma_f32_16x16x32_bf16 v[118:121], v[178:181], v[194:197], v[118:121]
	v_mfma_f32_16x16x32_bf16 v[114:117], v[186:189], v[194:197], v[114:117]
	v_mfma_f32_16x16x32_bf16 v[102:105], v[178:181], v[202:205], v[102:105]
	v_mfma_f32_16x16x32_bf16 v[98:101], v[186:189], v[202:205], v[98:101]
	v_mfma_f32_16x16x32_bf16 v[86:89], v[178:181], v[210:213], v[86:89]
	v_mfma_f32_16x16x32_bf16 v[82:85], v[186:189], v[210:213], v[82:85]
	v_mfma_f32_16x16x32_bf16 v[70:73], v[178:181], v[218:221], v[70:73]
	v_mfma_f32_16x16x32_bf16 v[66:69], v[186:189], v[218:221], v[66:69]
	s_barrier
; #define PG8_STAGE(bufoff, gbase, voff) do { _Pragma("unroll") for (int _i = 0; _i < 2; ++_i) \
;         __builtin_amdgcn_global_load_lds((const unsigned*)((const char*)(gbase) + (voff)[_i]), (PG8_LAS unsigned*)(lds + (bufoff) + ldsw + _i * 8192), 16, 0, 0); } while (0)
; #define PG8_LDA(dst, b, h) do { _Pragma("unroll") for (int m = 0; m < 4; ++m) _Pragma("unroll") for (int k = 0; k < 2; ++k) dst[m][k] = *(const PG8_LAS bf16x8*)(lds + PG8_SA(b, h) + aoff + m * 2048 + k * 1024); } while (0)
; #define PG8_MMA(ai, bj, At, Bt) do { __builtin_amdgcn_s_setprio(1); _Pragma("unroll") for (int m = 0; m < 4; ++m) _Pragma("unroll") for (int n = 0; n < 2; ++n) _Pragma("unroll") for (int k = 0; k < 2; ++k) \
;         acc[ai][bj][m][n] = __builtin_amdgcn_mfma_f32_16x16x32_bf16(Bt[n][k], At[m][k], acc[ai][bj][m][n], 0, 0, 0); __builtin_amdgcn_s_setprio(0); } while (0)
; #define PG8_WAIT_V(n) asm volatile("s_waitcnt vmcnt(" #n ")" ::: "memory")
; #define PG8_WAIT_L(n) asm volatile("s_waitcnt lgkmcnt(" #n ")" ::: "memory")
; #define PG8_BAR __builtin_amdgcn_s_barrier()
; #define PG8_SCHED __builtin_amdgcn_sched_barrier(0)
; template <class Epi, class Sched, bool ALIGN_EPI = false, bool SP2 = false>
; __device__ __forceinline__ void gemm_phase(PG8_LAS unsigned char* lds, const Gemm g, const Sched& S, const Epi& E) {
;     ...
;             PG8_LDA(At, 1, 1); PG8_STAGE(PG8_SB(1, 0), b3, voffB); PG8_STAGE(PG8_SB(1, 1), b3 + hstepB, voffB); PG8_STAGE(PG8_SA(1, 0), a3, voffA);
;             PG8_WAIT_V(8); PG8_WAIT_L(0); PG8_BAR; PG8_MMA(1, 0, At, B0); PG8_MMA(1, 1, At, B1); PG8_BAR; PG8_SCHED;
	s_setprio 1
	s_add_i32 s38, s66, s4
	v_lshl_add_u64 v[222:223], v[222:223], 0, s[8:9]
	s_mov_b32 m0, s38
	ds_read_b128 v[190:193], v156 offset:49152
	ds_read_b128 v[194:197], v156 offset:50176
	ds_read_b128 v[198:201], v156 offset:51200
	ds_read_b128 v[202:205], v156 offset:52224
	ds_read_b128 v[206:209], v156 offset:53248
	ds_read_b128 v[210:213], v156 offset:54272
	ds_read_b128 v[214:217], v156 offset:55296
	ds_read_b128 v[218:221], v156 offset:56320
	global_load_lds_dwordx4 v[222:223], off
	s_add_i32 m0, s38, 0x2000
	s_add_u32 s36, s36, 0x40080
	v_lshl_add_u64 v[222:223], v[224:225], 0, s[8:9]
	s_addc_u32 s37, s37, 0
	s_add_i32 s38, s67, s4
	global_load_lds_dwordx4 v[222:223], off
	v_lshl_add_u64 v[222:223], s[36:37], 0, v[132:133]
	s_mov_b32 m0, s38
	s_nop 0
	global_load_lds_dwordx4 v[222:223], off
	v_lshl_add_u64 v[222:223], s[36:37], 0, v[136:137]
	s_add_i32 m0, s38, 0x2000
	s_nop 0
	global_load_lds_dwordx4 v[222:223], off
	v_lshl_add_u64 v[222:223], v[226:227], 0, s[8:9]
	s_mov_b32 m0, s45
	s_nop 0
	global_load_lds_dwordx4 v[222:223], off
	v_lshl_add_u64 v[222:223], v[228:229], 0, s[8:9]
	s_mov_b32 m0, s46
	s_nop 0
	global_load_lds_dwordx4 v[222:223], off
	s_waitcnt vmcnt(8)
	s_waitcnt lgkmcnt(0)
	s_setprio 2
	s_barrier
	v_mfma_f32_16x16x32_bf16 v[62:65], v[158:161], v[190:193], v[62:65]
	v_mfma_f32_16x16x32_bf16 v[58:61], v[166:169], v[190:193], v[58:61]
	v_mfma_f32_16x16x32_bf16 v[46:49], v[158:161], v[198:201], v[46:49]
	v_mfma_f32_16x16x32_bf16 v[42:45], v[166:169], v[198:201], v[42:45]
	v_mfma_f32_16x16x32_bf16 v[30:33], v[158:161], v[206:209], v[30:33]
	v_mfma_f32_16x16x32_bf16 v[26:29], v[166:169], v[206:209], v[26:29]
	v_mfma_f32_16x16x32_bf16 v[14:17], v[158:161], v[214:217], v[14:17]
	v_mfma_f32_16x16x32_bf16 v[10:13], v[166:169], v[214:217], v[10:13]
	v_mfma_f32_16x16x32_bf16 v[62:65], v[162:165], v[194:197], v[62:65]
	v_mfma_f32_16x16x32_bf16 v[58:61], v[170:173], v[194:197], v[58:61]
	v_mfma_f32_16x16x32_bf16 v[46:49], v[162:165], v[202:205], v[46:49]
	v_mfma_f32_16x16x32_bf16 v[42:45], v[170:173], v[202:205], v[42:45]
	v_mfma_f32_16x16x32_bf16 v[30:33], v[162:165], v[210:213], v[30:33]
	v_mfma_f32_16x16x32_bf16 v[26:29], v[170:173], v[210:213], v[26:29]
	v_mfma_f32_16x16x32_bf16 v[14:17], v[162:165], v[218:221], v[14:17]
	v_mfma_f32_16x16x32_bf16 v[10:13], v[170:173], v[218:221], v[10:13]
	v_mfma_f32_16x16x32_bf16 v[54:57], v[174:177], v[190:193], v[54:57]
	v_mfma_f32_16x16x32_bf16 v[50:53], v[182:185], v[190:193], v[50:53]
	v_mfma_f32_16x16x32_bf16 v[38:41], v[174:177], v[198:201], v[38:41]
	v_mfma_f32_16x16x32_bf16 v[34:37], v[182:185], v[198:201], v[34:37]
	v_mfma_f32_16x16x32_bf16 v[22:25], v[174:177], v[206:209], v[22:25]
	v_mfma_f32_16x16x32_bf16 v[18:21], v[182:185], v[206:209], v[18:21]
	v_mfma_f32_16x16x32_bf16 v[6:9], v[174:177], v[214:217], v[6:9]
	v_mfma_f32_16x16x32_bf16 v[2:5], v[182:185], v[214:217], v[2:5]
	v_mfma_f32_16x16x32_bf16 v[54:57], v[178:181], v[194:197], v[54:57]
	v_mfma_f32_16x16x32_bf16 v[50:53], v[186:189], v[194:197], v[50:53]
	v_mfma_f32_16x16x32_bf16 v[38:41], v[178:181], v[202:205], v[38:41]
	v_mfma_f32_16x16x32_bf16 v[34:37], v[186:189], v[202:205], v[34:37]
	v_mfma_f32_16x16x32_bf16 v[22:25], v[178:181], v[210:213], v[22:25]
	v_mfma_f32_16x16x32_bf16 v[18:21], v[186:189], v[210:213], v[18:21]
	v_mfma_f32_16x16x32_bf16 v[6:9], v[178:181], v[218:221], v[6:9]
	v_mfma_f32_16x16x32_bf16 v[2:5], v[186:189], v[218:221], v[2:5]
	s_barrier
	s_setprio 1
	s_add_i32 s65, s65, 2
	s_add_u32 s30, s30, 0x100
	s_addc_u32 s31, s31, 0
	s_add_u32 s63, s63, 0x100
	s_addc_u32 s64, s64, 0
	s_cmp_gt_u32 s65, 13
	s_cbranch_scc0 .Lph1244_y
	s_setprio 0

;     __host__ __device__ bool next(int i, Unit& u) const { if (!so.next(i >> 1, u)) return false; u.k0 = (i & 1) * 512; return true; }
;     __host__ __device__ bool next(int i, Unit& u) const { if (!so.next(i, u)) return false; u.pe = main_tile(u.pn); return true; }
;     __host__ __device__ bool next(int i, Unit& u) const { if (start + i * stride >= limit) return false; if (!so.next(i, u)) return false; u.pe = late_tile(u.pn); return true; }
; #define PG8_STAGE(bufoff, gbase, voff) do { _Pragma("unroll") for (int _i = 0; _i < 2; ++_i) \
;         __builtin_amdgcn_global_load_lds((const unsigned*)((const char*)(gbase) + (voff)[_i]), (PG8_LAS unsigned*)(lds + (bufoff) + ldsw + _i * 8192), 16, 0, 0); } while (0)
; #define PG8_LDA(dst, b, h) do { _Pragma("unroll") for (int m = 0; m < 4; ++m) _Pragma("unroll") for (int k = 0; k < 2; ++k) dst[m][k] = *(const PG8_LAS bf16x8*)(lds + PG8_SA(b, h) + aoff + m * 2048 + k * 1024); } while (0)
; template <class Epi, class Sched, bool ALIGN_EPI = false, bool SP2 = false>
; __device__ __forceinline__ void gemm_phase(PG8_LAS unsigned char* lds, const Gemm g, const Sched& S, const Epi& E) {
;     ...
;         const bool has_next = S.next(ui + 1, nxt);
;         const char* nA = has_next ? (const char*)g.A + (size_t)nxt.pm * tstepA + (size_t)nxt.k0 * 2 : cA; const char* nB = has_next ? (const char*)g.Bt + (size_t)nxt.pn * tstepB + (size_t)nxt.k0 * 2 : cB;
;         for (int t = 0; t < nt; t += 2) {
;             const bool last = (t == nt - 2);
;             const char* a1 = cA + (size_t)(t + 1) * kstepA;
;             const char* a2 = last ? nA : cA + (size_t)(t + 2) * kstepA; const char* b2 = last ? nB : cB + (size_t)(t + 2) * kstep;
;             const char* a3 = a2 + kstepA; const char* b3 = b2 + kstep;
;             if (last && has_next) S.a_ready(nxt);
;             if constexpr (SP2) {
;             PG8_LDB(B0, 0, 0); PG8_LDB(B1, 0, 1); PG8_SCHED; PG8_LDA(At, 0, 0); PG8_STAGE(PG8_SA(1, 1), a1 + hstepA, voffA);
;             PG8_WAIT_V(8); PG8_WAIT_L(0); PG8_BAR; PG8_MMA(0, 0, At, B0); PG8_MMA(0, 1, At, B1); PG8_BAR; PG8_SCHED;
;             PG8_LDA(At, 0, 1); PG8_STAGE(PG8_SB(0, 0), b2, voffB); PG8_STAGE(PG8_SB(0, 1), b2 + hstepB, voffB); PG8_STAGE(PG8_SA(0, 0), a2, voffA);
;             PG8_WAIT_V(8); PG8_WAIT_L(0); PG8_BAR; PG8_MMA(1, 0, At, B0); PG8_MMA(1, 1, At, B1); PG8_BAR; PG8_SCHED;
.LBB0_1338:
	s_ashr_i32 s25, s24, 31
	s_lshl_b64 s[28:29], s[24:25], 21
	s_add_u32 s28, s26, s28
	s_addc_u32 s29, s27, s29
	s_and_b64 s[30:31], s[4:5], exec
	s_cselect_b32 s25, s29, s15
	s_cselect_b32 s59, s28, s14
	s_ashr_i32 s23, s22, 31
	s_lshl_b64 s[30:31], s[22:23], 21
	s_add_u32 s30, s12, s30
	s_addc_u32 s31, s13, s31
	s_and_b64 s[36:37], s[4:5], exec
	s_cselect_b32 s23, s31, s11
	s_cselect_b32 s62, s30, s10
	s_add_u32 s63, s10, 0x100
	s_addc_u32 s64, s11, 0
	s_mov_b32 s65, -2
	s_mov_b64 s[36:37], 0x10000
	v_mov_b64_e32 v[146:147], v[140:141]
	v_mov_b64_e32 v[148:149], v[138:139]
	s_cmp_lg_u32 s101, 0
	s_cbranch_scc1 .Lph1339_y
.LBB0_1339:
	v_add_u32_e32 v153, s56, v151
	ds_read_b128 v[154:157], v153
	ds_read_b128 v[158:161], v153 offset:1024
	ds_read_b128 v[162:165], v153 offset:2048
	ds_read_b128 v[166:169], v153 offset:3072
	v_add_u32_e32 v153, s57, v151
	ds_read_b128 v[172:175], v153
	ds_read_b128 v[176:179], v153 offset:1024
	ds_read_b128 v[180:183], v153 offset:2048
	ds_read_b128 v[184:187], v153 offset:3072
	s_add_u32 s38, s14, s36
	s_addc_u32 s39, s15, s37
	s_cmp_eq_u32 s65, 60
	s_cselect_b32 s42, s59, s38
	s_cselect_b32 s43, s25, s39
	s_cselect_b32 s40, s62, s63
	s_cselect_b32 s41, s23, s64
	s_add_u32 s38, s42, 0x8000
	s_addc_u32 s39, s43, 0
	v_lshl_add_u64 v[220:221], s[14:15], 0, v[148:149]
	s_add_i32 m0, s45, 0xc000
	ds_read_b128 v[188:191], v152
	ds_read_b128 v[192:195], v152 offset:1024
	ds_read_b128 v[196:199], v152 offset:2048
	ds_read_b128 v[200:203], v152 offset:3072
	ds_read_b128 v[204:207], v152 offset:4096
	ds_read_b128 v[208:211], v152 offset:5120
	ds_read_b128 v[212:215], v152 offset:6144
	ds_read_b128 v[216:219], v152 offset:7168
	global_load_lds_dwordx4 v[220:221], off
	v_lshl_add_u64 v[220:221], s[14:15], 0, v[146:147]
	s_add_i32 m0, s45, 0xe000
	s_nop 0
	global_load_lds_dwordx4 v[220:221], off
	s_waitcnt vmcnt(8)
	s_waitcnt lgkmcnt(0)
	s_setprio 1
	s_barrier
	v_mfma_f32_16x16x32_bf16 v[122:125], v[154:157], v[188:191], v[122:125]
	v_mfma_f32_16x16x32_bf16 v[126:129], v[162:165], v[188:191], v[126:129]
	v_mfma_f32_16x16x32_bf16 v[118:121], v[154:157], v[196:199], v[118:121]
	v_mfma_f32_16x16x32_bf16 v[106:109], v[162:165], v[196:199], v[106:109]
	v_mfma_f32_16x16x32_bf16 v[98:101], v[154:157], v[204:207], v[98:101]
	v_mfma_f32_16x16x32_bf16 v[90:93], v[162:165], v[204:207], v[90:93]
	v_mfma_f32_16x16x32_bf16 v[110:113], v[154:157], v[212:215], v[110:113]
	v_mfma_f32_16x16x32_bf16 v[82:85], v[162:165], v[212:215], v[82:85]
	v_mfma_f32_16x16x32_bf16 v[122:125], v[158:161], v[192:195], v[122:125]
	v_mfma_f32_16x16x32_bf16 v[126:129], v[166:169], v[192:195], v[126:129]
	v_mfma_f32_16x16x32_bf16 v[118:121], v[158:161], v[200:203], v[118:121]
	v_mfma_f32_16x16x32_bf16 v[106:109], v[166:169], v[200:203], v[106:109]
	v_mfma_f32_16x16x32_bf16 v[98:101], v[158:161], v[208:211], v[98:101]
	v_mfma_f32_16x16x32_bf16 v[90:93], v[166:169], v[208:211], v[90:93]
	v_mfma_f32_16x16x32_bf16 v[110:113], v[158:161], v[216:219], v[110:113]
	v_mfma_f32_16x16x32_bf16 v[82:85], v[166:169], v[216:219], v[82:85]
	v_mfma_f32_16x16x32_bf16 v[114:117], v[172:175], v[188:191], v[114:117]
	v_mfma_f32_16x16x32_bf16 v[102:105], v[180:183], v[188:191], v[102:105]
	v_mfma_f32_16x16x32_bf16 v[94:97], v[172:175], v[196:199], v[94:97]
	v_mfma_f32_16x16x32_bf16 v[86:89], v[180:183], v[196:199], v[86:89]
	v_mfma_f32_16x16x32_bf16 v[78:81], v[172:175], v[204:207], v[78:81]
	v_mfma_f32_16x16x32_bf16 v[70:73], v[180:183], v[204:207], v[70:73]
	v_mfma_f32_16x16x32_bf16 v[66:69], v[172:175], v[212:215], v[66:69]
	v_mfma_f32_16x16x32_bf16 v[74:77], v[180:183], v[212:215], v[74:77]
	v_mfma_f32_16x16x32_bf16 v[114:117], v[176:179], v[192:195], v[114:117]
	v_mfma_f32_16x16x32_bf16 v[102:105], v[184:187], v[192:195], v[102:105]
	v_mfma_f32_16x16x32_bf16 v[94:97], v[176:179], v[200:203], v[94:97]
	v_mfma_f32_16x16x32_bf16 v[86:89], v[184:187], v[200:203], v[86:89]
	v_mfma_f32_16x16x32_bf16 v[78:81], v[176:179], v[208:211], v[78:81]
	v_mfma_f32_16x16x32_bf16 v[70:73], v[184:187], v[208:211], v[70:73]
	v_mfma_f32_16x16x32_bf16 v[66:69], v[176:179], v[216:219], v[66:69]
	v_mfma_f32_16x16x32_bf16 v[74:77], v[184:187], v[216:219], v[74:77]
	s_barrier
	s_setprio 0
	s_add_i32 s66, s56, s44
	v_lshl_add_u64 v[220:221], s[40:41], 0, v[132:133]
	s_mov_b32 m0, s66
	ds_read_b128 v[188:191], v152 offset:16384
	ds_read_b128 v[192:195], v152 offset:17408
	ds_read_b128 v[196:199], v152 offset:18432
	ds_read_b128 v[200:203], v152 offset:19456
	ds_read_b128 v[204:207], v152 offset:20480
	ds_read_b128 v[208:211], v152 offset:21504
	ds_read_b128 v[212:215], v152 offset:22528
	ds_read_b128 v[216:219], v152 offset:23552
	global_load_lds_dwordx4 v[220:221], off
	s_add_i32 m0, s66, 0x2000
	s_add_u32 s66, s40, 0x100000
	v_lshl_add_u64 v[222:223], s[40:41], 0, v[136:137]
	s_addc_u32 s67, s41, 0
	s_add_i32 s68, s57, s44
	global_load_lds_dwordx4 v[222:223], off
	v_lshl_add_u64 v[224:225], s[66:67], 0, v[132:133]
	s_mov_b32 m0, s68
	s_nop 0
	global_load_lds_dwordx4 v[224:225], off
	v_lshl_add_u64 v[224:225], s[66:67], 0, v[136:137]
	s_add_i32 m0, s68, 0x2000
	s_nop 0
	global_load_lds_dwordx4 v[224:225], off
	v_lshl_add_u64 v[224:225], s[42:43], 0, v[130:131]
	s_mov_b32 m0, s45
	s_nop 0
	global_load_lds_dwordx4 v[224:225], off
	v_lshl_add_u64 v[224:225], s[42:43], 0, v[134:135]
	s_mov_b32 m0, s46
	s_nop 0
	global_load_lds_dwordx4 v[224:225], off
	s_waitcnt vmcnt(8)
	s_waitcnt lgkmcnt(0)
	s_setprio 1
	s_barrier
; #define PG8_STAGE(bufoff, gbase, voff) do { _Pragma("unroll") for (int _i = 0; _i < 2; ++_i) \
;         __builtin_amdgcn_global_load_lds((const unsigned*)((const char*)(gbase) + (voff)[_i]), (PG8_LAS unsigned*)(lds + (bufoff) + ldsw + _i * 8192), 16, 0, 0); } while (0)
; #define PG8_LDA(dst, b, h) do { _Pragma("unroll") for (int m = 0; m < 4; ++m) _Pragma("unroll") for (int k = 0; k < 2; ++k) dst[m][k] = *(const PG8_LAS bf16x8*)(lds + PG8_SA(b, h) + aoff + m * 2048 + k * 1024); } while (0)
; #define PG8_LDB(dst, b, h) do { _Pragma("unroll") for (int n = 0; n < 2; ++n) _Pragma("unroll") for (int k = 0; k < 2; ++k) dst[n][k] = *(const PG8_LAS bf16x8*)(lds + PG8_SB(b, h) + boff + n * 2048 + k * 1024); } while (0)
; #define PG8_MMA(ai, bj, At, Bt) do { __builtin_amdgcn_s_setprio(1); _Pragma("unroll") for (int m = 0; m < 4; ++m) _Pragma("unroll") for (int n = 0; n < 2; ++n) _Pragma("unroll") for (int k = 0; k < 2; ++k) \
;         acc[ai][bj][m][n] = __builtin_amdgcn_mfma_f32_16x16x32_bf16(Bt[n][k], At[m][k], acc[ai][bj][m][n], 0, 0, 0); __builtin_amdgcn_s_setprio(0); } while (0)
; #define PG8_WAIT_V(n) asm volatile("s_waitcnt vmcnt(" #n ")" ::: "memory")
; #define PG8_WAIT_L(n) asm volatile("s_waitcnt lgkmcnt(" #n ")" ::: "memory")
; #define PG8_BAR __builtin_amdgcn_s_barrier()
; #define PG8_SCHED __builtin_amdgcn_sched_barrier(0)
; template <class Epi, class Sched, bool ALIGN_EPI = false, bool SP2 = false>
; __device__ __forceinline__ void gemm_phase(PG8_LAS unsigned char* lds, const Gemm g, const Sched& S, const Epi& E) {
;     ...
;             PG8_WAIT_V(8); PG8_WAIT_L(0); PG8_BAR; PG8_MMA(1, 0, At, B0); PG8_MMA(1, 1, At, B1); PG8_BAR; PG8_SCHED;
;             PG8_LDB(B0, 1, 0); PG8_LDB(B1, 1, 1); PG8_SCHED; PG8_LDA(At, 1, 0); PG8_STAGE(PG8_SA(0, 1), a2 + hstepA, voffA);
;             PG8_WAIT_V(8); PG8_WAIT_L(0); PG8_BAR; PG8_MMA(0, 0, At, B0); PG8_MMA(0, 1, At, B1); PG8_BAR; PG8_SCHED;
;             PG8_LDA(At, 1, 1); PG8_STAGE(PG8_SB(1, 0), b3, voffB); PG8_STAGE(PG8_SB(1, 1), b3 + hstepB, voffB); PG8_STAGE(PG8_SA(1, 0), a3, voffA);
	v_mfma_f32_16x16x32_bf16 v[62:65], v[154:157], v[188:191], v[62:65]
	v_mfma_f32_16x16x32_bf16 v[58:61], v[162:165], v[188:191], v[58:61]
	v_mfma_f32_16x16x32_bf16 v[54:57], v[154:157], v[196:199], v[54:57]
	v_mfma_f32_16x16x32_bf16 v[46:49], v[162:165], v[196:199], v[46:49]
	v_mfma_f32_16x16x32_bf16 v[38:41], v[154:157], v[204:207], v[38:41]
	v_mfma_f32_16x16x32_bf16 v[30:33], v[162:165], v[204:207], v[30:33]
	v_mfma_f32_16x16x32_bf16 v[14:17], v[154:157], v[212:215], v[14:17]
	v_mfma_f32_16x16x32_bf16 v[10:13], v[162:165], v[212:215], v[10:13]
	v_mfma_f32_16x16x32_bf16 v[62:65], v[158:161], v[192:195], v[62:65]
	v_mfma_f32_16x16x32_bf16 v[58:61], v[166:169], v[192:195], v[58:61]
	v_mfma_f32_16x16x32_bf16 v[54:57], v[158:161], v[200:203], v[54:57]
	v_mfma_f32_16x16x32_bf16 v[46:49], v[166:169], v[200:203], v[46:49]
	v_mfma_f32_16x16x32_bf16 v[38:41], v[158:161], v[208:211], v[38:41]
	v_mfma_f32_16x16x32_bf16 v[30:33], v[166:169], v[208:211], v[30:33]
	v_mfma_f32_16x16x32_bf16 v[14:17], v[158:161], v[216:219], v[14:17]
	v_mfma_f32_16x16x32_bf16 v[10:13], v[166:169], v[216:219], v[10:13]
	v_mfma_f32_16x16x32_bf16 v[50:53], v[172:175], v[188:191], v[50:53]
	v_mfma_f32_16x16x32_bf16 v[42:45], v[180:183], v[188:191], v[42:45]
	v_mfma_f32_16x16x32_bf16 v[34:37], v[172:175], v[196:199], v[34:37]
	v_mfma_f32_16x16x32_bf16 v[26:29], v[180:183], v[196:199], v[26:29]
	v_mfma_f32_16x16x32_bf16 v[22:25], v[172:175], v[204:207], v[22:25]
	v_mfma_f32_16x16x32_bf16 v[18:21], v[180:183], v[204:207], v[18:21]
	v_mfma_f32_16x16x32_bf16 v[6:9], v[172:175], v[212:215], v[6:9]
	v_mfma_f32_16x16x32_bf16 v[2:5], v[180:183], v[212:215], v[2:5]
	v_mfma_f32_16x16x32_bf16 v[50:53], v[176:179], v[192:195], v[50:53]
	v_mfma_f32_16x16x32_bf16 v[42:45], v[184:187], v[192:195], v[42:45]
	v_mfma_f32_16x16x32_bf16 v[34:37], v[176:179], v[200:203], v[34:37]
	v_mfma_f32_16x16x32_bf16 v[26:29], v[184:187], v[200:203], v[26:29]
	v_mfma_f32_16x16x32_bf16 v[22:25], v[176:179], v[208:211], v[22:25]
	v_mfma_f32_16x16x32_bf16 v[18:21], v[184:187], v[208:211], v[18:21]
	v_mfma_f32_16x16x32_bf16 v[6:9], v[176:179], v[216:219], v[6:9]
	v_mfma_f32_16x16x32_bf16 v[2:5], v[184:187], v[216:219], v[2:5]
	s_barrier
	s_setprio 0
	s_add_i32 s66, 0, 0x18000
	v_add_u32_e32 v153, s66, v151
	s_add_i32 s67, 0, 0x1c000
	ds_read_b128 v[154:157], v153
	ds_read_b128 v[158:161], v153 offset:1024
	ds_read_b128 v[162:165], v153 offset:2048
	ds_read_b128 v[166:169], v153 offset:3072
	v_add_u32_e32 v153, s67, v151
	ds_read_b128 v[172:175], v153
	ds_read_b128 v[176:179], v153 offset:1024
	ds_read_b128 v[180:183], v153 offset:2048
	ds_read_b128 v[184:187], v153 offset:3072
	s_add_u32 s42, s42, 0x4000
	s_addc_u32 s43, s43, 0
	s_mov_b32 m0, s47
	v_lshl_add_u64 v[224:225], s[42:43], 0, v[130:131]
	ds_read_b128 v[188:191], v152 offset:32768
	ds_read_b128 v[192:195], v152 offset:33792
	ds_read_b128 v[196:199], v152 offset:34816
	ds_read_b128 v[200:203], v152 offset:35840
	ds_read_b128 v[204:207], v152 offset:36864
	ds_read_b128 v[208:211], v152 offset:37888
	ds_read_b128 v[212:215], v152 offset:38912
	ds_read_b128 v[216:219], v152 offset:39936
	global_load_lds_dwordx4 v[224:225], off
	v_lshl_add_u64 v[224:225], s[42:43], 0, v[134:135]
	s_mov_b32 m0, s48
	s_nop 0
	global_load_lds_dwordx4 v[224:225], off
	s_waitcnt vmcnt(8)
	s_waitcnt lgkmcnt(0)
	s_setprio 1
	s_barrier
	v_mfma_f32_16x16x32_bf16 v[122:125], v[154:157], v[188:191], v[122:125]
	v_mfma_f32_16x16x32_bf16 v[126:129], v[162:165], v[188:191], v[126:129]
	v_mfma_f32_16x16x32_bf16 v[118:121], v[154:157], v[196:199], v[118:121]
	v_mfma_f32_16x16x32_bf16 v[106:109], v[162:165], v[196:199], v[106:109]
	v_mfma_f32_16x16x32_bf16 v[98:101], v[154:157], v[204:207], v[98:101]
	v_mfma_f32_16x16x32_bf16 v[90:93], v[162:165], v[204:207], v[90:93]
	v_mfma_f32_16x16x32_bf16 v[110:113], v[154:157], v[212:215], v[110:113]
	v_mfma_f32_16x16x32_bf16 v[82:85], v[162:165], v[212:215], v[82:85]
	v_mfma_f32_16x16x32_bf16 v[122:125], v[158:161], v[192:195], v[122:125]
	v_mfma_f32_16x16x32_bf16 v[126:129], v[166:169], v[192:195], v[126:129]
	v_mfma_f32_16x16x32_bf16 v[118:121], v[158:161], v[200:203], v[118:121]
	v_mfma_f32_16x16x32_bf16 v[106:109], v[166:169], v[200:203], v[106:109]
	v_mfma_f32_16x16x32_bf16 v[98:101], v[158:161], v[208:211], v[98:101]
	v_mfma_f32_16x16x32_bf16 v[90:93], v[166:169], v[208:211], v[90:93]
	v_mfma_f32_16x16x32_bf16 v[110:113], v[158:161], v[216:219], v[110:113]
	v_mfma_f32_16x16x32_bf16 v[82:85], v[166:169], v[216:219], v[82:85]
	v_mfma_f32_16x16x32_bf16 v[114:117], v[172:175], v[188:191], v[114:117]
	v_mfma_f32_16x16x32_bf16 v[102:105], v[180:183], v[188:191], v[102:105]
	v_mfma_f32_16x16x32_bf16 v[94:97], v[172:175], v[196:199], v[94:97]
	v_mfma_f32_16x16x32_bf16 v[86:89], v[180:183], v[196:199], v[86:89]
	v_mfma_f32_16x16x32_bf16 v[78:81], v[172:175], v[204:207], v[78:81]
	v_mfma_f32_16x16x32_bf16 v[70:73], v[180:183], v[204:207], v[70:73]
	v_mfma_f32_16x16x32_bf16 v[66:69], v[172:175], v[212:215], v[66:69]
	v_mfma_f32_16x16x32_bf16 v[74:77], v[180:183], v[212:215], v[74:77]
	v_mfma_f32_16x16x32_bf16 v[114:117], v[176:179], v[192:195], v[114:117]
	v_mfma_f32_16x16x32_bf16 v[102:105], v[184:187], v[192:195], v[102:105]
	v_mfma_f32_16x16x32_bf16 v[94:97], v[176:179], v[200:203], v[94:97]
	v_mfma_f32_16x16x32_bf16 v[86:89], v[184:187], v[200:203], v[86:89]
	v_mfma_f32_16x16x32_bf16 v[78:81], v[176:179], v[208:211], v[78:81]
	v_mfma_f32_16x16x32_bf16 v[70:73], v[184:187], v[208:211], v[70:73]
	v_mfma_f32_16x16x32_bf16 v[66:69], v[176:179], v[216:219], v[66:69]
	v_mfma_f32_16x16x32_bf16 v[74:77], v[184:187], v[216:219], v[74:77]
	s_barrier
; #define PG8_STAGE(bufoff, gbase, voff) do { _Pragma("unroll") for (int _i = 0; _i < 2; ++_i) \
;         __builtin_amdgcn_global_load_lds((const unsigned*)((const char*)(gbase) + (voff)[_i]), (PG8_LAS unsigned*)(lds + (bufoff) + ldsw + _i * 8192), 16, 0, 0); } while (0)
; #define PG8_LDA(dst, b, h) do { _Pragma("unroll") for (int m = 0; m < 4; ++m) _Pragma("unroll") for (int k = 0; k < 2; ++k) dst[m][k] = *(const PG8_LAS bf16x8*)(lds + PG8_SA(b, h) + aoff + m * 2048 + k * 1024); } while (0)
; #define PG8_LDB(dst, b, h) do { _Pragma("unroll") for (int n = 0; n < 2; ++n) _Pragma("unroll") for (int k = 0; k < 2; ++k) dst[n][k] = *(const PG8_LAS bf16x8*)(lds + PG8_SB(b, h) + boff + n * 2048 + k * 1024); } while (0)
; #define PG8_MMA(ai, bj, At, Bt) do { __builtin_amdgcn_s_setprio(1); _Pragma("unroll") for (int m = 0; m < 4; ++m) _Pragma("unroll") for (int n = 0; n < 2; ++n) _Pragma("unroll") for (int k = 0; k < 2; ++k) \
;         acc[ai][bj][m][n] = __builtin_amdgcn_mfma_f32_16x16x32_bf16(Bt[n][k], At[m][k], acc[ai][bj][m][n], 0, 0, 0); __builtin_amdgcn_s_setprio(0); } while (0)
; #define PG8_WAIT_V(n) asm volatile("s_waitcnt vmcnt(" #n ")" ::: "memory")
; #define PG8_WAIT_L(n) asm volatile("s_waitcnt lgkmcnt(" #n ")" ::: "memory")
; #define PG8_BAR __builtin_amdgcn_s_barrier()
; #define PG8_SCHED __builtin_amdgcn_sched_barrier(0)
; template <class Epi, class Sched, bool ALIGN_EPI = false, bool SP2 = false>
; __device__ __forceinline__ void gemm_phase(PG8_LAS unsigned char* lds, const Gemm g, const Sched& S, const Epi& E) {
;     ...
;             PG8_LDB(B0, 0, 0); PG8_LDB(B1, 0, 1); PG8_SCHED; PG8_LDA(At, 0, 0); PG8_STAGE(PG8_SA(1, 1), a1 + hstepA, voffA);
;             PG8_WAIT_V(8); PG8_WAIT_L(0); PG8_BAR; PG8_MMA(0, 0, At, B0); PG8_MMA(0, 1, At, B1); PG8_BAR; PG8_SCHED;
;     ...
;             PG8_LDA(At, 1, 1); PG8_STAGE(PG8_SB(1, 0), b3, voffB); PG8_STAGE(PG8_SB(1, 1), b3 + hstepB, voffB); PG8_STAGE(PG8_SA(1, 0), a3, voffA);
;             PG8_WAIT_V(8); PG8_WAIT_L(0); PG8_BAR; PG8_MMA(1, 0, At, B0); PG8_MMA(1, 1, At, B1); PG8_BAR; PG8_SCHED;
	s_setprio 0
	s_add_i32 s42, s66, s44
	v_lshl_add_u64 v[220:221], v[220:221], 0, s[16:17]
	s_mov_b32 m0, s42
	ds_read_b128 v[188:191], v152 offset:49152
	ds_read_b128 v[192:195], v152 offset:50176
	ds_read_b128 v[196:199], v152 offset:51200
	ds_read_b128 v[200:203], v152 offset:52224
	ds_read_b128 v[204:207], v152 offset:53248
	ds_read_b128 v[208:211], v152 offset:54272
	ds_read_b128 v[212:215], v152 offset:55296
	ds_read_b128 v[216:219], v152 offset:56320
	global_load_lds_dwordx4 v[220:221], off
	s_add_i32 m0, s42, 0x2000
	s_add_u32 s40, s40, 0x100080
	v_lshl_add_u64 v[220:221], v[222:223], 0, s[16:17]
	s_addc_u32 s41, s41, 0
	s_add_i32 s42, s67, s44
	global_load_lds_dwordx4 v[220:221], off
	v_lshl_add_u64 v[220:221], s[40:41], 0, v[132:133]
	s_mov_b32 m0, s42
	s_nop 0
	global_load_lds_dwordx4 v[220:221], off
	v_lshl_add_u64 v[220:221], s[40:41], 0, v[136:137]
	s_add_i32 m0, s42, 0x2000
	s_nop 0
	global_load_lds_dwordx4 v[220:221], off
	v_lshl_add_u64 v[220:221], s[38:39], 0, v[130:131]
	s_mov_b32 m0, s50
	s_nop 0
	global_load_lds_dwordx4 v[220:221], off
	v_lshl_add_u64 v[220:221], s[38:39], 0, v[134:135]
	s_mov_b32 m0, s51
	s_nop 0
	global_load_lds_dwordx4 v[220:221], off
	s_waitcnt vmcnt(8)
	s_waitcnt lgkmcnt(0)
	s_setprio 1
	s_barrier
	v_mfma_f32_16x16x32_bf16 v[62:65], v[154:157], v[188:191], v[62:65]
	v_mfma_f32_16x16x32_bf16 v[58:61], v[162:165], v[188:191], v[58:61]
	v_mfma_f32_16x16x32_bf16 v[54:57], v[154:157], v[196:199], v[54:57]
	v_mfma_f32_16x16x32_bf16 v[46:49], v[162:165], v[196:199], v[46:49]
	v_mfma_f32_16x16x32_bf16 v[38:41], v[154:157], v[204:207], v[38:41]
	v_mfma_f32_16x16x32_bf16 v[30:33], v[162:165], v[204:207], v[30:33]
	v_mfma_f32_16x16x32_bf16 v[14:17], v[154:157], v[212:215], v[14:17]
	v_mfma_f32_16x16x32_bf16 v[10:13], v[162:165], v[212:215], v[10:13]
	v_mfma_f32_16x16x32_bf16 v[62:65], v[158:161], v[192:195], v[62:65]
	v_mfma_f32_16x16x32_bf16 v[58:61], v[166:169], v[192:195], v[58:61]
	v_mfma_f32_16x16x32_bf16 v[54:57], v[158:161], v[200:203], v[54:57]
	v_mfma_f32_16x16x32_bf16 v[46:49], v[166:169], v[200:203], v[46:49]
	v_mfma_f32_16x16x32_bf16 v[38:41], v[158:161], v[208:211], v[38:41]
	v_mfma_f32_16x16x32_bf16 v[30:33], v[166:169], v[208:211], v[30:33]
	v_mfma_f32_16x16x32_bf16 v[14:17], v[158:161], v[216:219], v[14:17]
	v_mfma_f32_16x16x32_bf16 v[10:13], v[166:169], v[216:219], v[10:13]
	v_mfma_f32_16x16x32_bf16 v[50:53], v[172:175], v[188:191], v[50:53]
	v_mfma_f32_16x16x32_bf16 v[42:45], v[180:183], v[188:191], v[42:45]
	v_mfma_f32_16x16x32_bf16 v[34:37], v[172:175], v[196:199], v[34:37]
	v_mfma_f32_16x16x32_bf16 v[26:29], v[180:183], v[196:199], v[26:29]
	v_mfma_f32_16x16x32_bf16 v[22:25], v[172:175], v[204:207], v[22:25]
	v_mfma_f32_16x16x32_bf16 v[18:21], v[180:183], v[204:207], v[18:21]
	v_mfma_f32_16x16x32_bf16 v[6:9], v[172:175], v[212:215], v[6:9]
	v_mfma_f32_16x16x32_bf16 v[2:5], v[180:183], v[212:215], v[2:5]
	v_mfma_f32_16x16x32_bf16 v[50:53], v[176:179], v[192:195], v[50:53]
	v_mfma_f32_16x16x32_bf16 v[42:45], v[184:187], v[192:195], v[42:45]
	v_mfma_f32_16x16x32_bf16 v[34:37], v[176:179], v[200:203], v[34:37]
	v_mfma_f32_16x16x32_bf16 v[26:29], v[184:187], v[200:203], v[26:29]
	v_mfma_f32_16x16x32_bf16 v[22:25], v[176:179], v[208:211], v[22:25]
	v_mfma_f32_16x16x32_bf16 v[18:21], v[184:187], v[208:211], v[18:21]
	v_mfma_f32_16x16x32_bf16 v[6:9], v[176:179], v[216:219], v[6:9]
	v_mfma_f32_16x16x32_bf16 v[2:5], v[184:187], v[216:219], v[2:5]
	s_barrier
	s_setprio 0
	s_add_i32 s65, s65, 2
	s_add_u32 s63, s63, 0x100
	s_addc_u32 s64, s64, 0
	s_add_u32 s36, s36, 0x10000
	s_addc_u32 s37, s37, 0
	v_lshl_add_u64 v[148:149], v[148:149], 0, s[18:19]
	s_cmp_gt_u32 s65, 61
	v_lshl_add_u64 v[146:147], v[146:147], 0, s[18:19]
	s_cbranch_scc0 .LBB0_1339
	s_branch .Lph1339_x
.Lph1339_y:
	v_add_u32_e32 v153, s56, v151
	ds_read_b128 v[154:157], v153
	ds_read_b128 v[158:161], v153 offset:1024
	ds_read_b128 v[162:165], v153 offset:2048
	ds_read_b128 v[166:169], v153 offset:3072
	v_add_u32_e32 v153, s57, v151
	ds_read_b128 v[172:175], v153
	ds_read_b128 v[176:179], v153 offset:1024
	ds_read_b128 v[180:183], v153 offset:2048
	ds_read_b128 v[184:187], v153 offset:3072
	s_add_u32 s38, s14, s36
	s_addc_u32 s39, s15, s37
	s_cmp_eq_u32 s65, 60
	s_cselect_b32 s42, s59, s38
	s_cselect_b32 s43, s25, s39
	s_cselect_b32 s40, s62, s63
	s_cselect_b32 s41, s23, s64
	s_add_u32 s38, s42, 0x8000
	s_addc_u32 s39, s43, 0
	v_lshl_add_u64 v[220:221], s[14:15], 0, v[148:149]
	s_add_i32 m0, s45, 0xc000
	ds_read_b128 v[188:191], v152
	ds_read_b128 v[192:195], v152 offset:1024
	ds_read_b128 v[196:199], v152 offset:2048
	ds_read_b128 v[200:203], v152 offset:3072
	ds_read_b128 v[204:207], v152 offset:4096
	ds_read_b128 v[208:211], v152 offset:5120
	ds_read_b128 v[212:215], v152 offset:6144
	ds_read_b128 v[216:219], v152 offset:7168
	global_load_lds_dwordx4 v[220:221], off
	v_lshl_add_u64 v[220:221], s[14:15], 0, v[146:147]
	s_add_i32 m0, s45, 0xe000
	s_nop 0
	global_load_lds_dwordx4 v[220:221], off
	s_waitcnt vmcnt(8)
	s_waitcnt lgkmcnt(0)
	s_setprio 2
	s_barrier
; #define PG8_STAGE(bufoff, gbase, voff) do { _Pragma("unroll") for (int _i = 0; _i < 2; ++_i) \
;         __builtin_amdgcn_global_load_lds((const unsigned*)((const char*)(gbase) + (voff)[_i]), (PG8_LAS unsigned*)(lds + (bufoff) + ldsw + _i * 8192), 16, 0, 0); } while (0)
; #define PG8_LDA(dst, b, h) do { _Pragma("unroll") for (int m = 0; m < 4; ++m) _Pragma("unroll") for (int k = 0; k < 2; ++k) dst[m][k] = *(const PG8_LAS bf16x8*)(lds + PG8_SA(b, h) + aoff + m * 2048 + k * 1024); } while (0)
; #define PG8_MMA(ai, bj, At, Bt) do { __builtin_amdgcn_s_setprio(1); _Pragma("unroll") for (int m = 0; m < 4; ++m) _Pragma("unroll") for (int n = 0; n < 2; ++n) _Pragma("unroll") for (int k = 0; k < 2; ++k) \
;         acc[ai][bj][m][n] = __builtin_amdgcn_mfma_f32_16x16x32_bf16(Bt[n][k], At[m][k], acc[ai][bj][m][n], 0, 0, 0); __builtin_amdgcn_s_setprio(0); } while (0)
; #define PG8_WAIT_V(n) asm volatile("s_waitcnt vmcnt(" #n ")" ::: "memory")
; #define PG8_WAIT_L(n) asm volatile("s_waitcnt lgkmcnt(" #n ")" ::: "memory")
; #define PG8_BAR __builtin_amdgcn_s_barrier()
; #define PG8_SCHED __builtin_amdgcn_sched_barrier(0)
; template <class Epi, class Sched, bool ALIGN_EPI = false, bool SP2 = false>
; __device__ __forceinline__ void gemm_phase(PG8_LAS unsigned char* lds, const Gemm g, const Sched& S, const Epi& E) {
;     ...
;             PG8_WAIT_V(8); PG8_WAIT_L(0); PG8_BAR; PG8_MMA(0, 0, At, B0); PG8_MMA(0, 1, At, B1); PG8_BAR; PG8_SCHED;
;             PG8_LDA(At, 0, 1); PG8_STAGE(PG8_SB(0, 0), b2, voffB); PG8_STAGE(PG8_SB(0, 1), b2 + hstepB, voffB); PG8_STAGE(PG8_SA(0, 0), a2, voffA);
;             PG8_WAIT_V(8); PG8_WAIT_L(0); PG8_BAR; PG8_MMA(1, 0, At, B0); PG8_MMA(1, 1, At, B1); PG8_BAR; PG8_SCHED;
	v_mfma_f32_16x16x32_bf16 v[122:125], v[154:157], v[188:191], v[122:125]
	v_mfma_f32_16x16x32_bf16 v[126:129], v[162:165], v[188:191], v[126:129]
	v_mfma_f32_16x16x32_bf16 v[118:121], v[154:157], v[196:199], v[118:121]
	v_mfma_f32_16x16x32_bf16 v[106:109], v[162:165], v[196:199], v[106:109]
	v_mfma_f32_16x16x32_bf16 v[98:101], v[154:157], v[204:207], v[98:101]
	v_mfma_f32_16x16x32_bf16 v[90:93], v[162:165], v[204:207], v[90:93]
	v_mfma_f32_16x16x32_bf16 v[110:113], v[154:157], v[212:215], v[110:113]
	v_mfma_f32_16x16x32_bf16 v[82:85], v[162:165], v[212:215], v[82:85]
	v_mfma_f32_16x16x32_bf16 v[122:125], v[158:161], v[192:195], v[122:125]
	v_mfma_f32_16x16x32_bf16 v[126:129], v[166:169], v[192:195], v[126:129]
	v_mfma_f32_16x16x32_bf16 v[118:121], v[158:161], v[200:203], v[118:121]
	v_mfma_f32_16x16x32_bf16 v[106:109], v[166:169], v[200:203], v[106:109]
	v_mfma_f32_16x16x32_bf16 v[98:101], v[158:161], v[208:211], v[98:101]
	v_mfma_f32_16x16x32_bf16 v[90:93], v[166:169], v[208:211], v[90:93]
	v_mfma_f32_16x16x32_bf16 v[110:113], v[158:161], v[216:219], v[110:113]
	v_mfma_f32_16x16x32_bf16 v[82:85], v[166:169], v[216:219], v[82:85]
	v_mfma_f32_16x16x32_bf16 v[114:117], v[172:175], v[188:191], v[114:117]
	v_mfma_f32_16x16x32_bf16 v[102:105], v[180:183], v[188:191], v[102:105]
	v_mfma_f32_16x16x32_bf16 v[94:97], v[172:175], v[196:199], v[94:97]
	v_mfma_f32_16x16x32_bf16 v[86:89], v[180:183], v[196:199], v[86:89]
	v_mfma_f32_16x16x32_bf16 v[78:81], v[172:175], v[204:207], v[78:81]
	v_mfma_f32_16x16x32_bf16 v[70:73], v[180:183], v[204:207], v[70:73]
	v_mfma_f32_16x16x32_bf16 v[66:69], v[172:175], v[212:215], v[66:69]
	v_mfma_f32_16x16x32_bf16 v[74:77], v[180:183], v[212:215], v[74:77]
	v_mfma_f32_16x16x32_bf16 v[114:117], v[176:179], v[192:195], v[114:117]
	v_mfma_f32_16x16x32_bf16 v[102:105], v[184:187], v[192:195], v[102:105]
	v_mfma_f32_16x16x32_bf16 v[94:97], v[176:179], v[200:203], v[94:97]
	v_mfma_f32_16x16x32_bf16 v[86:89], v[184:187], v[200:203], v[86:89]
	v_mfma_f32_16x16x32_bf16 v[78:81], v[176:179], v[208:211], v[78:81]
	v_mfma_f32_16x16x32_bf16 v[70:73], v[184:187], v[208:211], v[70:73]
	v_mfma_f32_16x16x32_bf16 v[66:69], v[176:179], v[216:219], v[66:69]
	v_mfma_f32_16x16x32_bf16 v[74:77], v[184:187], v[216:219], v[74:77]
	s_barrier
	s_setprio 1
	s_add_i32 s66, s56, s44
	v_lshl_add_u64 v[220:221], s[40:41], 0, v[132:133]
	s_mov_b32 m0, s66
	ds_read_b128 v[188:191], v152 offset:16384
	ds_read_b128 v[192:195], v152 offset:17408
	ds_read_b128 v[196:199], v152 offset:18432
	ds_read_b128 v[200:203], v152 offset:19456
	ds_read_b128 v[204:207], v152 offset:20480
	ds_read_b128 v[208:211], v152 offset:21504
	ds_read_b128 v[212:215], v152 offset:22528
	ds_read_b128 v[216:219], v152 offset:23552
	global_load_lds_dwordx4 v[220:221], off
	s_add_i32 m0, s66, 0x2000
	s_add_u32 s66, s40, 0x100000
	v_lshl_add_u64 v[222:223], s[40:41], 0, v[136:137]
	s_addc_u32 s67, s41, 0
	s_add_i32 s68, s57, s44
	global_load_lds_dwordx4 v[222:223], off
	v_lshl_add_u64 v[224:225], s[66:67], 0, v[132:133]
	s_mov_b32 m0, s68
	s_nop 0
	global_load_lds_dwordx4 v[224:225], off
	v_lshl_add_u64 v[224:225], s[66:67], 0, v[136:137]
	s_add_i32 m0, s68, 0x2000
	s_nop 0
	global_load_lds_dwordx4 v[224:225], off
	v_lshl_add_u64 v[224:225], s[42:43], 0, v[130:131]
	s_mov_b32 m0, s45
	s_nop 0
	global_load_lds_dwordx4 v[224:225], off
	v_lshl_add_u64 v[224:225], s[42:43], 0, v[134:135]
	s_mov_b32 m0, s46
	s_nop 0
	global_load_lds_dwordx4 v[224:225], off
	s_waitcnt vmcnt(8)
	s_waitcnt lgkmcnt(0)
	s_setprio 2
	s_barrier
	v_mfma_f32_16x16x32_bf16 v[62:65], v[154:157], v[188:191], v[62:65]
	v_mfma_f32_16x16x32_bf16 v[58:61], v[162:165], v[188:191], v[58:61]
	v_mfma_f32_16x16x32_bf16 v[54:57], v[154:157], v[196:199], v[54:57]
	v_mfma_f32_16x16x32_bf16 v[46:49], v[162:165], v[196:199], v[46:49]
	v_mfma_f32_16x16x32_bf16 v[38:41], v[154:157], v[204:207], v[38:41]
	v_mfma_f32_16x16x32_bf16 v[30:33], v[162:165], v[204:207], v[30:33]
	v_mfma_f32_16x16x32_bf16 v[14:17], v[154:157], v[212:215], v[14:17]
	v_mfma_f32_16x16x32_bf16 v[10:13], v[162:165], v[212:215], v[10:13]
	v_mfma_f32_16x16x32_bf16 v[62:65], v[158:161], v[192:195], v[62:65]
	v_mfma_f32_16x16x32_bf16 v[58:61], v[166:169], v[192:195], v[58:61]
	v_mfma_f32_16x16x32_bf16 v[54:57], v[158:161], v[200:203], v[54:57]
	v_mfma_f32_16x16x32_bf16 v[46:49], v[166:169], v[200:203], v[46:49]
	v_mfma_f32_16x16x32_bf16 v[38:41], v[158:161], v[208:211], v[38:41]
	v_mfma_f32_16x16x32_bf16 v[30:33], v[166:169], v[208:211], v[30:33]
	v_mfma_f32_16x16x32_bf16 v[14:17], v[158:161], v[216:219], v[14:17]
	v_mfma_f32_16x16x32_bf16 v[10:13], v[166:169], v[216:219], v[10:13]
	v_mfma_f32_16x16x32_bf16 v[50:53], v[172:175], v[188:191], v[50:53]
	v_mfma_f32_16x16x32_bf16 v[42:45], v[180:183], v[188:191], v[42:45]
	v_mfma_f32_16x16x32_bf16 v[34:37], v[172:175], v[196:199], v[34:37]
	v_mfma_f32_16x16x32_bf16 v[26:29], v[180:183], v[196:199], v[26:29]
	v_mfma_f32_16x16x32_bf16 v[22:25], v[172:175], v[204:207], v[22:25]
	v_mfma_f32_16x16x32_bf16 v[18:21], v[180:183], v[204:207], v[18:21]
	v_mfma_f32_16x16x32_bf16 v[6:9], v[172:175], v[212:215], v[6:9]
	v_mfma_f32_16x16x32_bf16 v[2:5], v[180:183], v[212:215], v[2:5]
	v_mfma_f32_16x16x32_bf16 v[50:53], v[176:179], v[192:195], v[50:53]
	v_mfma_f32_16x16x32_bf16 v[42:45], v[184:187], v[192:195], v[42:45]
	v_mfma_f32_16x16x32_bf16 v[34:37], v[176:179], v[200:203], v[34:37]
	v_mfma_f32_16x16x32_bf16 v[26:29], v[184:187], v[200:203], v[26:29]
	v_mfma_f32_16x16x32_bf16 v[22:25], v[176:179], v[208:211], v[22:25]
	v_mfma_f32_16x16x32_bf16 v[18:21], v[184:187], v[208:211], v[18:21]
	v_mfma_f32_16x16x32_bf16 v[6:9], v[176:179], v[216:219], v[6:9]
	v_mfma_f32_16x16x32_bf16 v[2:5], v[184:187], v[216:219], v[2:5]
	s_barrier
; #define PG8_STAGE(bufoff, gbase, voff) do { _Pragma("unroll") for (int _i = 0; _i < 2; ++_i) \
;         __builtin_amdgcn_global_load_lds((const unsigned*)((const char*)(gbase) + (voff)[_i]), (PG8_LAS unsigned*)(lds + (bufoff) + ldsw + _i * 8192), 16, 0, 0); } while (0)
; #define PG8_LDA(dst, b, h) do { _Pragma("unroll") for (int m = 0; m < 4; ++m) _Pragma("unroll") for (int k = 0; k < 2; ++k) dst[m][k] = *(const PG8_LAS bf16x8*)(lds + PG8_SA(b, h) + aoff + m * 2048 + k * 1024); } while (0)
; #define PG8_LDB(dst, b, h) do { _Pragma("unroll") for (int n = 0; n < 2; ++n) _Pragma("unroll") for (int k = 0; k < 2; ++k) dst[n][k] = *(const PG8_LAS bf16x8*)(lds + PG8_SB(b, h) + boff + n * 2048 + k * 1024); } while (0)
; #define PG8_MMA(ai, bj, At, Bt) do { __builtin_amdgcn_s_setprio(1); _Pragma("unroll") for (int m = 0; m < 4; ++m) _Pragma("unroll") for (int n = 0; n < 2; ++n) _Pragma("unroll") for (int k = 0; k < 2; ++k) \
;         acc[ai][bj][m][n] = __builtin_amdgcn_mfma_f32_16x16x32_bf16(Bt[n][k], At[m][k], acc[ai][bj][m][n], 0, 0, 0); __builtin_amdgcn_s_setprio(0); } while (0)
; #define PG8_WAIT_V(n) asm volatile("s_waitcnt vmcnt(" #n ")" ::: "memory")
; #define PG8_WAIT_L(n) asm volatile("s_waitcnt lgkmcnt(" #n ")" ::: "memory")
; #define PG8_BAR __builtin_amdgcn_s_barrier()
; #define PG8_SCHED __builtin_amdgcn_sched_barrier(0)
; template <class Epi, class Sched, bool ALIGN_EPI = false, bool SP2 = false>
; __device__ __forceinline__ void gemm_phase(PG8_LAS unsigned char* lds, const Gemm g, const Sched& S, const Epi& E) {
;     ...
;             PG8_LDB(B0, 1, 0); PG8_LDB(B1, 1, 1); PG8_SCHED; PG8_LDA(At, 1, 0); PG8_STAGE(PG8_SA(0, 1), a2 + hstepA, voffA);
;             PG8_WAIT_V(8); PG8_WAIT_L(0); PG8_BAR; PG8_MMA(0, 0, At, B0); PG8_MMA(0, 1, At, B1); PG8_BAR; PG8_SCHED;
	s_setprio 1
	s_add_i32 s66, 0, 0x18000
	v_add_u32_e32 v153, s66, v151
	s_add_i32 s67, 0, 0x1c000
	ds_read_b128 v[154:157], v153
	ds_read_b128 v[158:161], v153 offset:1024
	ds_read_b128 v[162:165], v153 offset:2048
	ds_read_b128 v[166:169], v153 offset:3072
	v_add_u32_e32 v153, s67, v151
	ds_read_b128 v[172:175], v153
	ds_read_b128 v[176:179], v153 offset:1024
	ds_read_b128 v[180:183], v153 offset:2048
	ds_read_b128 v[184:187], v153 offset:3072
	s_add_u32 s42, s42, 0x4000
	s_addc_u32 s43, s43, 0
	s_mov_b32 m0, s47
	v_lshl_add_u64 v[224:225], s[42:43], 0, v[130:131]
	ds_read_b128 v[188:191], v152 offset:32768
	ds_read_b128 v[192:195], v152 offset:33792
	ds_read_b128 v[196:199], v152 offset:34816
	ds_read_b128 v[200:203], v152 offset:35840
	ds_read_b128 v[204:207], v152 offset:36864
	ds_read_b128 v[208:211], v152 offset:37888
	ds_read_b128 v[212:215], v152 offset:38912
	ds_read_b128 v[216:219], v152 offset:39936
	global_load_lds_dwordx4 v[224:225], off
	v_lshl_add_u64 v[224:225], s[42:43], 0, v[134:135]
	s_mov_b32 m0, s48
	s_nop 0
	global_load_lds_dwordx4 v[224:225], off
	s_waitcnt vmcnt(8)
	s_waitcnt lgkmcnt(0)
	s_setprio 2
	s_barrier
	v_mfma_f32_16x16x32_bf16 v[122:125], v[154:157], v[188:191], v[122:125]
	v_mfma_f32_16x16x32_bf16 v[126:129], v[162:165], v[188:191], v[126:129]
	v_mfma_f32_16x16x32_bf16 v[118:121], v[154:157], v[196:199], v[118:121]
	v_mfma_f32_16x16x32_bf16 v[106:109], v[162:165], v[196:199], v[106:109]
	v_mfma_f32_16x16x32_bf16 v[98:101], v[154:157], v[204:207], v[98:101]
	v_mfma_f32_16x16x32_bf16 v[90:93], v[162:165], v[204:207], v[90:93]
	v_mfma_f32_16x16x32_bf16 v[110:113], v[154:157], v[212:215], v[110:113]
	v_mfma_f32_16x16x32_bf16 v[82:85], v[162:165], v[212:215], v[82:85]
	v_mfma_f32_16x16x32_bf16 v[122:125], v[158:161], v[192:195], v[122:125]
	v_mfma_f32_16x16x32_bf16 v[126:129], v[166:169], v[192:195], v[126:129]
	v_mfma_f32_16x16x32_bf16 v[118:121], v[158:161], v[200:203], v[118:121]
	v_mfma_f32_16x16x32_bf16 v[106:109], v[166:169], v[200:203], v[106:109]
	v_mfma_f32_16x16x32_bf16 v[98:101], v[158:161], v[208:211], v[98:101]
	v_mfma_f32_16x16x32_bf16 v[90:93], v[166:169], v[208:211], v[90:93]
	v_mfma_f32_16x16x32_bf16 v[110:113], v[158:161], v[216:219], v[110:113]
	v_mfma_f32_16x16x32_bf16 v[82:85], v[166:169], v[216:219], v[82:85]
	v_mfma_f32_16x16x32_bf16 v[114:117], v[172:175], v[188:191], v[114:117]
	v_mfma_f32_16x16x32_bf16 v[102:105], v[180:183], v[188:191], v[102:105]
	v_mfma_f32_16x16x32_bf16 v[94:97], v[172:175], v[196:199], v[94:97]
	v_mfma_f32_16x16x32_bf16 v[86:89], v[180:183], v[196:199], v[86:89]
	v_mfma_f32_16x16x32_bf16 v[78:81], v[172:175], v[204:207], v[78:81]
	v_mfma_f32_16x16x32_bf16 v[70:73], v[180:183], v[204:207], v[70:73]
	v_mfma_f32_16x16x32_bf16 v[66:69], v[172:175], v[212:215], v[66:69]
	v_mfma_f32_16x16x32_bf16 v[74:77], v[180:183], v[212:215], v[74:77]
	v_mfma_f32_16x16x32_bf16 v[114:117], v[176:179], v[192:195], v[114:117]
	v_mfma_f32_16x16x32_bf16 v[102:105], v[184:187], v[192:195], v[102:105]
	v_mfma_f32_16x16x32_bf16 v[94:97], v[176:179], v[200:203], v[94:97]
	v_mfma_f32_16x16x32_bf16 v[86:89], v[184:187], v[200:203], v[86:89]
	v_mfma_f32_16x16x32_bf16 v[78:81], v[176:179], v[208:211], v[78:81]
	v_mfma_f32_16x16x32_bf16 v[70:73], v[184:187], v[208:211], v[70:73]
	v_mfma_f32_16x16x32_bf16 v[66:69], v[176:179], v[216:219], v[66:69]
	v_mfma_f32_16x16x32_bf16 v[74:77], v[184:187], v[216:219], v[74:77]
	s_barrier
; #define PG8_STAGE(bufoff, gbase, voff) do { _Pragma("unroll") for (int _i = 0; _i < 2; ++_i) \
;         __builtin_amdgcn_global_load_lds((const unsigned*)((const char*)(gbase) + (voff)[_i]), (PG8_LAS unsigned*)(lds + (bufoff) + ldsw + _i * 8192), 16, 0, 0); } while (0)
; #define PG8_LDA(dst, b, h) do { _Pragma("unroll") for (int m = 0; m < 4; ++m) _Pragma("unroll") for (int k = 0; k < 2; ++k) dst[m][k] = *(const PG8_LAS bf16x8*)(lds + PG8_SA(b, h) + aoff + m * 2048 + k * 1024); } while (0)
; #define PG8_MMA(ai, bj, At, Bt) do { __builtin_amdgcn_s_setprio(1); _Pragma("unroll") for (int m = 0; m < 4; ++m) _Pragma("unroll") for (int n = 0; n < 2; ++n) _Pragma("unroll") for (int k = 0; k < 2; ++k) \
;         acc[ai][bj][m][n] = __builtin_amdgcn_mfma_f32_16x16x32_bf16(Bt[n][k], At[m][k], acc[ai][bj][m][n], 0, 0, 0); __builtin_amdgcn_s_setprio(0); } while (0)
; #define PG8_WAIT_V(n) asm volatile("s_waitcnt vmcnt(" #n ")" ::: "memory")
; #define PG8_WAIT_L(n) asm volatile("s_waitcnt lgkmcnt(" #n ")" ::: "memory")
; #define PG8_BAR __builtin_amdgcn_s_barrier()
; #define PG8_SCHED __builtin_amdgcn_sched_barrier(0)
; template <class Epi, class Sched, bool ALIGN_EPI = false, bool SP2 = false>
; __device__ __forceinline__ void gemm_phase(PG8_LAS unsigned char* lds, const Gemm g, const Sched& S, const Epi& E) {
;     ...
;             PG8_LDA(At, 1, 1); PG8_STAGE(PG8_SB(1, 0), b3, voffB); PG8_STAGE(PG8_SB(1, 1), b3 + hstepB, voffB); PG8_STAGE(PG8_SA(1, 0), a3, voffA);
;             PG8_WAIT_V(8); PG8_WAIT_L(0); PG8_BAR; PG8_MMA(1, 0, At, B0); PG8_MMA(1, 1, At, B1); PG8_BAR; PG8_SCHED;
	s_setprio 1
	s_add_i32 s42, s66, s44
	v_lshl_add_u64 v[220:221], v[220:221], 0, s[16:17]
	s_mov_b32 m0, s42
	ds_read_b128 v[188:191], v152 offset:49152
	ds_read_b128 v[192:195], v152 offset:50176
	ds_read_b128 v[196:199], v152 offset:51200
	ds_read_b128 v[200:203], v152 offset:52224
	ds_read_b128 v[204:207], v152 offset:53248
	ds_read_b128 v[208:211], v152 offset:54272
	ds_read_b128 v[212:215], v152 offset:55296
	ds_read_b128 v[216:219], v152 offset:56320
	global_load_lds_dwordx4 v[220:221], off
	s_add_i32 m0, s42, 0x2000
	s_add_u32 s40, s40, 0x100080
	v_lshl_add_u64 v[220:221], v[222:223], 0, s[16:17]
	s_addc_u32 s41, s41, 0
	s_add_i32 s42, s67, s44
	global_load_lds_dwordx4 v[220:221], off
	v_lshl_add_u64 v[220:221], s[40:41], 0, v[132:133]
	s_mov_b32 m0, s42
	s_nop 0
	global_load_lds_dwordx4 v[220:221], off
	v_lshl_add_u64 v[220:221], s[40:41], 0, v[136:137]
	s_add_i32 m0, s42, 0x2000
	s_nop 0
	global_load_lds_dwordx4 v[220:221], off
	v_lshl_add_u64 v[220:221], s[38:39], 0, v[130:131]
	s_mov_b32 m0, s50
	s_nop 0
	global_load_lds_dwordx4 v[220:221], off
	v_lshl_add_u64 v[220:221], s[38:39], 0, v[134:135]
	s_mov_b32 m0, s51
	s_nop 0
	global_load_lds_dwordx4 v[220:221], off
	s_waitcnt vmcnt(8)
	s_waitcnt lgkmcnt(0)
	s_setprio 2
	s_barrier
	v_mfma_f32_16x16x32_bf16 v[62:65], v[154:157], v[188:191], v[62:65]
	v_mfma_f32_16x16x32_bf16 v[58:61], v[162:165], v[188:191], v[58:61]
	v_mfma_f32_16x16x32_bf16 v[54:57], v[154:157], v[196:199], v[54:57]
	v_mfma_f32_16x16x32_bf16 v[46:49], v[162:165], v[196:199], v[46:49]
	v_mfma_f32_16x16x32_bf16 v[38:41], v[154:157], v[204:207], v[38:41]
	v_mfma_f32_16x16x32_bf16 v[30:33], v[162:165], v[204:207], v[30:33]
	v_mfma_f32_16x16x32_bf16 v[14:17], v[154:157], v[212:215], v[14:17]
	v_mfma_f32_16x16x32_bf16 v[10:13], v[162:165], v[212:215], v[10:13]
	v_mfma_f32_16x16x32_bf16 v[62:65], v[158:161], v[192:195], v[62:65]
	v_mfma_f32_16x16x32_bf16 v[58:61], v[166:169], v[192:195], v[58:61]
	v_mfma_f32_16x16x32_bf16 v[54:57], v[158:161], v[200:203], v[54:57]
	v_mfma_f32_16x16x32_bf16 v[46:49], v[166:169], v[200:203], v[46:49]
	v_mfma_f32_16x16x32_bf16 v[38:41], v[158:161], v[208:211], v[38:41]
	v_mfma_f32_16x16x32_bf16 v[30:33], v[166:169], v[208:211], v[30:33]
	v_mfma_f32_16x16x32_bf16 v[14:17], v[158:161], v[216:219], v[14:17]
	v_mfma_f32_16x16x32_bf16 v[10:13], v[166:169], v[216:219], v[10:13]
	v_mfma_f32_16x16x32_bf16 v[50:53], v[172:175], v[188:191], v[50:53]
	v_mfma_f32_16x16x32_bf16 v[42:45], v[180:183], v[188:191], v[42:45]
	v_mfma_f32_16x16x32_bf16 v[34:37], v[172:175], v[196:199], v[34:37]
	v_mfma_f32_16x16x32_bf16 v[26:29], v[180:183], v[196:199], v[26:29]
	v_mfma_f32_16x16x32_bf16 v[22:25], v[172:175], v[204:207], v[22:25]
	v_mfma_f32_16x16x32_bf16 v[18:21], v[180:183], v[204:207], v[18:21]
	v_mfma_f32_16x16x32_bf16 v[6:9], v[172:175], v[212:215], v[6:9]
	v_mfma_f32_16x16x32_bf16 v[2:5], v[180:183], v[212:215], v[2:5]
	v_mfma_f32_16x16x32_bf16 v[50:53], v[176:179], v[192:195], v[50:53]
	v_mfma_f32_16x16x32_bf16 v[42:45], v[184:187], v[192:195], v[42:45]
	v_mfma_f32_16x16x32_bf16 v[34:37], v[176:179], v[200:203], v[34:37]
	v_mfma_f32_16x16x32_bf16 v[26:29], v[184:187], v[200:203], v[26:29]
	v_mfma_f32_16x16x32_bf16 v[22:25], v[176:179], v[208:211], v[22:25]
	v_mfma_f32_16x16x32_bf16 v[18:21], v[184:187], v[208:211], v[18:21]
	v_mfma_f32_16x16x32_bf16 v[6:9], v[176:179], v[216:219], v[6:9]
	v_mfma_f32_16x16x32_bf16 v[2:5], v[184:187], v[216:219], v[2:5]
	s_barrier
	s_setprio 1
	s_add_i32 s65, s65, 2
	s_add_u32 s63, s63, 0x100
	s_addc_u32 s64, s64, 0
	s_add_u32 s36, s36, 0x10000
	s_addc_u32 s37, s37, 0
	v_lshl_add_u64 v[148:149], v[148:149], 0, s[18:19]
	s_cmp_gt_u32 s65, 61
	v_lshl_add_u64 v[146:147], v[146:147], 0, s[18:19]
	s_cbranch_scc0 .Lph1339_y
	s_setprio 0
